# stack: counted store drain before small_gemm, window-copy loop issues both loads first, ssm_b C-operand ds_reads hoisted, sample-attention staging loads issued before the workgroup barrier
# speedup vs baseline: 1.0122x; 1.0122x over previous
.LBB0_69:
	s_waitcnt vmcnt(16)
	s_cmpk_gt_u32 s25, 0xff
	s_cbranch_scc1 .LBB0_71
	s_barrier

.LBB0_72:
	s_andn2_b64 vcc, exec, s[30:31]
	v_readfirstlane_b32 s0, v204
	s_cbranch_vccnz .LBB0_78
	s_ashr_i32 s22, s0, 6
	s_lshl_b32 s0, s22, 7
	s_ashr_i32 s1, s0, 31
	s_lshl_b64 s[0:1], s[0:1], 1
	s_add_u32 s2, s52, s0
	s_addc_u32 s3, s53, s1
	s_waitcnt vmcnt(16)
	v_bfe_u32 v2, v204, 4, 2
	s_add_u32 s0, s19, s0
	v_lshlrev_b32_e32 v0, 4, v2
	s_addc_u32 s1, s24, s1
	v_lshl_add_u64 v[38:39], s[2:3], 0, v[0:1]
	v_lshl_add_u64 v[40:41], s[0:1], 0, v[0:1]
	v_lshlrev_b32_e32 v0, 2, v2
	v_lshlrev_b32_e32 v4, 2, v204
	v_lshl_or_b32 v2, s22, 5, v0
	v_ashrrev_i32_e32 v0, 4, v204
	v_and_b32_e32 v44, 60, v4
	s_movk_i32 s2, 0x110
	v_lshl_add_u32 v3, v176, 2, 0
	v_lshl_add_u32 v4, v44, 2, 0
	s_cmp_lg_u64 s[28:29], 0
	v_mul_lo_u32 v2, v2, s2
	v_mul_lo_u32 v5, v0, s2
	s_cselect_b64 s[0:1], -1, 0
	s_lshl_b32 s2, s90, 6
	s_lshl_b32 s3, s92, 6
	v_add_u32_e32 v45, v3, v2
	v_add_u32_e32 v46, v4, v5
	s_mov_b32 s19, s90
	s_branch .LBB0_76

.LBB0_95:
	s_add_u32 s22, s8, 0xfffc0080
	s_addc_u32 s23, s9, -1
	s_add_i32 s63, 0, 0x10000
	v_add_u32_e32 v78, s63, v178
	ds_read_b128 v[58:61], v78
	ds_read_b128 v[66:69], v78 offset:1024
	ds_read_b128 v[74:77], v78 offset:2048
	ds_read_b128 v[78:81], v78 offset:3072
	s_cmp_eq_u32 s49, 12
	s_cselect_b32 s29, s25, s23
	s_cselect_b32 s28, s26, s22
	s_cselect_b32 s23, s27, s47
	s_cselect_b32 s22, s30, s31
	v_lshl_add_u64 v[186:187], s[8:9], 0, v[168:169]
	s_add_i32 m0, s3, 0xc000
	ds_read_b128 v[172:175], v180
	ds_read_b128 v[182:185], v180 offset:1024
	ds_read_b128 v[206:209], v180 offset:2048
	ds_read_b128 v[210:213], v180 offset:3072
	ds_read_b128 v[214:217], v180 offset:4096
	ds_read_b128 v[218:221], v180 offset:5120
	ds_read_b128 v[222:225], v180 offset:6144
	ds_read_b128 v[226:229], v180 offset:7168
	global_load_lds_dwordx4 v[186:187], off
	v_lshl_add_u64 v[186:187], s[8:9], 0, v[170:171]
	s_add_i32 m0, s3, 0xe000
	s_nop 0
	global_load_lds_dwordx4 v[186:187], off
	s_waitcnt lgkmcnt(8)
	s_barrier
	s_waitcnt lgkmcnt(0)
	s_setprio 1
	s_waitcnt lgkmcnt(0)
	v_mfma_f32_16x16x32_bf16 v[142:145], v[58:61], v[172:175], v[142:145]
	v_mfma_f32_16x16x32_bf16 v[138:141], v[74:77], v[172:175], v[138:141]
	v_mfma_f32_16x16x32_bf16 v[126:129], v[58:61], v[206:209], v[126:129]
	v_mfma_f32_16x16x32_bf16 v[118:121], v[74:77], v[206:209], v[118:121]
	v_mfma_f32_16x16x32_bf16 v[110:113], v[58:61], v[214:217], v[110:113]
	v_mfma_f32_16x16x32_bf16 v[102:105], v[74:77], v[214:217], v[102:105]
	v_mfma_f32_16x16x32_bf16 v[94:97], v[58:61], v[222:225], v[94:97]
	v_mfma_f32_16x16x32_bf16 v[86:89], v[74:77], v[222:225], v[86:89]
	v_mfma_f32_16x16x32_bf16 v[142:145], v[66:69], v[182:185], v[142:145]
	v_mfma_f32_16x16x32_bf16 v[138:141], v[78:81], v[182:185], v[138:141]
	v_mfma_f32_16x16x32_bf16 v[126:129], v[66:69], v[210:213], v[126:129]
	v_mfma_f32_16x16x32_bf16 v[118:121], v[78:81], v[210:213], v[118:121]
	v_mfma_f32_16x16x32_bf16 v[110:113], v[66:69], v[218:221], v[110:113]
	v_mfma_f32_16x16x32_bf16 v[102:105], v[78:81], v[218:221], v[102:105]
	v_mfma_f32_16x16x32_bf16 v[94:97], v[66:69], v[226:229], v[94:97]
	v_mfma_f32_16x16x32_bf16 v[86:89], v[78:81], v[226:229], v[86:89]
	s_setprio 0
	s_barrier
	s_add_i32 s66, 0, 0x14000
	s_add_i32 s63, s63, s37
	v_add_u32_e32 v181, s66, v178
	v_lshl_add_u64 v[186:187], s[22:23], 0, v[0:1]
	s_mov_b32 m0, s63
	ds_read_b128 v[230:233], v181
	ds_read_b128 v[234:237], v181 offset:1024
	ds_read_b128 v[238:241], v181 offset:2048
	ds_read_b128 v[242:245], v181 offset:3072
	global_load_lds_dwordx4 v[186:187], off
	v_lshl_add_u64 v[246:247], s[22:23], 0, v[166:167]
	s_add_i32 m0, s63, 0x2000
	s_nop 0
	global_load_lds_dwordx4 v[246:247], off
	s_barrier
	s_waitcnt lgkmcnt(0)
	s_setprio 1
	s_waitcnt lgkmcnt(0)
	v_mfma_f32_16x16x32_bf16 v[134:137], v[230:233], v[172:175], v[134:137]
	v_mfma_f32_16x16x32_bf16 v[130:133], v[238:241], v[172:175], v[130:133]
	v_mfma_f32_16x16x32_bf16 v[122:125], v[230:233], v[206:209], v[122:125]
	v_mfma_f32_16x16x32_bf16 v[114:117], v[238:241], v[206:209], v[114:117]
	v_mfma_f32_16x16x32_bf16 v[106:109], v[230:233], v[214:217], v[106:109]
	v_mfma_f32_16x16x32_bf16 v[98:101], v[238:241], v[214:217], v[98:101]
	v_mfma_f32_16x16x32_bf16 v[90:93], v[230:233], v[222:225], v[90:93]
	v_mfma_f32_16x16x32_bf16 v[82:85], v[238:241], v[222:225], v[82:85]
	v_mfma_f32_16x16x32_bf16 v[134:137], v[234:237], v[182:185], v[134:137]
	v_mfma_f32_16x16x32_bf16 v[130:133], v[242:245], v[182:185], v[130:133]
	v_mfma_f32_16x16x32_bf16 v[122:125], v[234:237], v[210:213], v[122:125]
	v_mfma_f32_16x16x32_bf16 v[114:117], v[242:245], v[210:213], v[114:117]
	v_mfma_f32_16x16x32_bf16 v[106:109], v[234:237], v[218:221], v[106:109]
	v_mfma_f32_16x16x32_bf16 v[98:101], v[242:245], v[218:221], v[98:101]
	v_mfma_f32_16x16x32_bf16 v[90:93], v[234:237], v[226:229], v[90:93]
	v_mfma_f32_16x16x32_bf16 v[82:85], v[242:245], v[226:229], v[82:85]
	s_setprio 0
	s_mov_b32 m0, s3
	v_lshl_add_u64 v[248:249], s[28:29], 0, v[162:163]
	s_barrier
	ds_read_b128 v[172:175], v180 offset:16384
	ds_read_b128 v[182:185], v180 offset:17408
	ds_read_b128 v[206:209], v180 offset:18432
	ds_read_b128 v[210:213], v180 offset:19456
	ds_read_b128 v[214:217], v180 offset:20480
	ds_read_b128 v[218:221], v180 offset:21504
	ds_read_b128 v[222:225], v180 offset:22528
	ds_read_b128 v[226:229], v180 offset:23552
	global_load_lds_dwordx4 v[248:249], off
	v_lshl_add_u64 v[250:251], s[28:29], 0, v[164:165]
	s_mov_b32 m0, s56
	s_nop 0
	global_load_lds_dwordx4 v[250:251], off
	s_barrier
	s_waitcnt lgkmcnt(0)
	s_setprio 1
	s_waitcnt lgkmcnt(0)
	v_mfma_f32_16x16x32_bf16 v[70:73], v[58:61], v[172:175], v[70:73]
	v_mfma_f32_16x16x32_bf16 v[54:57], v[74:77], v[172:175], v[54:57]
	v_mfma_f32_16x16x32_bf16 v[46:49], v[58:61], v[206:209], v[46:49]
	v_mfma_f32_16x16x32_bf16 v[38:41], v[74:77], v[206:209], v[38:41]
	v_mfma_f32_16x16x32_bf16 v[30:33], v[58:61], v[214:217], v[30:33]
	v_mfma_f32_16x16x32_bf16 v[22:25], v[74:77], v[214:217], v[22:25]
	v_mfma_f32_16x16x32_bf16 v[14:17], v[58:61], v[222:225], v[14:17]
	v_mfma_f32_16x16x32_bf16 v[6:9], v[74:77], v[222:225], v[6:9]
	v_mfma_f32_16x16x32_bf16 v[70:73], v[66:69], v[182:185], v[70:73]
	v_mfma_f32_16x16x32_bf16 v[54:57], v[78:81], v[182:185], v[54:57]
	v_mfma_f32_16x16x32_bf16 v[46:49], v[66:69], v[210:213], v[46:49]
	v_mfma_f32_16x16x32_bf16 v[38:41], v[78:81], v[210:213], v[38:41]
	v_mfma_f32_16x16x32_bf16 v[30:33], v[66:69], v[218:221], v[30:33]
	v_mfma_f32_16x16x32_bf16 v[22:25], v[78:81], v[218:221], v[22:25]
	v_mfma_f32_16x16x32_bf16 v[14:17], v[66:69], v[226:229], v[14:17]
	v_mfma_f32_16x16x32_bf16 v[6:9], v[78:81], v[226:229], v[6:9]
	s_setprio 0
	s_barrier
	s_add_u32 s64, s22, 0x40000
	s_addc_u32 s65, s23, 0
	s_add_i32 s63, s66, s37
	v_lshl_add_u64 v[58:59], s[64:65], 0, v[0:1]
	s_mov_b32 m0, s63
	s_nop 0
	global_load_lds_dwordx4 v[58:59], off
	v_lshl_add_u64 v[58:59], s[64:65], 0, v[166:167]
	s_add_i32 m0, s63, 0x2000
	s_nop 0
	global_load_lds_dwordx4 v[58:59], off
	s_waitcnt vmcnt(6)
	s_barrier
	s_setprio 1
	v_mfma_f32_16x16x32_bf16 v[50:53], v[238:241], v[172:175], v[50:53]
	v_mfma_f32_16x16x32_bf16 v[42:45], v[230:233], v[206:209], v[42:45]
	v_mfma_f32_16x16x32_bf16 v[34:37], v[238:241], v[206:209], v[34:37]
	v_mfma_f32_16x16x32_bf16 v[26:29], v[230:233], v[214:217], v[26:29]
	v_mfma_f32_16x16x32_bf16 v[18:21], v[238:241], v[214:217], v[18:21]
	v_mfma_f32_16x16x32_bf16 v[10:13], v[230:233], v[222:225], v[10:13]
	v_mfma_f32_16x16x32_bf16 v[2:5], v[238:241], v[222:225], v[2:5]
	v_mfma_f32_16x16x32_bf16 v[58:61], v[230:233], v[172:175], v[62:65]
	v_mfma_f32_16x16x32_bf16 v[50:53], v[242:245], v[182:185], v[50:53]
	v_mfma_f32_16x16x32_bf16 v[42:45], v[234:237], v[210:213], v[42:45]
	v_mfma_f32_16x16x32_bf16 v[34:37], v[242:245], v[210:213], v[34:37]
	v_mfma_f32_16x16x32_bf16 v[26:29], v[234:237], v[218:221], v[26:29]
	v_mfma_f32_16x16x32_bf16 v[18:21], v[242:245], v[218:221], v[18:21]
	v_mfma_f32_16x16x32_bf16 v[10:13], v[234:237], v[226:229], v[10:13]
	v_mfma_f32_16x16x32_bf16 v[2:5], v[242:245], v[226:229], v[2:5]
	v_mfma_f32_16x16x32_bf16 v[58:61], v[234:237], v[182:185], v[58:61]
	s_setprio 0
	s_add_i32 s63, 0, 0x18000
	v_add_u32_e32 v78, s63, v178
	s_barrier
	ds_read_b128 v[62:65], v78
	ds_read_b128 v[66:69], v78 offset:1024
	ds_read_b128 v[74:77], v78 offset:2048
	ds_read_b128 v[78:81], v78 offset:3072
	s_add_u32 s28, s28, 0x40000
	s_addc_u32 s29, s29, 0
	s_mov_b32 m0, s57
	v_lshl_add_u64 v[230:231], s[28:29], 0, v[162:163]
	ds_read_b128 v[172:175], v180 offset:32768
	ds_read_b128 v[182:185], v180 offset:33792
	ds_read_b128 v[206:209], v180 offset:34816
	ds_read_b128 v[210:213], v180 offset:35840
	ds_read_b128 v[214:217], v180 offset:36864
	ds_read_b128 v[218:221], v180 offset:37888
	ds_read_b128 v[222:225], v180 offset:38912
	ds_read_b128 v[226:229], v180 offset:39936
	global_load_lds_dwordx4 v[230:231], off
	v_lshl_add_u64 v[230:231], s[28:29], 0, v[164:165]
	s_mov_b32 m0, s58
	s_nop 0
	global_load_lds_dwordx4 v[230:231], off
	s_waitcnt lgkmcnt(8)
	s_barrier
	s_waitcnt lgkmcnt(0)
	s_setprio 1
	s_waitcnt lgkmcnt(0)
	v_mfma_f32_16x16x32_bf16 v[142:145], v[62:65], v[172:175], v[142:145]
	v_mfma_f32_16x16x32_bf16 v[138:141], v[74:77], v[172:175], v[138:141]
	v_mfma_f32_16x16x32_bf16 v[126:129], v[62:65], v[206:209], v[126:129]
	v_mfma_f32_16x16x32_bf16 v[118:121], v[74:77], v[206:209], v[118:121]
	v_mfma_f32_16x16x32_bf16 v[110:113], v[62:65], v[214:217], v[110:113]
	v_mfma_f32_16x16x32_bf16 v[102:105], v[74:77], v[214:217], v[102:105]
	v_mfma_f32_16x16x32_bf16 v[94:97], v[62:65], v[222:225], v[94:97]
	v_mfma_f32_16x16x32_bf16 v[86:89], v[74:77], v[222:225], v[86:89]
	v_mfma_f32_16x16x32_bf16 v[142:145], v[66:69], v[182:185], v[142:145]
	v_mfma_f32_16x16x32_bf16 v[138:141], v[78:81], v[182:185], v[138:141]
	v_mfma_f32_16x16x32_bf16 v[126:129], v[66:69], v[210:213], v[126:129]
	v_mfma_f32_16x16x32_bf16 v[118:121], v[78:81], v[210:213], v[118:121]
	v_mfma_f32_16x16x32_bf16 v[110:113], v[66:69], v[218:221], v[110:113]
	v_mfma_f32_16x16x32_bf16 v[102:105], v[78:81], v[218:221], v[102:105]
	v_mfma_f32_16x16x32_bf16 v[94:97], v[66:69], v[226:229], v[94:97]
	v_mfma_f32_16x16x32_bf16 v[86:89], v[78:81], v[226:229], v[86:89]
	s_setprio 0
	s_barrier
	s_add_i32 s28, 0, 0x1c000
	s_add_i32 s29, s63, s37
	v_add_u32_e32 v181, s28, v178
	v_lshl_add_u64 v[186:187], v[186:187], 0, s[94:95]
	s_mov_b32 m0, s29
	ds_read_b128 v[230:233], v181
	ds_read_b128 v[234:237], v181 offset:1024
	ds_read_b128 v[238:241], v181 offset:2048
	ds_read_b128 v[242:245], v181 offset:3072
	global_load_lds_dwordx4 v[186:187], off
	v_lshl_add_u64 v[186:187], v[246:247], 0, s[94:95]
	s_add_i32 m0, s29, 0x2000
	s_nop 0
	global_load_lds_dwordx4 v[186:187], off
	s_barrier
	s_waitcnt lgkmcnt(0)
	s_setprio 1
	s_waitcnt lgkmcnt(0)
	v_mfma_f32_16x16x32_bf16 v[134:137], v[230:233], v[172:175], v[134:137]
	v_mfma_f32_16x16x32_bf16 v[130:133], v[238:241], v[172:175], v[130:133]
	v_mfma_f32_16x16x32_bf16 v[122:125], v[230:233], v[206:209], v[122:125]
	v_mfma_f32_16x16x32_bf16 v[114:117], v[238:241], v[206:209], v[114:117]
	v_mfma_f32_16x16x32_bf16 v[106:109], v[230:233], v[214:217], v[106:109]
	v_mfma_f32_16x16x32_bf16 v[98:101], v[238:241], v[214:217], v[98:101]
	v_mfma_f32_16x16x32_bf16 v[90:93], v[230:233], v[222:225], v[90:93]
	v_mfma_f32_16x16x32_bf16 v[82:85], v[238:241], v[222:225], v[82:85]
	v_mfma_f32_16x16x32_bf16 v[134:137], v[234:237], v[182:185], v[134:137]
	v_mfma_f32_16x16x32_bf16 v[130:133], v[242:245], v[182:185], v[130:133]
	v_mfma_f32_16x16x32_bf16 v[122:125], v[234:237], v[210:213], v[122:125]
	v_mfma_f32_16x16x32_bf16 v[114:117], v[242:245], v[210:213], v[114:117]
	v_mfma_f32_16x16x32_bf16 v[106:109], v[234:237], v[218:221], v[106:109]
	v_mfma_f32_16x16x32_bf16 v[98:101], v[242:245], v[218:221], v[98:101]
	v_mfma_f32_16x16x32_bf16 v[90:93], v[234:237], v[226:229], v[90:93]
	v_mfma_f32_16x16x32_bf16 v[82:85], v[242:245], v[226:229], v[82:85]
	s_setprio 0
	s_mov_b32 m0, s59
	v_lshl_add_u64 v[186:187], v[248:249], 0, s[94:95]
	s_barrier
	ds_read_b128 v[172:175], v180 offset:49152
	ds_read_b128 v[182:185], v180 offset:50176
	ds_read_b128 v[206:209], v180 offset:51200
	ds_read_b128 v[210:213], v180 offset:52224
	ds_read_b128 v[214:217], v180 offset:53248
	ds_read_b128 v[218:221], v180 offset:54272
	ds_read_b128 v[222:225], v180 offset:55296
	ds_read_b128 v[226:229], v180 offset:56320
	global_load_lds_dwordx4 v[186:187], off
	v_lshl_add_u64 v[186:187], v[250:251], 0, s[94:95]
	s_mov_b32 m0, s60
	s_nop 0
	global_load_lds_dwordx4 v[186:187], off
	s_barrier
	s_waitcnt lgkmcnt(0)
	s_setprio 1
	s_waitcnt lgkmcnt(0)
	v_mfma_f32_16x16x32_bf16 v[70:73], v[62:65], v[172:175], v[70:73]
	v_mfma_f32_16x16x32_bf16 v[54:57], v[74:77], v[172:175], v[54:57]
	v_mfma_f32_16x16x32_bf16 v[46:49], v[62:65], v[206:209], v[46:49]
	v_mfma_f32_16x16x32_bf16 v[38:41], v[74:77], v[206:209], v[38:41]
	v_mfma_f32_16x16x32_bf16 v[30:33], v[62:65], v[214:217], v[30:33]
	v_mfma_f32_16x16x32_bf16 v[22:25], v[74:77], v[214:217], v[22:25]
	v_mfma_f32_16x16x32_bf16 v[14:17], v[62:65], v[222:225], v[14:17]
	v_mfma_f32_16x16x32_bf16 v[6:9], v[74:77], v[222:225], v[6:9]
	v_mfma_f32_16x16x32_bf16 v[70:73], v[66:69], v[182:185], v[70:73]
	v_mfma_f32_16x16x32_bf16 v[54:57], v[78:81], v[182:185], v[54:57]
	v_mfma_f32_16x16x32_bf16 v[46:49], v[66:69], v[210:213], v[46:49]
	v_mfma_f32_16x16x32_bf16 v[38:41], v[78:81], v[210:213], v[38:41]
	v_mfma_f32_16x16x32_bf16 v[30:33], v[66:69], v[218:221], v[30:33]
	v_mfma_f32_16x16x32_bf16 v[22:25], v[78:81], v[218:221], v[22:25]
	v_mfma_f32_16x16x32_bf16 v[14:17], v[66:69], v[226:229], v[14:17]
	v_mfma_f32_16x16x32_bf16 v[6:9], v[78:81], v[226:229], v[6:9]
	s_setprio 0
	s_barrier
	s_add_u32 s22, s22, 0x40080
	s_addc_u32 s23, s23, 0
	s_add_i32 s28, s28, s37
	v_lshl_add_u64 v[62:63], s[22:23], 0, v[0:1]
	s_mov_b32 m0, s28
	s_nop 0
	global_load_lds_dwordx4 v[62:63], off
	v_lshl_add_u64 v[62:63], s[22:23], 0, v[166:167]
	s_add_i32 m0, s28, 0x2000
	s_nop 0
	global_load_lds_dwordx4 v[62:63], off
	s_waitcnt vmcnt(6)
	s_barrier
	s_setprio 1
	v_mfma_f32_16x16x32_bf16 v[58:61], v[230:233], v[172:175], v[58:61]
	v_mfma_f32_16x16x32_bf16 v[50:53], v[238:241], v[172:175], v[50:53]
	v_mfma_f32_16x16x32_bf16 v[42:45], v[230:233], v[206:209], v[42:45]
	v_mfma_f32_16x16x32_bf16 v[34:37], v[238:241], v[206:209], v[34:37]
	v_mfma_f32_16x16x32_bf16 v[26:29], v[230:233], v[214:217], v[26:29]
	v_mfma_f32_16x16x32_bf16 v[18:21], v[238:241], v[214:217], v[18:21]
	v_mfma_f32_16x16x32_bf16 v[10:13], v[230:233], v[222:225], v[10:13]
	v_mfma_f32_16x16x32_bf16 v[2:5], v[238:241], v[222:225], v[2:5]
	v_mfma_f32_16x16x32_bf16 v[62:65], v[234:237], v[182:185], v[58:61]
	v_mfma_f32_16x16x32_bf16 v[50:53], v[242:245], v[182:185], v[50:53]
	v_mfma_f32_16x16x32_bf16 v[42:45], v[234:237], v[210:213], v[42:45]
	v_mfma_f32_16x16x32_bf16 v[34:37], v[242:245], v[210:213], v[34:37]
	v_mfma_f32_16x16x32_bf16 v[26:29], v[234:237], v[218:221], v[26:29]
	v_mfma_f32_16x16x32_bf16 v[18:21], v[242:245], v[218:221], v[18:21]
	v_mfma_f32_16x16x32_bf16 v[10:13], v[234:237], v[226:229], v[10:13]
	v_mfma_f32_16x16x32_bf16 v[2:5], v[242:245], v[226:229], v[2:5]
	s_setprio 0
	s_add_i32 s49, s49, 2
	s_add_u32 s8, s8, 0x100
	s_addc_u32 s9, s9, 0
	s_add_u32 s31, s31, 0x100
	s_addc_u32 s47, s47, 0
	s_cmp_gt_u32 s49, 13
	s_barrier
	s_cbranch_scc0 .LBB0_95
	v_lshl_or_b32 v172, s24, 7, v179
	v_ashrrev_i32_e32 v173, 31, v172
	v_lshlrev_b64 v[58:59], 2, v[172:173]
	v_lshl_add_u64 v[60:61], s[40:41], 0, v[58:59]
	v_lshl_add_u64 v[74:75], s[44:45], 0, v[58:59]
	global_load_dwordx4 v[66:69], v[60:61], off offset:16
	global_load_dwordx4 v[78:81], v[60:61], off
	s_nop 0
	global_load_dwordx4 v[58:61], v[74:75], off offset:16
	s_nop 0
	global_load_dwordx4 v[74:77], v[74:75], off
	v_lshl_add_u32 v174, s2, 8, v177
	v_ashrrev_i32_e32 v175, 31, v174
	v_lshl_add_u64 v[172:173], v[172:173], 1, s[20:21]
	v_lshlrev_b64 v[182:183], 11, v[174:175]
	s_mov_b32 s2, 0x50000
	s_mov_b32 s24, s46
	s_mov_b64 s[22:23], s[54:55]
	s_mov_b64 s[8:9], s[50:51]
	s_waitcnt vmcnt(0)
	v_add_f32_e32 v138, v138, v66
	v_add_f32_e32 v126, v126, v78
	v_add_f32_e32 v130, v130, v58
	v_mul_f32_e32 v130, 0xbfb8aa3b, v130
	v_add_f32_e32 v131, v131, v59
	v_add_f32_e32 v122, v122, v74
	v_exp_f32_e32 v130, v130
	v_mul_f32_e32 v131, 0xbfb8aa3b, v131
	v_mul_f32_e32 v122, 0xbfb8aa3b, v122
	v_add_f32_e32 v123, v123, v75
	v_exp_f32_e32 v131, v131
	v_exp_f32_e32 v122, v122
	v_mul_f32_e32 v123, 0xbfb8aa3b, v123
	v_add_f32_e32 v124, v124, v76
	v_exp_f32_e32 v123, v123
	v_mul_f32_e32 v124, 0xbfb8aa3b, v124
	v_add_f32_e32 v125, v125, v77
	v_add_f32_e32 v114, v114, v58
	v_exp_f32_e32 v124, v124
	v_mul_f32_e32 v125, 0xbfb8aa3b, v125
	v_mul_f32_e32 v114, 0xbfb8aa3b, v114
	v_add_f32_e32 v115, v115, v59
	v_add_f32_e32 v106, v106, v74
	v_add_f32_e32 v130, 1.0, v130
	v_exp_f32_e32 v125, v125
	v_exp_f32_e32 v114, v114
	v_mul_f32_e32 v115, 0xbfb8aa3b, v115
	v_mul_f32_e32 v106, 0xbfb8aa3b, v106
	v_add_f32_e32 v107, v107, v75
	v_rcp_f32_e32 v130, v130
	v_add_f32_e32 v131, 1.0, v131
	v_add_f32_e32 v122, 1.0, v122
	v_exp_f32_e32 v115, v115
	v_exp_f32_e32 v106, v106
	v_mul_f32_e32 v107, 0xbfb8aa3b, v107
	v_add_f32_e32 v108, v108, v76
	v_rcp_f32_e32 v131, v131
	v_rcp_f32_e32 v122, v122
	v_add_f32_e32 v123, 1.0, v123
	v_exp_f32_e32 v107, v107
	v_mul_f32_e32 v108, 0xbfb8aa3b, v108
	v_add_f32_e32 v109, v109, v77
	v_add_f32_e32 v98, v98, v58
	v_rcp_f32_e32 v123, v123
	v_add_f32_e32 v124, 1.0, v124
	v_exp_f32_e32 v108, v108
	v_mul_f32_e32 v109, 0xbfb8aa3b, v109
	v_mul_f32_e32 v98, 0xbfb8aa3b, v98
	v_add_f32_e32 v99, v99, v59
	v_add_f32_e32 v90, v90, v74
	v_rcp_f32_e32 v124, v124
	v_add_f32_e32 v125, 1.0, v125
	v_add_f32_e32 v114, 1.0, v114
	v_exp_f32_e32 v109, v109
	v_exp_f32_e32 v98, v98
	v_mul_f32_e32 v99, 0xbfb8aa3b, v99
	v_mul_f32_e32 v90, 0xbfb8aa3b, v90
	v_add_f32_e32 v91, v91, v75
	v_mul_f32_e32 v138, v138, v130
	v_add_f32_e32 v130, v139, v67
	v_rcp_f32_e32 v125, v125
	v_rcp_f32_e32 v114, v114
	v_add_f32_e32 v115, 1.0, v115
	v_add_f32_e32 v106, 1.0, v106
	v_exp_f32_e32 v99, v99
	v_exp_f32_e32 v90, v90
	v_mul_f32_e32 v91, 0xbfb8aa3b, v91
	v_add_f32_e32 v92, v92, v76
	v_mul_f32_e32 v139, v130, v131
	v_add_f32_e32 v131, v132, v60
	v_mul_f32_e32 v122, v126, v122
	v_add_f32_e32 v126, v127, v79
	v_rcp_f32_e32 v115, v115
	v_rcp_f32_e32 v106, v106
	v_add_f32_e32 v107, 1.0, v107
	v_exp_f32_e32 v91, v91
	v_mul_f32_e32 v92, 0xbfb8aa3b, v92
	v_add_f32_e32 v93, v93, v77
	v_add_f32_e32 v82, v82, v58
	v_mul_f32_e32 v131, 0xbfb8aa3b, v131
	v_mul_f32_e32 v123, v126, v123
	v_add_f32_e32 v126, v128, v80
	v_rcp_f32_e32 v107, v107
	v_add_f32_e32 v108, 1.0, v108
	v_exp_f32_e32 v92, v92
	v_mul_f32_e32 v93, 0xbfb8aa3b, v93
	v_mul_f32_e32 v82, 0xbfb8aa3b, v82
	v_add_f32_e32 v83, v83, v59
	v_add_f32_e32 v50, v50, v58
	v_exp_f32_e32 v131, v131
	v_mul_f32_e32 v124, v126, v124
	v_add_f32_e32 v126, v129, v81
	v_add_f32_e32 v118, v118, v66
	v_rcp_f32_e32 v108, v108
	v_add_f32_e32 v109, 1.0, v109
	v_add_f32_e32 v98, 1.0, v98
	v_exp_f32_e32 v93, v93
	v_exp_f32_e32 v82, v82
	v_mul_f32_e32 v83, 0xbfb8aa3b, v83
	v_mul_f32_e32 v50, 0xbfb8aa3b, v50
	v_add_f32_e32 v51, v51, v59
	v_mul_f32_e32 v125, v126, v125
	v_mul_f32_e32 v126, v118, v114
	v_add_f32_e32 v114, v119, v67
	v_add_f32_e32 v110, v110, v78
	v_rcp_f32_e32 v109, v109
	v_rcp_f32_e32 v98, v98
	v_add_f32_e32 v99, 1.0, v99
	v_add_f32_e32 v90, 1.0, v90
	v_exp_f32_e32 v83, v83
	v_exp_f32_e32 v50, v50
	v_mul_f32_e32 v51, 0xbfb8aa3b, v51
	v_add_f32_e32 v34, v34, v58
	v_mul_f32_e32 v127, v114, v115
	v_add_f32_e32 v115, v116, v60
	v_mul_f32_e32 v106, v110, v106
	v_add_f32_e32 v110, v111, v79
	v_rcp_f32_e32 v99, v99
	v_rcp_f32_e32 v90, v90
	v_add_f32_e32 v91, 1.0, v91
	v_exp_f32_e32 v51, v51
	v_mul_f32_e32 v34, 0xbfb8aa3b, v34
	v_add_f32_e32 v35, v35, v59
	v_mul_f32_e32 v115, 0xbfb8aa3b, v115
	v_mul_f32_e32 v107, v110, v107
	v_add_f32_e32 v110, v112, v80
	v_rcp_f32_e32 v91, v91
	v_add_f32_e32 v92, 1.0, v92
	v_exp_f32_e32 v34, v34
	v_mul_f32_e32 v35, 0xbfb8aa3b, v35
	v_add_f32_e32 v18, v18, v58
	v_add_f32_e32 v131, 1.0, v131
	v_exp_f32_e32 v115, v115
	v_mul_f32_e32 v108, v110, v108
	v_add_f32_e32 v110, v113, v81
	v_add_f32_e32 v102, v102, v66
	v_rcp_f32_e32 v92, v92
	v_add_f32_e32 v93, 1.0, v93
	v_add_f32_e32 v82, 1.0, v82
	v_exp_f32_e32 v35, v35
	v_mul_f32_e32 v18, 0xbfb8aa3b, v18
	v_add_f32_e32 v19, v19, v59
	v_rcp_f32_e32 v131, v131
	v_mul_f32_e32 v109, v110, v109
	v_mul_f32_e32 v110, v102, v98
	v_add_f32_e32 v98, v103, v67
	v_add_f32_e32 v94, v94, v78
	v_rcp_f32_e32 v93, v93
	v_rcp_f32_e32 v82, v82
	v_add_f32_e32 v83, 1.0, v83
	v_add_f32_e32 v50, 1.0, v50
	v_exp_f32_e32 v18, v18
	v_mul_f32_e32 v19, 0xbfb8aa3b, v19
	v_add_f32_e32 v2, v2, v58
	v_mul_f32_e32 v111, v98, v99
	v_add_f32_e32 v99, v100, v60
	v_mul_f32_e32 v90, v94, v90
	v_add_f32_e32 v94, v95, v79
	v_rcp_f32_e32 v83, v83
	v_rcp_f32_e32 v50, v50
	v_add_f32_e32 v51, 1.0, v51
	v_exp_f32_e32 v19, v19
	v_mul_f32_e32 v2, 0xbfb8aa3b, v2
	v_add_f32_e32 v3, v3, v59
	v_add_f32_e32 v134, v134, v74
	v_mul_f32_e32 v99, 0xbfb8aa3b, v99
	v_mul_f32_e32 v91, v94, v91
	v_add_f32_e32 v94, v96, v80
	v_rcp_f32_e32 v51, v51
	v_add_f32_e32 v34, 1.0, v34
	v_exp_f32_e32 v2, v2
	v_mul_f32_e32 v3, 0xbfb8aa3b, v3
	v_mul_f32_e32 v134, 0xbfb8aa3b, v134
	v_add_f32_e32 v135, v135, v75
	v_add_f32_e32 v130, v140, v68
	v_add_f32_e32 v115, 1.0, v115
	v_exp_f32_e32 v99, v99
	v_mul_f32_e32 v92, v94, v92
	v_add_f32_e32 v94, v97, v81
	v_add_f32_e32 v86, v86, v66
	v_rcp_f32_e32 v34, v34
	v_add_f32_e32 v35, 1.0, v35
	v_exp_f32_e32 v3, v3
	v_exp_f32_e32 v134, v134
	v_mul_f32_e32 v135, 0xbfb8aa3b, v135
	v_add_f32_e32 v136, v136, v76
	v_mul_f32_e32 v140, v130, v131
	v_add_f32_e32 v131, v133, v61
	v_rcp_f32_e32 v115, v115
	v_mul_f32_e32 v93, v94, v93
	v_mul_f32_e32 v94, v86, v82
	v_add_f32_e32 v82, v87, v67
	v_add_f32_e32 v54, v54, v66
	v_rcp_f32_e32 v35, v35
	v_add_f32_e32 v18, 1.0, v18
	v_exp_f32_e32 v135, v135
	v_mul_f32_e32 v136, 0xbfb8aa3b, v136
	v_add_f32_e32 v137, v137, v77
	v_mul_f32_e32 v131, 0xbfb8aa3b, v131
	v_mul_f32_e32 v95, v82, v83
	v_add_f32_e32 v83, v84, v60
	v_mul_f32_e32 v54, v54, v50
	v_add_f32_e32 v50, v55, v67
	v_rcp_f32_e32 v18, v18
	v_add_f32_e32 v19, 1.0, v19
	v_exp_f32_e32 v136, v136
	v_mul_f32_e32 v137, 0xbfb8aa3b, v137
	v_exp_f32_e32 v131, v131
	v_mul_f32_e32 v83, 0xbfb8aa3b, v83
	v_mul_f32_e32 v55, v50, v51
	v_add_f32_e32 v51, v52, v60
	v_add_f32_e32 v38, v38, v66
	v_rcp_f32_e32 v19, v19
	v_add_f32_e32 v2, 1.0, v2
	v_exp_f32_e32 v137, v137
	v_add_f32_e32 v114, v120, v68
	v_add_f32_e32 v99, 1.0, v99
	v_exp_f32_e32 v83, v83
	v_mul_f32_e32 v51, 0xbfb8aa3b, v51
	v_mul_f32_e32 v38, v38, v34
	v_add_f32_e32 v34, v39, v67
	v_rcp_f32_e32 v2, v2
	v_add_f32_e32 v3, 1.0, v3
	v_add_f32_e32 v134, 1.0, v134
	v_mul_f32_e32 v120, v114, v115
	v_add_f32_e32 v115, v117, v61
	v_rcp_f32_e32 v99, v99
	v_exp_f32_e32 v51, v51
	v_mul_f32_e32 v39, v34, v35
	v_add_f32_e32 v35, v36, v60
	v_add_f32_e32 v22, v22, v66
	v_rcp_f32_e32 v3, v3
	v_rcp_f32_e32 v134, v134
	v_add_f32_e32 v135, 1.0, v135
	v_mul_f32_e32 v115, 0xbfb8aa3b, v115
	v_mul_f32_e32 v35, 0xbfb8aa3b, v35
	v_mul_f32_e32 v22, v22, v18
	v_add_f32_e32 v18, v23, v67
	v_rcp_f32_e32 v135, v135
	v_add_f32_e32 v136, 1.0, v136
	v_add_f32_e32 v131, 1.0, v131
	v_exp_f32_e32 v115, v115
	v_exp_f32_e32 v35, v35
	v_mul_f32_e32 v23, v18, v19
	v_add_f32_e32 v19, v20, v60
	v_add_f32_e32 v6, v6, v66
	v_rcp_f32_e32 v136, v136
	v_add_f32_e32 v137, 1.0, v137
	v_rcp_f32_e32 v131, v131
	v_add_f32_e32 v98, v104, v68
	v_add_f32_e32 v83, 1.0, v83
	v_mul_f32_e32 v19, 0xbfb8aa3b, v19
	v_mul_f32_e32 v6, v6, v2
	v_add_f32_e32 v2, v7, v67
	v_add_f32_e32 v142, v142, v78
	v_rcp_f32_e32 v137, v137
	v_mul_f32_e32 v104, v98, v99
	v_add_f32_e32 v99, v101, v61
	v_rcp_f32_e32 v83, v83
	v_add_f32_e32 v51, 1.0, v51
	v_exp_f32_e32 v19, v19
	v_mul_f32_e32 v7, v2, v3
	v_add_f32_e32 v3, v4, v60
	v_mul_f32_e32 v134, v142, v134
	v_add_f32_e32 v142, v143, v79
	v_mul_f32_e32 v99, 0xbfb8aa3b, v99
	v_rcp_f32_e32 v51, v51
	v_mul_f32_e32 v3, 0xbfb8aa3b, v3
	v_mul_f32_e32 v135, v142, v135
	v_add_f32_e32 v142, v144, v80
	v_add_f32_e32 v130, v141, v69
	v_add_f32_e32 v115, 1.0, v115
	v_exp_f32_e32 v99, v99
	v_add_f32_e32 v62, v62, v74
	v_add_f32_e32 v35, 1.0, v35
	v_exp_f32_e32 v3, v3
	v_mul_f32_e32 v136, v142, v136
	v_add_f32_e32 v142, v145, v81
	v_mul_f32_e32 v141, v130, v131
	v_lshl_add_u64 v[130:131], v[172:173], 0, v[182:183]
	v_cvt_pk_bf16_f32 v132, v134, v135
	v_rcp_f32_e32 v115, v115
	v_add_f32_e32 v82, v88, v68
	v_mul_f32_e32 v62, 0xbfb8aa3b, v62
	v_add_f32_e32 v63, v63, v75
	v_rcp_f32_e32 v35, v35
	v_mul_f32_e32 v137, v142, v137
	v_cvt_pk_bf16_f32 v133, v136, v137
	v_cvt_pk_bf16_f32 v134, v138, v139
	v_cvt_pk_bf16_f32 v135, v140, v141
	global_store_dwordx4 v[130:131], v[132:135], off
	v_mul_f32_e32 v88, v82, v83
	v_add_f32_e32 v83, v85, v61
	v_or_b32_e32 v132, 16, v174
	v_exp_f32_e32 v62, v62
	v_mul_f32_e32 v63, 0xbfb8aa3b, v63
	v_add_f32_e32 v64, v64, v76
	v_add_f32_e32 v50, v56, v68
	v_add_f32_e32 v42, v42, v74
	v_add_f32_e32 v19, 1.0, v19
	v_ashrrev_i32_e32 v133, 31, v132
	v_mul_f32_e32 v83, 0xbfb8aa3b, v83
	v_exp_f32_e32 v63, v63
	v_mul_f32_e32 v64, 0xbfb8aa3b, v64
	v_add_f32_e32 v65, v65, v77
	v_mul_f32_e32 v56, v50, v51
	v_add_f32_e32 v51, v53, v61
	v_mul_f32_e32 v42, 0xbfb8aa3b, v42
	v_add_f32_e32 v43, v43, v75
	v_rcp_f32_e32 v19, v19
	v_lshlrev_b64 v[132:133], 11, v[132:133]
	v_add_f32_e32 v114, v121, v69
	v_add_f32_e32 v99, 1.0, v99
	v_exp_f32_e32 v83, v83
	v_exp_f32_e32 v64, v64
	v_mul_f32_e32 v65, 0xbfb8aa3b, v65
	v_mul_f32_e32 v51, 0xbfb8aa3b, v51
	v_exp_f32_e32 v42, v42
	v_mul_f32_e32 v43, 0xbfb8aa3b, v43
	v_add_f32_e32 v44, v44, v76
	v_add_f32_e32 v34, v40, v68
	v_add_f32_e32 v26, v26, v74
	v_add_f32_e32 v3, 1.0, v3
	v_mul_f32_e32 v117, v114, v115
	v_lshl_add_u64 v[118:119], v[172:173], 0, v[132:133]
	v_cvt_pk_bf16_f32 v114, v122, v123
	v_rcp_f32_e32 v99, v99
	v_exp_f32_e32 v65, v65
	v_exp_f32_e32 v51, v51
	v_exp_f32_e32 v43, v43
	v_mul_f32_e32 v44, 0xbfb8aa3b, v44
	v_add_f32_e32 v45, v45, v77
	v_mul_f32_e32 v40, v34, v35
	v_add_f32_e32 v35, v37, v61
	v_mul_f32_e32 v26, 0xbfb8aa3b, v26
	v_add_f32_e32 v27, v27, v75
	v_rcp_f32_e32 v3, v3
	v_cvt_pk_bf16_f32 v115, v124, v125
	v_cvt_pk_bf16_f32 v116, v126, v127
	v_cvt_pk_bf16_f32 v117, v120, v117
	global_store_dwordx4 v[118:119], v[114:117], off
	v_add_f32_e32 v62, 1.0, v62
	v_exp_f32_e32 v44, v44
	v_or_b32_e32 v114, 32, v174
	v_mul_f32_e32 v45, 0xbfb8aa3b, v45
	v_mul_f32_e32 v35, 0xbfb8aa3b, v35
	v_exp_f32_e32 v26, v26
	v_mul_f32_e32 v27, 0xbfb8aa3b, v27
	v_add_f32_e32 v28, v28, v76
	v_add_f32_e32 v18, v24, v68
	v_add_f32_e32 v10, v10, v74
	v_ashrrev_i32_e32 v115, 31, v114
	v_rcp_f32_e32 v62, v62
	v_add_f32_e32 v63, 1.0, v63
	v_exp_f32_e32 v45, v45
	v_exp_f32_e32 v35, v35
	v_exp_f32_e32 v27, v27
	v_mul_f32_e32 v28, 0xbfb8aa3b, v28
	v_add_f32_e32 v29, v29, v77
	v_mul_f32_e32 v24, v18, v19
	v_add_f32_e32 v19, v21, v61
	v_mul_f32_e32 v10, 0xbfb8aa3b, v10
	v_add_f32_e32 v11, v11, v75
	v_lshlrev_b64 v[114:115], 11, v[114:115]
	v_add_f32_e32 v98, v105, v69
	v_add_f32_e32 v83, 1.0, v83
	v_rcp_f32_e32 v63, v63
	v_add_f32_e32 v64, 1.0, v64
	v_add_f32_e32 v42, 1.0, v42
	v_exp_f32_e32 v28, v28
	v_mul_f32_e32 v29, 0xbfb8aa3b, v29
	v_mul_f32_e32 v19, 0xbfb8aa3b, v19
	v_exp_f32_e32 v10, v10
	v_mul_f32_e32 v11, 0xbfb8aa3b, v11
	v_add_f32_e32 v12, v12, v76
	v_add_f32_e32 v2, v8, v68
	v_mul_f32_e32 v101, v98, v99
	v_lshl_add_u64 v[102:103], v[172:173], 0, v[114:115]
	v_cvt_pk_bf16_f32 v98, v106, v107
	v_rcp_f32_e32 v83, v83
	v_rcp_f32_e32 v64, v64
	v_add_f32_e32 v65, 1.0, v65
	v_add_f32_e32 v51, 1.0, v51
	v_rcp_f32_e32 v42, v42
	v_add_f32_e32 v43, 1.0, v43
	v_exp_f32_e32 v29, v29
	v_exp_f32_e32 v19, v19
	v_exp_f32_e32 v11, v11
	v_mul_f32_e32 v12, 0xbfb8aa3b, v12
	v_add_f32_e32 v13, v13, v77
	v_mul_f32_e32 v8, v2, v3
	v_add_f32_e32 v3, v5, v61
	v_cvt_pk_bf16_f32 v99, v108, v109
	v_cvt_pk_bf16_f32 v100, v110, v111
	v_cvt_pk_bf16_f32 v101, v104, v101
	global_store_dwordx4 v[102:103], v[98:101], off
	v_add_f32_e32 v70, v70, v78
	v_rcp_f32_e32 v65, v65
	v_or_b32_e32 v98, 48, v174
	v_rcp_f32_e32 v51, v51
	v_rcp_f32_e32 v43, v43
	v_add_f32_e32 v44, 1.0, v44
	v_add_f32_e32 v26, 1.0, v26
	v_exp_f32_e32 v12, v12
	v_mul_f32_e32 v13, 0xbfb8aa3b, v13
	v_mul_f32_e32 v3, 0xbfb8aa3b, v3
	v_ashrrev_i32_e32 v99, 31, v98
	v_mul_f32_e32 v62, v70, v62
	v_add_f32_e32 v70, v71, v79
	v_rcp_f32_e32 v44, v44
	v_add_f32_e32 v45, 1.0, v45
	v_add_f32_e32 v35, 1.0, v35
	v_rcp_f32_e32 v26, v26
	v_add_f32_e32 v27, 1.0, v27
	v_exp_f32_e32 v13, v13
	v_exp_f32_e32 v3, v3
	v_lshlrev_b64 v[98:99], 11, v[98:99]
	v_add_f32_e32 v82, v89, v69
	v_mul_f32_e32 v63, v70, v63
	v_add_f32_e32 v70, v72, v80
	v_add_f32_e32 v46, v46, v78
	v_rcp_f32_e32 v45, v45
	v_rcp_f32_e32 v35, v35
	v_rcp_f32_e32 v27, v27
	v_add_f32_e32 v28, 1.0, v28
	v_add_f32_e32 v10, 1.0, v10
	v_mul_f32_e32 v85, v82, v83
	v_lshl_add_u64 v[86:87], v[172:173], 0, v[98:99]
	v_mul_f32_e32 v64, v70, v64
	v_add_f32_e32 v70, v73, v81
	v_add_f32_e32 v50, v57, v69
	v_mul_f32_e32 v42, v46, v42
	v_add_f32_e32 v46, v47, v79
	v_rcp_f32_e32 v28, v28
	v_add_f32_e32 v29, 1.0, v29
	v_add_f32_e32 v19, 1.0, v19
	v_rcp_f32_e32 v10, v10
	v_add_f32_e32 v11, 1.0, v11
	v_cvt_pk_bf16_f32 v82, v90, v91
	v_cvt_pk_bf16_f32 v83, v92, v93
	v_cvt_pk_bf16_f32 v84, v94, v95
	v_cvt_pk_bf16_f32 v85, v88, v85
	global_store_dwordx4 v[86:87], v[82:85], off
	v_mul_f32_e32 v65, v70, v65
	v_mul_f32_e32 v53, v50, v51
	v_cvt_pk_bf16_f32 v50, v62, v63
	v_cvt_pk_bf16_f32 v51, v64, v65
	v_cvt_pk_bf16_f32 v52, v54, v55
	v_add_co_u32_e32 v54, vcc, s67, v130
	v_mul_f32_e32 v43, v46, v43
	v_add_f32_e32 v46, v48, v80
	v_add_f32_e32 v30, v30, v78
	v_rcp_f32_e32 v29, v29
	v_rcp_f32_e32 v19, v19
	v_rcp_f32_e32 v11, v11
	v_add_f32_e32 v12, 1.0, v12
	v_addc_co_u32_e32 v55, vcc, 0, v131, vcc
	v_mul_f32_e32 v44, v46, v44
	v_add_f32_e32 v46, v49, v81
	v_add_f32_e32 v34, v41, v69
	v_mul_f32_e32 v26, v30, v26
	v_add_f32_e32 v30, v31, v79
	v_rcp_f32_e32 v12, v12
	v_add_f32_e32 v13, 1.0, v13
	v_add_f32_e32 v3, 1.0, v3
	v_cvt_pk_bf16_f32 v53, v56, v53
	global_store_dwordx4 v[54:55], v[50:53], off
	v_mul_f32_e32 v45, v46, v45
	v_mul_f32_e32 v37, v34, v35
	v_cvt_pk_bf16_f32 v34, v42, v43
	v_cvt_pk_bf16_f32 v35, v44, v45
	v_cvt_pk_bf16_f32 v36, v38, v39
	v_add_co_u32_e32 v38, vcc, s68, v130
	v_mul_f32_e32 v27, v30, v27
	v_add_f32_e32 v30, v32, v80
	v_add_f32_e32 v14, v14, v78
	v_rcp_f32_e32 v13, v13
	v_rcp_f32_e32 v3, v3
	v_addc_co_u32_e32 v39, vcc, 0, v131, vcc
	v_mul_f32_e32 v28, v30, v28
	v_add_f32_e32 v30, v33, v81
	v_add_f32_e32 v18, v25, v69
	v_mul_f32_e32 v10, v14, v10
	v_add_f32_e32 v14, v15, v79
	v_cvt_pk_bf16_f32 v37, v40, v37
	global_store_dwordx4 v[38:39], v[34:37], off
	v_mul_f32_e32 v29, v30, v29
	v_mul_f32_e32 v21, v18, v19
	v_cvt_pk_bf16_f32 v18, v26, v27
	v_cvt_pk_bf16_f32 v19, v28, v29
	v_cvt_pk_bf16_f32 v20, v22, v23
	v_add_co_u32_e32 v22, vcc, s2, v130
	v_mul_f32_e32 v11, v14, v11
	v_add_f32_e32 v14, v16, v80
	v_addc_co_u32_e32 v23, vcc, 0, v131, vcc
	v_mul_f32_e32 v12, v14, v12
	v_add_f32_e32 v14, v17, v81
	v_add_f32_e32 v2, v9, v69
	v_cvt_pk_bf16_f32 v21, v24, v21
	global_store_dwordx4 v[22:23], v[18:21], off
	v_mul_f32_e32 v13, v14, v13
	v_mul_f32_e32 v5, v2, v3
	v_cvt_pk_bf16_f32 v2, v10, v11
	v_cvt_pk_bf16_f32 v3, v12, v13
	v_cvt_pk_bf16_f32 v4, v6, v7
	v_add_co_u32_e32 v6, vcc, 0x58000, v130
	s_mov_b32 s2, s48
	s_nop 0
	v_addc_co_u32_e32 v7, vcc, 0, v131, vcc
	s_and_b64 vcc, exec, s[38:39]
	v_cvt_pk_bf16_f32 v5, v8, v5
	global_store_dwordx4 v[6:7], v[2:5], off
	s_cbranch_vccz .LBB0_88
	s_waitcnt vmcnt(8)
	s_cmpk_gt_u32 s35, 0xff
	s_cbranch_scc1 .LBB0_99
	s_barrier

.LBB0_100:
	s_andn2_b64 vcc, exec, s[0:1]
	v_readfirstlane_b32 s0, v204
	s_cbranch_vccnz .LBB0_244
	s_ashr_i32 s8, s0, 6
	s_lshl_b32 s0, s8, 7
	s_ashr_i32 s1, s0, 31
	s_lshl_b64 s[0:1], s[0:1], 1
	s_add_u32 s2, s14, s0
	s_addc_u32 s3, s15, s1
	s_waitcnt vmcnt(8)
	v_bfe_u32 v6, v204, 4, 2
	s_add_u32 s0, s19, s0
	v_lshlrev_b32_e32 v0, 4, v6
	s_addc_u32 s1, s34, s1
	v_lshl_add_u64 v[2:3], s[2:3], 0, v[0:1]
	v_lshl_add_u64 v[4:5], s[0:1], 0, v[0:1]
	v_lshlrev_b32_e32 v0, 2, v6
	v_lshlrev_b32_e32 v8, 2, v204
	v_lshl_or_b32 v6, s8, 5, v0
	v_ashrrev_i32_e32 v0, 4, v204
	v_and_b32_e32 v14, 60, v8
	s_movk_i32 s0, 0x110
	v_lshl_add_u32 v7, v176, 2, 0
	v_lshl_add_u32 v8, v14, 2, 0
	s_add_u32 s2, s40, 0x1000
	v_mul_lo_u32 v6, v6, s0
	v_mul_lo_u32 v9, v0, s0
	v_cmp_gt_u32_e32 vcc, 32, v14
	s_addc_u32 s3, s41, 0
	v_add_u32_e32 v15, v8, v9
	s_lshl_b32 s8, s90, 5
	s_lshl_b32 s9, s92, 5
	s_lshl_b32 s19, s90, 6
	s_lshl_b32 s22, s92, 6
	v_add_u32_e32 v16, v7, v6
	s_mov_b32 s23, s90
	s_branch .LBB0_103

.LBB0_126:
	s_mov_b64 s[54:55], exec
	s_waitcnt lgkmcnt(0)
	s_load_dwordx2 s[38:39], s[80:81], 0x20
	s_load_dwordx2 s[40:41], s[80:81], 0x28
	s_load_dwordx2 s[56:57], s[80:81], 0xd0
	s_lshr_b32 s45, s90, 1
	s_and_b32 s46, s90, 1
	v_readfirstlane_b32 s47, v204
	v_and_b32_e32 v0, 15, v204
	v_lshrrev_b32_e32 v2, 4, v204
	s_lshr_b32 s47, s47, 6
	s_lshl_b32 s44, s46, 3
	s_add_i32 s44, s44, s47
	s_lshl_b32 s2, s45, 16
	s_lshl_b32 s3, s46, 8
	s_add_i32 s2, s2, s3
	v_lshlrev_b32_e32 v3, 9, v2
	v_lshl_add_u32 v3, v0, 4, v3
	v_add_u32_e32 v3, s2, v3
	v_add_u32_e32 v4, 0x4000, v3
	v_add_u32_e32 v5, 0x8000, v3
	v_add_u32_e32 v6, 0xc000, v3
	s_waitcnt lgkmcnt(0)
	global_load_dwordx4 v[20:23], v3, s[38:39]
	global_load_dwordx4 v[24:27], v4, s[38:39]
	global_load_dwordx4 v[28:31], v5, s[38:39]
	global_load_dwordx4 v[32:35], v6, s[38:39]
	global_load_dwordx4 v[36:39], v3, s[40:41]
	global_load_dwordx4 v[40:43], v4, s[40:41]
	global_load_dwordx4 v[44:47], v5, s[40:41]
	global_load_dwordx4 v[48:51], v6, s[40:41]
	s_add_u32 s8, s10, 0x13140000
	s_addc_u32 s9, s11, 0
	s_lshl_b32 s2, s45, 11
	s_lshl_b32 s3, s46, 7
	s_add_i32 s2, s2, s3
	s_add_i32 s2, s2, 0x800000
	v_and_b32_e32 v7, 63, v204
	v_bfe_u32 v8, v204, 6, 2
	v_lshrrev_b32_e32 v9, 8, v204
	v_lshlrev_b32_e32 v10, 1, v7
	v_lshl_add_u32 v10, v8, 9, v10
	v_lshl_add_u32 v10, v9, 8, v10
	v_add_u32_e32 v10, s2, v10
	global_load_ushort v52, v10, s[8:9]
	s_add_u32 s42, s10, 0xb580000
	s_addc_u32 s43, s11, 0
	s_lshl_b32 s2, s45, 13
	s_lshl_b32 s3, s44, 7
	s_add_i32 s2, s2, s3
	s_add_i32 s22, s2, 0x2000000
	v_lshl_add_u32 v11, v7, 1, s22
	v_add_u32_e32 v12, 0x1000, v11
	global_load_ushort v56, v11, s[42:43]
	global_load_ushort v57, v11, s[42:43] offset:2048
	global_load_ushort v58, v12, s[42:43]
	global_load_ushort v59, v12, s[42:43] offset:2048
	s_lshl_b32 s2, s44, 2
	s_cmp_gt_u32 s82, 30
	s_cselect_b32 s3, 64, 0
	s_add_i32 s2, s2, s3
	s_load_dword s58, s[56:57], s2
	v_mul_u32_u24_e32 v13, 272, v2
	v_lshl_add_u32 v13, v0, 4, v13
	v_lshlrev_b32_e32 v14, 8, v2
	v_lshl_add_u32 v14, v0, 4, v14
	v_add_u32_e32 v14, 0x9000, v14
	s_barrier
	s_waitcnt vmcnt(12)
	ds_write_b128 v13, v[20:23]
	s_waitcnt vmcnt(11)
	ds_write_b128 v13, v[24:27] offset:8704
	s_waitcnt vmcnt(10)
	ds_write_b128 v13, v[28:31] offset:17408
	s_waitcnt vmcnt(9)
	ds_write_b128 v13, v[32:35] offset:26112
	s_waitcnt vmcnt(8)
	ds_write_b128 v14, v[36:39]
	s_waitcnt vmcnt(7)
	ds_write_b128 v14, v[40:43] offset:8192
	s_waitcnt vmcnt(6)
	ds_write_b128 v14, v[44:47] offset:16384
	s_waitcnt vmcnt(5)
	ds_write_b128 v14, v[48:51] offset:24576
	v_mul_u32_u24_e32 v15, 272, v8
	v_add_u32_e32 v15, 34816, v15
	v_lshlrev_b32_e32 v16, 8, v8
	v_add_u32_e32 v16, 69632, v16
	v_cmp_eq_u32_e32 vcc, 0, v9
	s_nop 1
	v_cndmask_b32_e32 v15, v16, v15, vcc
	v_lshl_add_u32 v15, v7, 2, v15
	s_waitcnt vmcnt(4)
	v_lshlrev_b32_e32 v52, 16, v52
	ds_write_b32 v15, v52
	s_lshl_b32 s3, s47, 12
	s_add_i32 s59, s3, 0x12000
	v_lshl_add_u32 v17, v7, 4, s59
	s_waitcnt vmcnt(0)
	v_lshlrev_b32_e32 v56, 16, v56
	v_lshlrev_b32_e32 v57, 16, v57
	v_lshlrev_b32_e32 v58, 16, v58
	v_lshlrev_b32_e32 v59, 16, v59
	ds_write_b128 v17, v[56:59]
	s_waitcnt lgkmcnt(0)
	s_barrier
	v_mul_u32_u24_e32 v19, 272, v7
	v_min_u32_e32 v2, 3, v7
	v_mul_u32_u24_e32 v2, 272, v2
	v_add_u32_e32 v2, 34816, v2
	v_mov_b32_e32 v3, s59
	v_mov_b32_e32 v20, 0
	v_mov_b32_e32 v21, 0
	v_mov_b32_e32 v22, 0
	v_mov_b32_e32 v23, 0
	v_mov_b32_e32 v24, 0
	v_mov_b32_e32 v25, 0
	v_mov_b32_e32 v26, 0
	v_mov_b32_e32 v27, 0
	v_mov_b32_e32 v28, 0
	v_mov_b32_e32 v29, 0
	v_mov_b32_e32 v30, 0
	v_mov_b32_e32 v31, 0
	ds_read_b128 v[32:35], v19 offset:0
	ds_read_b128 v[36:39], v19 offset:17408
	ds_read_b128 v[40:43], v2 offset:0
	ds_read_b128 v[56:59], v3 offset:0
	ds_read_b128 v[60:63], v3 offset:16
	ds_read_b128 v[64:67], v3 offset:32
	ds_read_b128 v[68:71], v3 offset:48
	ds_read_b128 v[44:47], v19 offset:16
	ds_read_b128 v[48:51], v19 offset:17424
	ds_read_b128 v[52:55], v2 offset:16
	s_waitcnt lgkmcnt(7)
	s_waitcnt lgkmcnt(6)
	v_fmac_f32_e32 v20, v56, v32
	v_fmac_f32_e32 v21, v57, v32
	v_fmac_f32_e32 v22, v58, v32
	v_fmac_f32_e32 v23, v59, v32
	v_fmac_f32_e32 v24, v56, v36
	v_fmac_f32_e32 v25, v57, v36
	v_fmac_f32_e32 v26, v58, v36
	v_fmac_f32_e32 v27, v59, v36
	v_fmac_f32_e32 v28, v56, v40
	v_fmac_f32_e32 v29, v57, v40
	v_fmac_f32_e32 v30, v58, v40
	v_fmac_f32_e32 v31, v59, v40
	ds_read_b128 v[56:59], v3 offset:64
	s_waitcnt lgkmcnt(6)
	v_fmac_f32_e32 v20, v60, v33
	v_fmac_f32_e32 v21, v61, v33
	v_fmac_f32_e32 v22, v62, v33
	v_fmac_f32_e32 v23, v63, v33
	v_fmac_f32_e32 v24, v60, v37
	v_fmac_f32_e32 v25, v61, v37
	v_fmac_f32_e32 v26, v62, v37
	v_fmac_f32_e32 v27, v63, v37
	v_fmac_f32_e32 v28, v60, v41
	v_fmac_f32_e32 v29, v61, v41
	v_fmac_f32_e32 v30, v62, v41
	v_fmac_f32_e32 v31, v63, v41
	ds_read_b128 v[60:63], v3 offset:80
	s_waitcnt lgkmcnt(6)
	v_fmac_f32_e32 v20, v64, v34
	v_fmac_f32_e32 v21, v65, v34
	v_fmac_f32_e32 v22, v66, v34
	v_fmac_f32_e32 v23, v67, v34
	v_fmac_f32_e32 v24, v64, v38
	v_fmac_f32_e32 v25, v65, v38
	v_fmac_f32_e32 v26, v66, v38
	v_fmac_f32_e32 v27, v67, v38
	v_fmac_f32_e32 v28, v64, v42
	v_fmac_f32_e32 v29, v65, v42
	v_fmac_f32_e32 v30, v66, v42
	v_fmac_f32_e32 v31, v67, v42
	ds_read_b128 v[64:67], v3 offset:96
	s_waitcnt lgkmcnt(6)
	v_fmac_f32_e32 v20, v68, v35
	v_fmac_f32_e32 v21, v69, v35
	v_fmac_f32_e32 v22, v70, v35
	v_fmac_f32_e32 v23, v71, v35
	v_fmac_f32_e32 v24, v68, v39
	v_fmac_f32_e32 v25, v69, v39
	v_fmac_f32_e32 v26, v70, v39
	v_fmac_f32_e32 v27, v71, v39
	v_fmac_f32_e32 v28, v68, v43
	v_fmac_f32_e32 v29, v69, v43
	v_fmac_f32_e32 v30, v70, v43
	v_fmac_f32_e32 v31, v71, v43
	ds_read_b128 v[68:71], v3 offset:112
	ds_read_b128 v[32:35], v19 offset:32
	ds_read_b128 v[36:39], v19 offset:17440
	ds_read_b128 v[40:43], v2 offset:32
	s_waitcnt lgkmcnt(7)
	s_waitcnt lgkmcnt(6)
	v_fmac_f32_e32 v20, v56, v44
	v_fmac_f32_e32 v21, v57, v44
	v_fmac_f32_e32 v22, v58, v44
	v_fmac_f32_e32 v23, v59, v44
	v_fmac_f32_e32 v24, v56, v48
	v_fmac_f32_e32 v25, v57, v48
	v_fmac_f32_e32 v26, v58, v48
	v_fmac_f32_e32 v27, v59, v48
	v_fmac_f32_e32 v28, v56, v52
	v_fmac_f32_e32 v29, v57, v52
	v_fmac_f32_e32 v30, v58, v52
	v_fmac_f32_e32 v31, v59, v52
	ds_read_b128 v[56:59], v3 offset:128
	s_waitcnt lgkmcnt(6)
	v_fmac_f32_e32 v20, v60, v45
	v_fmac_f32_e32 v21, v61, v45
	v_fmac_f32_e32 v22, v62, v45
	v_fmac_f32_e32 v23, v63, v45
	v_fmac_f32_e32 v24, v60, v49
	v_fmac_f32_e32 v25, v61, v49
	v_fmac_f32_e32 v26, v62, v49
	v_fmac_f32_e32 v27, v63, v49
	v_fmac_f32_e32 v28, v60, v53
	v_fmac_f32_e32 v29, v61, v53
	v_fmac_f32_e32 v30, v62, v53
	v_fmac_f32_e32 v31, v63, v53
	ds_read_b128 v[60:63], v3 offset:144
	s_waitcnt lgkmcnt(6)
	v_fmac_f32_e32 v20, v64, v46
	v_fmac_f32_e32 v21, v65, v46
	v_fmac_f32_e32 v22, v66, v46
	v_fmac_f32_e32 v23, v67, v46
	v_fmac_f32_e32 v24, v64, v50
	v_fmac_f32_e32 v25, v65, v50
	v_fmac_f32_e32 v26, v66, v50
	v_fmac_f32_e32 v27, v67, v50
	v_fmac_f32_e32 v28, v64, v54
	v_fmac_f32_e32 v29, v65, v54
	v_fmac_f32_e32 v30, v66, v54
	v_fmac_f32_e32 v31, v67, v54
	ds_read_b128 v[64:67], v3 offset:160
	s_waitcnt lgkmcnt(6)
	v_fmac_f32_e32 v20, v68, v47
	v_fmac_f32_e32 v21, v69, v47
	v_fmac_f32_e32 v22, v70, v47
	v_fmac_f32_e32 v23, v71, v47
	v_fmac_f32_e32 v24, v68, v51
	v_fmac_f32_e32 v25, v69, v51
	v_fmac_f32_e32 v26, v70, v51
	v_fmac_f32_e32 v27, v71, v51
	v_fmac_f32_e32 v28, v68, v55
	v_fmac_f32_e32 v29, v69, v55
	v_fmac_f32_e32 v30, v70, v55
	v_fmac_f32_e32 v31, v71, v55
	ds_read_b128 v[68:71], v3 offset:176
	ds_read_b128 v[44:47], v19 offset:48
	ds_read_b128 v[48:51], v19 offset:17456
	ds_read_b128 v[52:55], v2 offset:48
	s_waitcnt lgkmcnt(7)
	s_waitcnt lgkmcnt(6)
	v_fmac_f32_e32 v20, v56, v32
	v_fmac_f32_e32 v21, v57, v32
	v_fmac_f32_e32 v22, v58, v32
	v_fmac_f32_e32 v23, v59, v32
	v_fmac_f32_e32 v24, v56, v36
	v_fmac_f32_e32 v25, v57, v36
	v_fmac_f32_e32 v26, v58, v36
	v_fmac_f32_e32 v27, v59, v36
	v_fmac_f32_e32 v28, v56, v40
	v_fmac_f32_e32 v29, v57, v40
	v_fmac_f32_e32 v30, v58, v40
	v_fmac_f32_e32 v31, v59, v40
	ds_read_b128 v[56:59], v3 offset:192
	s_waitcnt lgkmcnt(6)
	v_fmac_f32_e32 v20, v60, v33
	v_fmac_f32_e32 v21, v61, v33
	v_fmac_f32_e32 v22, v62, v33
	v_fmac_f32_e32 v23, v63, v33
	v_fmac_f32_e32 v24, v60, v37
	v_fmac_f32_e32 v25, v61, v37
	v_fmac_f32_e32 v26, v62, v37
	v_fmac_f32_e32 v27, v63, v37
	v_fmac_f32_e32 v28, v60, v41
	v_fmac_f32_e32 v29, v61, v41
	v_fmac_f32_e32 v30, v62, v41
	v_fmac_f32_e32 v31, v63, v41
	ds_read_b128 v[60:63], v3 offset:208
	s_waitcnt lgkmcnt(6)
	v_fmac_f32_e32 v20, v64, v34
	v_fmac_f32_e32 v21, v65, v34
	v_fmac_f32_e32 v22, v66, v34
	v_fmac_f32_e32 v23, v67, v34
	v_fmac_f32_e32 v24, v64, v38
	v_fmac_f32_e32 v25, v65, v38
	v_fmac_f32_e32 v26, v66, v38
	v_fmac_f32_e32 v27, v67, v38
	v_fmac_f32_e32 v28, v64, v42
	v_fmac_f32_e32 v29, v65, v42
	v_fmac_f32_e32 v30, v66, v42
	v_fmac_f32_e32 v31, v67, v42
	ds_read_b128 v[64:67], v3 offset:224
	s_waitcnt lgkmcnt(6)
	v_fmac_f32_e32 v20, v68, v35
	v_fmac_f32_e32 v21, v69, v35
	v_fmac_f32_e32 v22, v70, v35
	v_fmac_f32_e32 v23, v71, v35
	v_fmac_f32_e32 v24, v68, v39
	v_fmac_f32_e32 v25, v69, v39
	v_fmac_f32_e32 v26, v70, v39
	v_fmac_f32_e32 v27, v71, v39
	v_fmac_f32_e32 v28, v68, v43
	v_fmac_f32_e32 v29, v69, v43
	v_fmac_f32_e32 v30, v70, v43
	v_fmac_f32_e32 v31, v71, v43
	ds_read_b128 v[68:71], v3 offset:240
	ds_read_b128 v[32:35], v19 offset:64
	ds_read_b128 v[36:39], v19 offset:17472
	ds_read_b128 v[40:43], v2 offset:64
	s_waitcnt lgkmcnt(7)
	s_waitcnt lgkmcnt(6)
	v_fmac_f32_e32 v20, v56, v44
	v_fmac_f32_e32 v21, v57, v44
	v_fmac_f32_e32 v22, v58, v44
	v_fmac_f32_e32 v23, v59, v44
	v_fmac_f32_e32 v24, v56, v48
	v_fmac_f32_e32 v25, v57, v48
	v_fmac_f32_e32 v26, v58, v48
	v_fmac_f32_e32 v27, v59, v48
	v_fmac_f32_e32 v28, v56, v52
	v_fmac_f32_e32 v29, v57, v52
	v_fmac_f32_e32 v30, v58, v52
	v_fmac_f32_e32 v31, v59, v52
	ds_read_b128 v[56:59], v3 offset:256
	s_waitcnt lgkmcnt(6)
	v_fmac_f32_e32 v20, v60, v45
	v_fmac_f32_e32 v21, v61, v45
	v_fmac_f32_e32 v22, v62, v45
	v_fmac_f32_e32 v23, v63, v45
	v_fmac_f32_e32 v24, v60, v49
	v_fmac_f32_e32 v25, v61, v49
	v_fmac_f32_e32 v26, v62, v49
	v_fmac_f32_e32 v27, v63, v49
	v_fmac_f32_e32 v28, v60, v53
	v_fmac_f32_e32 v29, v61, v53
	v_fmac_f32_e32 v30, v62, v53
	v_fmac_f32_e32 v31, v63, v53
	ds_read_b128 v[60:63], v3 offset:272
	s_waitcnt lgkmcnt(6)
	v_fmac_f32_e32 v20, v64, v46
	v_fmac_f32_e32 v21, v65, v46
	v_fmac_f32_e32 v22, v66, v46
	v_fmac_f32_e32 v23, v67, v46
	v_fmac_f32_e32 v24, v64, v50
	v_fmac_f32_e32 v25, v65, v50
	v_fmac_f32_e32 v26, v66, v50
	v_fmac_f32_e32 v27, v67, v50
	v_fmac_f32_e32 v28, v64, v54
	v_fmac_f32_e32 v29, v65, v54
	v_fmac_f32_e32 v30, v66, v54
	v_fmac_f32_e32 v31, v67, v54
	ds_read_b128 v[64:67], v3 offset:288
	s_waitcnt lgkmcnt(6)
	v_fmac_f32_e32 v20, v68, v47
	v_fmac_f32_e32 v21, v69, v47
	v_fmac_f32_e32 v22, v70, v47
	v_fmac_f32_e32 v23, v71, v47
	v_fmac_f32_e32 v24, v68, v51
	v_fmac_f32_e32 v25, v69, v51
	v_fmac_f32_e32 v26, v70, v51
	v_fmac_f32_e32 v27, v71, v51
	v_fmac_f32_e32 v28, v68, v55
	v_fmac_f32_e32 v29, v69, v55
	v_fmac_f32_e32 v30, v70, v55
	v_fmac_f32_e32 v31, v71, v55
	ds_read_b128 v[68:71], v3 offset:304
	ds_read_b128 v[44:47], v19 offset:80
	ds_read_b128 v[48:51], v19 offset:17488
	ds_read_b128 v[52:55], v2 offset:80
	s_waitcnt lgkmcnt(7)
	s_waitcnt lgkmcnt(6)
	v_fmac_f32_e32 v20, v56, v32
	v_fmac_f32_e32 v21, v57, v32
	v_fmac_f32_e32 v22, v58, v32
	v_fmac_f32_e32 v23, v59, v32
	v_fmac_f32_e32 v24, v56, v36
	v_fmac_f32_e32 v25, v57, v36
	v_fmac_f32_e32 v26, v58, v36
	v_fmac_f32_e32 v27, v59, v36
	v_fmac_f32_e32 v28, v56, v40
	v_fmac_f32_e32 v29, v57, v40
	v_fmac_f32_e32 v30, v58, v40
	v_fmac_f32_e32 v31, v59, v40
	ds_read_b128 v[56:59], v3 offset:320
	s_waitcnt lgkmcnt(6)
	v_fmac_f32_e32 v20, v60, v33
	v_fmac_f32_e32 v21, v61, v33
	v_fmac_f32_e32 v22, v62, v33
	v_fmac_f32_e32 v23, v63, v33
	v_fmac_f32_e32 v24, v60, v37
	v_fmac_f32_e32 v25, v61, v37
	v_fmac_f32_e32 v26, v62, v37
	v_fmac_f32_e32 v27, v63, v37
	v_fmac_f32_e32 v28, v60, v41
	v_fmac_f32_e32 v29, v61, v41
	v_fmac_f32_e32 v30, v62, v41
	v_fmac_f32_e32 v31, v63, v41
	ds_read_b128 v[60:63], v3 offset:336
	s_waitcnt lgkmcnt(6)
	v_fmac_f32_e32 v20, v64, v34
	v_fmac_f32_e32 v21, v65, v34
	v_fmac_f32_e32 v22, v66, v34
	v_fmac_f32_e32 v23, v67, v34
	v_fmac_f32_e32 v24, v64, v38
	v_fmac_f32_e32 v25, v65, v38
	v_fmac_f32_e32 v26, v66, v38
	v_fmac_f32_e32 v27, v67, v38
	v_fmac_f32_e32 v28, v64, v42
	v_fmac_f32_e32 v29, v65, v42
	v_fmac_f32_e32 v30, v66, v42
	v_fmac_f32_e32 v31, v67, v42
	ds_read_b128 v[64:67], v3 offset:352
	s_waitcnt lgkmcnt(6)
	v_fmac_f32_e32 v20, v68, v35
	v_fmac_f32_e32 v21, v69, v35
	v_fmac_f32_e32 v22, v70, v35
	v_fmac_f32_e32 v23, v71, v35
	v_fmac_f32_e32 v24, v68, v39
	v_fmac_f32_e32 v25, v69, v39
	v_fmac_f32_e32 v26, v70, v39
	v_fmac_f32_e32 v27, v71, v39
	v_fmac_f32_e32 v28, v68, v43
	v_fmac_f32_e32 v29, v69, v43
	v_fmac_f32_e32 v30, v70, v43
	v_fmac_f32_e32 v31, v71, v43
	ds_read_b128 v[68:71], v3 offset:368
	ds_read_b128 v[32:35], v19 offset:96
	ds_read_b128 v[36:39], v19 offset:17504
	ds_read_b128 v[40:43], v2 offset:96
	s_waitcnt lgkmcnt(7)
	s_waitcnt lgkmcnt(6)
	v_fmac_f32_e32 v20, v56, v44
	v_fmac_f32_e32 v21, v57, v44
	v_fmac_f32_e32 v22, v58, v44
	v_fmac_f32_e32 v23, v59, v44
	v_fmac_f32_e32 v24, v56, v48
	v_fmac_f32_e32 v25, v57, v48
	v_fmac_f32_e32 v26, v58, v48
	v_fmac_f32_e32 v27, v59, v48
	v_fmac_f32_e32 v28, v56, v52
	v_fmac_f32_e32 v29, v57, v52
	v_fmac_f32_e32 v30, v58, v52
	v_fmac_f32_e32 v31, v59, v52
	ds_read_b128 v[56:59], v3 offset:384
	s_waitcnt lgkmcnt(6)
	v_fmac_f32_e32 v20, v60, v45
	v_fmac_f32_e32 v21, v61, v45
	v_fmac_f32_e32 v22, v62, v45
	v_fmac_f32_e32 v23, v63, v45
	v_fmac_f32_e32 v24, v60, v49
	v_fmac_f32_e32 v25, v61, v49
	v_fmac_f32_e32 v26, v62, v49
	v_fmac_f32_e32 v27, v63, v49
	v_fmac_f32_e32 v28, v60, v53
	v_fmac_f32_e32 v29, v61, v53
	v_fmac_f32_e32 v30, v62, v53
	v_fmac_f32_e32 v31, v63, v53
	ds_read_b128 v[60:63], v3 offset:400
	s_waitcnt lgkmcnt(6)
	v_fmac_f32_e32 v20, v64, v46
	v_fmac_f32_e32 v21, v65, v46
	v_fmac_f32_e32 v22, v66, v46
	v_fmac_f32_e32 v23, v67, v46
	v_fmac_f32_e32 v24, v64, v50
	v_fmac_f32_e32 v25, v65, v50
	v_fmac_f32_e32 v26, v66, v50
	v_fmac_f32_e32 v27, v67, v50
	v_fmac_f32_e32 v28, v64, v54
	v_fmac_f32_e32 v29, v65, v54
	v_fmac_f32_e32 v30, v66, v54
	v_fmac_f32_e32 v31, v67, v54
	ds_read_b128 v[64:67], v3 offset:416
	s_waitcnt lgkmcnt(6)
	v_fmac_f32_e32 v20, v68, v47
	v_fmac_f32_e32 v21, v69, v47
	v_fmac_f32_e32 v22, v70, v47
	v_fmac_f32_e32 v23, v71, v47
	v_fmac_f32_e32 v24, v68, v51
	v_fmac_f32_e32 v25, v69, v51
	v_fmac_f32_e32 v26, v70, v51
	v_fmac_f32_e32 v27, v71, v51
	v_fmac_f32_e32 v28, v68, v55
	v_fmac_f32_e32 v29, v69, v55
	v_fmac_f32_e32 v30, v70, v55
	v_fmac_f32_e32 v31, v71, v55
	ds_read_b128 v[68:71], v3 offset:432
	ds_read_b128 v[44:47], v19 offset:112
	ds_read_b128 v[48:51], v19 offset:17520
	ds_read_b128 v[52:55], v2 offset:112
	s_waitcnt lgkmcnt(7)
	s_waitcnt lgkmcnt(6)
	v_fmac_f32_e32 v20, v56, v32
	v_fmac_f32_e32 v21, v57, v32
	v_fmac_f32_e32 v22, v58, v32
	v_fmac_f32_e32 v23, v59, v32
	v_fmac_f32_e32 v24, v56, v36
	v_fmac_f32_e32 v25, v57, v36
	v_fmac_f32_e32 v26, v58, v36
	v_fmac_f32_e32 v27, v59, v36
	v_fmac_f32_e32 v28, v56, v40
	v_fmac_f32_e32 v29, v57, v40
	v_fmac_f32_e32 v30, v58, v40
	v_fmac_f32_e32 v31, v59, v40
	ds_read_b128 v[56:59], v3 offset:448
	s_waitcnt lgkmcnt(6)
	v_fmac_f32_e32 v20, v60, v33
	v_fmac_f32_e32 v21, v61, v33
	v_fmac_f32_e32 v22, v62, v33
	v_fmac_f32_e32 v23, v63, v33
	v_fmac_f32_e32 v24, v60, v37
	v_fmac_f32_e32 v25, v61, v37
	v_fmac_f32_e32 v26, v62, v37
	v_fmac_f32_e32 v27, v63, v37
	v_fmac_f32_e32 v28, v60, v41
	v_fmac_f32_e32 v29, v61, v41
	v_fmac_f32_e32 v30, v62, v41
	v_fmac_f32_e32 v31, v63, v41
	ds_read_b128 v[60:63], v3 offset:464
	s_waitcnt lgkmcnt(6)
	v_fmac_f32_e32 v20, v64, v34
	v_fmac_f32_e32 v21, v65, v34
	v_fmac_f32_e32 v22, v66, v34
	v_fmac_f32_e32 v23, v67, v34
	v_fmac_f32_e32 v24, v64, v38
	v_fmac_f32_e32 v25, v65, v38
	v_fmac_f32_e32 v26, v66, v38
	v_fmac_f32_e32 v27, v67, v38
	v_fmac_f32_e32 v28, v64, v42
	v_fmac_f32_e32 v29, v65, v42
	v_fmac_f32_e32 v30, v66, v42
	v_fmac_f32_e32 v31, v67, v42
	ds_read_b128 v[64:67], v3 offset:480
	s_waitcnt lgkmcnt(6)
	v_fmac_f32_e32 v20, v68, v35
	v_fmac_f32_e32 v21, v69, v35
	v_fmac_f32_e32 v22, v70, v35
	v_fmac_f32_e32 v23, v71, v35
	v_fmac_f32_e32 v24, v68, v39
	v_fmac_f32_e32 v25, v69, v39
	v_fmac_f32_e32 v26, v70, v39
	v_fmac_f32_e32 v27, v71, v39
	v_fmac_f32_e32 v28, v68, v43
	v_fmac_f32_e32 v29, v69, v43
	v_fmac_f32_e32 v30, v70, v43
	v_fmac_f32_e32 v31, v71, v43
	ds_read_b128 v[68:71], v3 offset:496
	ds_read_b128 v[32:35], v19 offset:128
	ds_read_b128 v[36:39], v19 offset:17536
	ds_read_b128 v[40:43], v2 offset:128
	s_waitcnt lgkmcnt(7)
	s_waitcnt lgkmcnt(6)
	v_fmac_f32_e32 v20, v56, v44
	v_fmac_f32_e32 v21, v57, v44
	v_fmac_f32_e32 v22, v58, v44
	v_fmac_f32_e32 v23, v59, v44
	v_fmac_f32_e32 v24, v56, v48
	v_fmac_f32_e32 v25, v57, v48
	v_fmac_f32_e32 v26, v58, v48
	v_fmac_f32_e32 v27, v59, v48
	v_fmac_f32_e32 v28, v56, v52
	v_fmac_f32_e32 v29, v57, v52
	v_fmac_f32_e32 v30, v58, v52
	v_fmac_f32_e32 v31, v59, v52
	ds_read_b128 v[56:59], v3 offset:512
	s_waitcnt lgkmcnt(6)
	v_fmac_f32_e32 v20, v60, v45
	v_fmac_f32_e32 v21, v61, v45
	v_fmac_f32_e32 v22, v62, v45
	v_fmac_f32_e32 v23, v63, v45
	v_fmac_f32_e32 v24, v60, v49
	v_fmac_f32_e32 v25, v61, v49
	v_fmac_f32_e32 v26, v62, v49
	v_fmac_f32_e32 v27, v63, v49
	v_fmac_f32_e32 v28, v60, v53
	v_fmac_f32_e32 v29, v61, v53
	v_fmac_f32_e32 v30, v62, v53
	v_fmac_f32_e32 v31, v63, v53
	ds_read_b128 v[60:63], v3 offset:528
	s_waitcnt lgkmcnt(6)
	v_fmac_f32_e32 v20, v64, v46
	v_fmac_f32_e32 v21, v65, v46
	v_fmac_f32_e32 v22, v66, v46
	v_fmac_f32_e32 v23, v67, v46
	v_fmac_f32_e32 v24, v64, v50
	v_fmac_f32_e32 v25, v65, v50
	v_fmac_f32_e32 v26, v66, v50
	v_fmac_f32_e32 v27, v67, v50
	v_fmac_f32_e32 v28, v64, v54
	v_fmac_f32_e32 v29, v65, v54
	v_fmac_f32_e32 v30, v66, v54
	v_fmac_f32_e32 v31, v67, v54
	ds_read_b128 v[64:67], v3 offset:544
	s_waitcnt lgkmcnt(6)
	v_fmac_f32_e32 v20, v68, v47
	v_fmac_f32_e32 v21, v69, v47
	v_fmac_f32_e32 v22, v70, v47
	v_fmac_f32_e32 v23, v71, v47
	v_fmac_f32_e32 v24, v68, v51
	v_fmac_f32_e32 v25, v69, v51
	v_fmac_f32_e32 v26, v70, v51
	v_fmac_f32_e32 v27, v71, v51
	v_fmac_f32_e32 v28, v68, v55
	v_fmac_f32_e32 v29, v69, v55
	v_fmac_f32_e32 v30, v70, v55
	v_fmac_f32_e32 v31, v71, v55
	ds_read_b128 v[68:71], v3 offset:560
	ds_read_b128 v[44:47], v19 offset:144
	ds_read_b128 v[48:51], v19 offset:17552
	ds_read_b128 v[52:55], v2 offset:144
	s_waitcnt lgkmcnt(7)
	s_waitcnt lgkmcnt(6)
	v_fmac_f32_e32 v20, v56, v32
	v_fmac_f32_e32 v21, v57, v32
	v_fmac_f32_e32 v22, v58, v32
	v_fmac_f32_e32 v23, v59, v32
	v_fmac_f32_e32 v24, v56, v36
	v_fmac_f32_e32 v25, v57, v36
	v_fmac_f32_e32 v26, v58, v36
	v_fmac_f32_e32 v27, v59, v36
	v_fmac_f32_e32 v28, v56, v40
	v_fmac_f32_e32 v29, v57, v40
	v_fmac_f32_e32 v30, v58, v40
	v_fmac_f32_e32 v31, v59, v40
	ds_read_b128 v[56:59], v3 offset:576
	s_waitcnt lgkmcnt(6)
	v_fmac_f32_e32 v20, v60, v33
	v_fmac_f32_e32 v21, v61, v33
	v_fmac_f32_e32 v22, v62, v33
	v_fmac_f32_e32 v23, v63, v33
	v_fmac_f32_e32 v24, v60, v37
	v_fmac_f32_e32 v25, v61, v37
	v_fmac_f32_e32 v26, v62, v37
	v_fmac_f32_e32 v27, v63, v37
	v_fmac_f32_e32 v28, v60, v41
	v_fmac_f32_e32 v29, v61, v41
	v_fmac_f32_e32 v30, v62, v41
	v_fmac_f32_e32 v31, v63, v41
	ds_read_b128 v[60:63], v3 offset:592
	s_waitcnt lgkmcnt(6)
	v_fmac_f32_e32 v20, v64, v34
	v_fmac_f32_e32 v21, v65, v34
	v_fmac_f32_e32 v22, v66, v34
	v_fmac_f32_e32 v23, v67, v34
	v_fmac_f32_e32 v24, v64, v38
	v_fmac_f32_e32 v25, v65, v38
	v_fmac_f32_e32 v26, v66, v38
	v_fmac_f32_e32 v27, v67, v38
	v_fmac_f32_e32 v28, v64, v42
	v_fmac_f32_e32 v29, v65, v42
	v_fmac_f32_e32 v30, v66, v42
	v_fmac_f32_e32 v31, v67, v42
	ds_read_b128 v[64:67], v3 offset:608
	s_waitcnt lgkmcnt(6)
	v_fmac_f32_e32 v20, v68, v35
	v_fmac_f32_e32 v21, v69, v35
	v_fmac_f32_e32 v22, v70, v35
	v_fmac_f32_e32 v23, v71, v35
	v_fmac_f32_e32 v24, v68, v39
	v_fmac_f32_e32 v25, v69, v39
	v_fmac_f32_e32 v26, v70, v39
	v_fmac_f32_e32 v27, v71, v39
	v_fmac_f32_e32 v28, v68, v43
	v_fmac_f32_e32 v29, v69, v43
	v_fmac_f32_e32 v30, v70, v43
	v_fmac_f32_e32 v31, v71, v43
	ds_read_b128 v[68:71], v3 offset:624
	ds_read_b128 v[32:35], v19 offset:160
	ds_read_b128 v[36:39], v19 offset:17568
	ds_read_b128 v[40:43], v2 offset:160
	s_waitcnt lgkmcnt(7)
	s_waitcnt lgkmcnt(6)
	v_fmac_f32_e32 v20, v56, v44
	v_fmac_f32_e32 v21, v57, v44
	v_fmac_f32_e32 v22, v58, v44
	v_fmac_f32_e32 v23, v59, v44
	v_fmac_f32_e32 v24, v56, v48
	v_fmac_f32_e32 v25, v57, v48
	v_fmac_f32_e32 v26, v58, v48
	v_fmac_f32_e32 v27, v59, v48
	v_fmac_f32_e32 v28, v56, v52
	v_fmac_f32_e32 v29, v57, v52
	v_fmac_f32_e32 v30, v58, v52
	v_fmac_f32_e32 v31, v59, v52
	ds_read_b128 v[56:59], v3 offset:640
	s_waitcnt lgkmcnt(6)
	v_fmac_f32_e32 v20, v60, v45
	v_fmac_f32_e32 v21, v61, v45
	v_fmac_f32_e32 v22, v62, v45
	v_fmac_f32_e32 v23, v63, v45
	v_fmac_f32_e32 v24, v60, v49
	v_fmac_f32_e32 v25, v61, v49
	v_fmac_f32_e32 v26, v62, v49
	v_fmac_f32_e32 v27, v63, v49
	v_fmac_f32_e32 v28, v60, v53
	v_fmac_f32_e32 v29, v61, v53
	v_fmac_f32_e32 v30, v62, v53
	v_fmac_f32_e32 v31, v63, v53
	ds_read_b128 v[60:63], v3 offset:656
	s_waitcnt lgkmcnt(6)
	v_fmac_f32_e32 v20, v64, v46
	v_fmac_f32_e32 v21, v65, v46
	v_fmac_f32_e32 v22, v66, v46
	v_fmac_f32_e32 v23, v67, v46
	v_fmac_f32_e32 v24, v64, v50
	v_fmac_f32_e32 v25, v65, v50
	v_fmac_f32_e32 v26, v66, v50
	v_fmac_f32_e32 v27, v67, v50
	v_fmac_f32_e32 v28, v64, v54
	v_fmac_f32_e32 v29, v65, v54
	v_fmac_f32_e32 v30, v66, v54
	v_fmac_f32_e32 v31, v67, v54
	ds_read_b128 v[64:67], v3 offset:672
	s_waitcnt lgkmcnt(6)
	v_fmac_f32_e32 v20, v68, v47
	v_fmac_f32_e32 v21, v69, v47
	v_fmac_f32_e32 v22, v70, v47
	v_fmac_f32_e32 v23, v71, v47
	v_fmac_f32_e32 v24, v68, v51
	v_fmac_f32_e32 v25, v69, v51
	v_fmac_f32_e32 v26, v70, v51
	v_fmac_f32_e32 v27, v71, v51
	v_fmac_f32_e32 v28, v68, v55
	v_fmac_f32_e32 v29, v69, v55
	v_fmac_f32_e32 v30, v70, v55
	v_fmac_f32_e32 v31, v71, v55
	ds_read_b128 v[68:71], v3 offset:688
	ds_read_b128 v[44:47], v19 offset:176
	ds_read_b128 v[48:51], v19 offset:17584
	ds_read_b128 v[52:55], v2 offset:176
	s_waitcnt lgkmcnt(7)
	s_waitcnt lgkmcnt(6)
	v_fmac_f32_e32 v20, v56, v32
	v_fmac_f32_e32 v21, v57, v32
	v_fmac_f32_e32 v22, v58, v32
	v_fmac_f32_e32 v23, v59, v32
	v_fmac_f32_e32 v24, v56, v36
	v_fmac_f32_e32 v25, v57, v36
	v_fmac_f32_e32 v26, v58, v36
	v_fmac_f32_e32 v27, v59, v36
	v_fmac_f32_e32 v28, v56, v40
	v_fmac_f32_e32 v29, v57, v40
	v_fmac_f32_e32 v30, v58, v40
	v_fmac_f32_e32 v31, v59, v40
	ds_read_b128 v[56:59], v3 offset:704
	s_waitcnt lgkmcnt(6)
	v_fmac_f32_e32 v20, v60, v33
	v_fmac_f32_e32 v21, v61, v33
	v_fmac_f32_e32 v22, v62, v33
	v_fmac_f32_e32 v23, v63, v33
	v_fmac_f32_e32 v24, v60, v37
	v_fmac_f32_e32 v25, v61, v37
	v_fmac_f32_e32 v26, v62, v37
	v_fmac_f32_e32 v27, v63, v37
	v_fmac_f32_e32 v28, v60, v41
	v_fmac_f32_e32 v29, v61, v41
	v_fmac_f32_e32 v30, v62, v41
	v_fmac_f32_e32 v31, v63, v41
	ds_read_b128 v[60:63], v3 offset:720
	s_waitcnt lgkmcnt(6)
	v_fmac_f32_e32 v20, v64, v34
	v_fmac_f32_e32 v21, v65, v34
	v_fmac_f32_e32 v22, v66, v34
	v_fmac_f32_e32 v23, v67, v34
	v_fmac_f32_e32 v24, v64, v38
	v_fmac_f32_e32 v25, v65, v38
	v_fmac_f32_e32 v26, v66, v38
	v_fmac_f32_e32 v27, v67, v38
	v_fmac_f32_e32 v28, v64, v42
	v_fmac_f32_e32 v29, v65, v42
	v_fmac_f32_e32 v30, v66, v42
	v_fmac_f32_e32 v31, v67, v42
	ds_read_b128 v[64:67], v3 offset:736
	s_waitcnt lgkmcnt(6)
	v_fmac_f32_e32 v20, v68, v35
	v_fmac_f32_e32 v21, v69, v35
	v_fmac_f32_e32 v22, v70, v35
	v_fmac_f32_e32 v23, v71, v35
	v_fmac_f32_e32 v24, v68, v39
	v_fmac_f32_e32 v25, v69, v39
	v_fmac_f32_e32 v26, v70, v39
	v_fmac_f32_e32 v27, v71, v39
	v_fmac_f32_e32 v28, v68, v43
	v_fmac_f32_e32 v29, v69, v43
	v_fmac_f32_e32 v30, v70, v43
	v_fmac_f32_e32 v31, v71, v43
	ds_read_b128 v[68:71], v3 offset:752
	ds_read_b128 v[32:35], v19 offset:192
	ds_read_b128 v[36:39], v19 offset:17600
	ds_read_b128 v[40:43], v2 offset:192
	s_waitcnt lgkmcnt(7)
	s_waitcnt lgkmcnt(6)
	v_fmac_f32_e32 v20, v56, v44
	v_fmac_f32_e32 v21, v57, v44
	v_fmac_f32_e32 v22, v58, v44
	v_fmac_f32_e32 v23, v59, v44
	v_fmac_f32_e32 v24, v56, v48
	v_fmac_f32_e32 v25, v57, v48
	v_fmac_f32_e32 v26, v58, v48
	v_fmac_f32_e32 v27, v59, v48
	v_fmac_f32_e32 v28, v56, v52
	v_fmac_f32_e32 v29, v57, v52
	v_fmac_f32_e32 v30, v58, v52
	v_fmac_f32_e32 v31, v59, v52
	ds_read_b128 v[56:59], v3 offset:768
	s_waitcnt lgkmcnt(6)
	v_fmac_f32_e32 v20, v60, v45
	v_fmac_f32_e32 v21, v61, v45
	v_fmac_f32_e32 v22, v62, v45
	v_fmac_f32_e32 v23, v63, v45
	v_fmac_f32_e32 v24, v60, v49
	v_fmac_f32_e32 v25, v61, v49
	v_fmac_f32_e32 v26, v62, v49
	v_fmac_f32_e32 v27, v63, v49
	v_fmac_f32_e32 v28, v60, v53
	v_fmac_f32_e32 v29, v61, v53
	v_fmac_f32_e32 v30, v62, v53
	v_fmac_f32_e32 v31, v63, v53
	ds_read_b128 v[60:63], v3 offset:784
	s_waitcnt lgkmcnt(6)
	v_fmac_f32_e32 v20, v64, v46
	v_fmac_f32_e32 v21, v65, v46
	v_fmac_f32_e32 v22, v66, v46
	v_fmac_f32_e32 v23, v67, v46
	v_fmac_f32_e32 v24, v64, v50
	v_fmac_f32_e32 v25, v65, v50
	v_fmac_f32_e32 v26, v66, v50
	v_fmac_f32_e32 v27, v67, v50
	v_fmac_f32_e32 v28, v64, v54
	v_fmac_f32_e32 v29, v65, v54
	v_fmac_f32_e32 v30, v66, v54
	v_fmac_f32_e32 v31, v67, v54
	ds_read_b128 v[64:67], v3 offset:800
	s_waitcnt lgkmcnt(6)
	v_fmac_f32_e32 v20, v68, v47
	v_fmac_f32_e32 v21, v69, v47
	v_fmac_f32_e32 v22, v70, v47
	v_fmac_f32_e32 v23, v71, v47
	v_fmac_f32_e32 v24, v68, v51
	v_fmac_f32_e32 v25, v69, v51
	v_fmac_f32_e32 v26, v70, v51
	v_fmac_f32_e32 v27, v71, v51
	v_fmac_f32_e32 v28, v68, v55
	v_fmac_f32_e32 v29, v69, v55
	v_fmac_f32_e32 v30, v70, v55
	v_fmac_f32_e32 v31, v71, v55
	ds_read_b128 v[68:71], v3 offset:816
	ds_read_b128 v[44:47], v19 offset:208
	ds_read_b128 v[48:51], v19 offset:17616
	ds_read_b128 v[52:55], v2 offset:208
	s_waitcnt lgkmcnt(7)
	s_waitcnt lgkmcnt(6)
	v_fmac_f32_e32 v20, v56, v32
	v_fmac_f32_e32 v21, v57, v32
	v_fmac_f32_e32 v22, v58, v32
	v_fmac_f32_e32 v23, v59, v32
	v_fmac_f32_e32 v24, v56, v36
	v_fmac_f32_e32 v25, v57, v36
	v_fmac_f32_e32 v26, v58, v36
	v_fmac_f32_e32 v27, v59, v36
	v_fmac_f32_e32 v28, v56, v40
	v_fmac_f32_e32 v29, v57, v40
	v_fmac_f32_e32 v30, v58, v40
	v_fmac_f32_e32 v31, v59, v40
	ds_read_b128 v[56:59], v3 offset:832
	s_waitcnt lgkmcnt(6)
	v_fmac_f32_e32 v20, v60, v33
	v_fmac_f32_e32 v21, v61, v33
	v_fmac_f32_e32 v22, v62, v33
	v_fmac_f32_e32 v23, v63, v33
	v_fmac_f32_e32 v24, v60, v37
	v_fmac_f32_e32 v25, v61, v37
	v_fmac_f32_e32 v26, v62, v37
	v_fmac_f32_e32 v27, v63, v37
	v_fmac_f32_e32 v28, v60, v41
	v_fmac_f32_e32 v29, v61, v41
	v_fmac_f32_e32 v30, v62, v41
	v_fmac_f32_e32 v31, v63, v41
	ds_read_b128 v[60:63], v3 offset:848
	s_waitcnt lgkmcnt(6)
	v_fmac_f32_e32 v20, v64, v34
	v_fmac_f32_e32 v21, v65, v34
	v_fmac_f32_e32 v22, v66, v34
	v_fmac_f32_e32 v23, v67, v34
	v_fmac_f32_e32 v24, v64, v38
	v_fmac_f32_e32 v25, v65, v38
	v_fmac_f32_e32 v26, v66, v38
	v_fmac_f32_e32 v27, v67, v38
	v_fmac_f32_e32 v28, v64, v42
	v_fmac_f32_e32 v29, v65, v42
	v_fmac_f32_e32 v30, v66, v42
	v_fmac_f32_e32 v31, v67, v42
	ds_read_b128 v[64:67], v3 offset:864
	s_waitcnt lgkmcnt(6)
	v_fmac_f32_e32 v20, v68, v35
	v_fmac_f32_e32 v21, v69, v35
	v_fmac_f32_e32 v22, v70, v35
	v_fmac_f32_e32 v23, v71, v35
	v_fmac_f32_e32 v24, v68, v39
	v_fmac_f32_e32 v25, v69, v39
	v_fmac_f32_e32 v26, v70, v39
	v_fmac_f32_e32 v27, v71, v39
	v_fmac_f32_e32 v28, v68, v43
	v_fmac_f32_e32 v29, v69, v43
	v_fmac_f32_e32 v30, v70, v43
	v_fmac_f32_e32 v31, v71, v43
	ds_read_b128 v[68:71], v3 offset:880
	ds_read_b128 v[32:35], v19 offset:224
	ds_read_b128 v[36:39], v19 offset:17632
	ds_read_b128 v[40:43], v2 offset:224
	s_waitcnt lgkmcnt(7)
	s_waitcnt lgkmcnt(6)
	v_fmac_f32_e32 v20, v56, v44
	v_fmac_f32_e32 v21, v57, v44
	v_fmac_f32_e32 v22, v58, v44
	v_fmac_f32_e32 v23, v59, v44
	v_fmac_f32_e32 v24, v56, v48
	v_fmac_f32_e32 v25, v57, v48
	v_fmac_f32_e32 v26, v58, v48
	v_fmac_f32_e32 v27, v59, v48
	v_fmac_f32_e32 v28, v56, v52
	v_fmac_f32_e32 v29, v57, v52
	v_fmac_f32_e32 v30, v58, v52
	v_fmac_f32_e32 v31, v59, v52
	ds_read_b128 v[56:59], v3 offset:896
	s_waitcnt lgkmcnt(6)
	v_fmac_f32_e32 v20, v60, v45
	v_fmac_f32_e32 v21, v61, v45
	v_fmac_f32_e32 v22, v62, v45
	v_fmac_f32_e32 v23, v63, v45
	v_fmac_f32_e32 v24, v60, v49
	v_fmac_f32_e32 v25, v61, v49
	v_fmac_f32_e32 v26, v62, v49
	v_fmac_f32_e32 v27, v63, v49
	v_fmac_f32_e32 v28, v60, v53
	v_fmac_f32_e32 v29, v61, v53
	v_fmac_f32_e32 v30, v62, v53
	v_fmac_f32_e32 v31, v63, v53
	ds_read_b128 v[60:63], v3 offset:912
	s_waitcnt lgkmcnt(6)
	v_fmac_f32_e32 v20, v64, v46
	v_fmac_f32_e32 v21, v65, v46
	v_fmac_f32_e32 v22, v66, v46
	v_fmac_f32_e32 v23, v67, v46
	v_fmac_f32_e32 v24, v64, v50
	v_fmac_f32_e32 v25, v65, v50
	v_fmac_f32_e32 v26, v66, v50
	v_fmac_f32_e32 v27, v67, v50
	v_fmac_f32_e32 v28, v64, v54
	v_fmac_f32_e32 v29, v65, v54
	v_fmac_f32_e32 v30, v66, v54
	v_fmac_f32_e32 v31, v67, v54
	ds_read_b128 v[64:67], v3 offset:928
	s_waitcnt lgkmcnt(6)
	v_fmac_f32_e32 v20, v68, v47
	v_fmac_f32_e32 v21, v69, v47
	v_fmac_f32_e32 v22, v70, v47
	v_fmac_f32_e32 v23, v71, v47
	v_fmac_f32_e32 v24, v68, v51
	v_fmac_f32_e32 v25, v69, v51
	v_fmac_f32_e32 v26, v70, v51
	v_fmac_f32_e32 v27, v71, v51
	v_fmac_f32_e32 v28, v68, v55
	v_fmac_f32_e32 v29, v69, v55
	v_fmac_f32_e32 v30, v70, v55
	v_fmac_f32_e32 v31, v71, v55
	ds_read_b128 v[68:71], v3 offset:944
	ds_read_b128 v[44:47], v19 offset:240
	ds_read_b128 v[48:51], v19 offset:17648
	ds_read_b128 v[52:55], v2 offset:240
	s_waitcnt lgkmcnt(7)
	s_waitcnt lgkmcnt(6)
	v_fmac_f32_e32 v20, v56, v32
	v_fmac_f32_e32 v21, v57, v32
	v_fmac_f32_e32 v22, v58, v32
	v_fmac_f32_e32 v23, v59, v32
	v_fmac_f32_e32 v24, v56, v36
	v_fmac_f32_e32 v25, v57, v36
	v_fmac_f32_e32 v26, v58, v36
	v_fmac_f32_e32 v27, v59, v36
	v_fmac_f32_e32 v28, v56, v40
	v_fmac_f32_e32 v29, v57, v40
	v_fmac_f32_e32 v30, v58, v40
	v_fmac_f32_e32 v31, v59, v40
	ds_read_b128 v[56:59], v3 offset:960
	s_waitcnt lgkmcnt(6)
	v_fmac_f32_e32 v20, v60, v33
	v_fmac_f32_e32 v21, v61, v33
	v_fmac_f32_e32 v22, v62, v33
	v_fmac_f32_e32 v23, v63, v33
	v_fmac_f32_e32 v24, v60, v37
	v_fmac_f32_e32 v25, v61, v37
	v_fmac_f32_e32 v26, v62, v37
	v_fmac_f32_e32 v27, v63, v37
	v_fmac_f32_e32 v28, v60, v41
	v_fmac_f32_e32 v29, v61, v41
	v_fmac_f32_e32 v30, v62, v41
	v_fmac_f32_e32 v31, v63, v41
	ds_read_b128 v[60:63], v3 offset:976
	s_waitcnt lgkmcnt(6)
	v_fmac_f32_e32 v20, v64, v34
	v_fmac_f32_e32 v21, v65, v34
	v_fmac_f32_e32 v22, v66, v34
	v_fmac_f32_e32 v23, v67, v34
	v_fmac_f32_e32 v24, v64, v38
	v_fmac_f32_e32 v25, v65, v38
	v_fmac_f32_e32 v26, v66, v38
	v_fmac_f32_e32 v27, v67, v38
	v_fmac_f32_e32 v28, v64, v42
	v_fmac_f32_e32 v29, v65, v42
	v_fmac_f32_e32 v30, v66, v42
	v_fmac_f32_e32 v31, v67, v42
	ds_read_b128 v[64:67], v3 offset:992
	s_waitcnt lgkmcnt(6)
	v_fmac_f32_e32 v20, v68, v35
	v_fmac_f32_e32 v21, v69, v35
	v_fmac_f32_e32 v22, v70, v35
	v_fmac_f32_e32 v23, v71, v35
	v_fmac_f32_e32 v24, v68, v39
	v_fmac_f32_e32 v25, v69, v39
	v_fmac_f32_e32 v26, v70, v39
	v_fmac_f32_e32 v27, v71, v39
	v_fmac_f32_e32 v28, v68, v43
	v_fmac_f32_e32 v29, v69, v43
	v_fmac_f32_e32 v30, v70, v43
	v_fmac_f32_e32 v31, v71, v43
	ds_read_b128 v[68:71], v3 offset:1008
	s_waitcnt lgkmcnt(4)
	s_waitcnt lgkmcnt(3)
	v_fmac_f32_e32 v20, v56, v44
	v_fmac_f32_e32 v21, v57, v44
	v_fmac_f32_e32 v22, v58, v44
	v_fmac_f32_e32 v23, v59, v44
	v_fmac_f32_e32 v24, v56, v48
	v_fmac_f32_e32 v25, v57, v48
	v_fmac_f32_e32 v26, v58, v48
	v_fmac_f32_e32 v27, v59, v48
	v_fmac_f32_e32 v28, v56, v52
	v_fmac_f32_e32 v29, v57, v52
	v_fmac_f32_e32 v30, v58, v52
	v_fmac_f32_e32 v31, v59, v52
	s_waitcnt lgkmcnt(2)
	v_fmac_f32_e32 v20, v60, v45
	v_fmac_f32_e32 v21, v61, v45
	v_fmac_f32_e32 v22, v62, v45
	v_fmac_f32_e32 v23, v63, v45
	v_fmac_f32_e32 v24, v60, v49
	v_fmac_f32_e32 v25, v61, v49
	v_fmac_f32_e32 v26, v62, v49
	v_fmac_f32_e32 v27, v63, v49
	v_fmac_f32_e32 v28, v60, v53
	v_fmac_f32_e32 v29, v61, v53
	v_fmac_f32_e32 v30, v62, v53
	v_fmac_f32_e32 v31, v63, v53
	s_waitcnt lgkmcnt(1)
	v_fmac_f32_e32 v20, v64, v46
	v_fmac_f32_e32 v21, v65, v46
	v_fmac_f32_e32 v22, v66, v46
	v_fmac_f32_e32 v23, v67, v46
	v_fmac_f32_e32 v24, v64, v50
	v_fmac_f32_e32 v25, v65, v50
	v_fmac_f32_e32 v26, v66, v50
	v_fmac_f32_e32 v27, v67, v50
	v_fmac_f32_e32 v28, v64, v54
	v_fmac_f32_e32 v29, v65, v54
	v_fmac_f32_e32 v30, v66, v54
	v_fmac_f32_e32 v31, v67, v54
	s_waitcnt lgkmcnt(0)
	v_fmac_f32_e32 v20, v68, v47
	v_fmac_f32_e32 v21, v69, v47
	v_fmac_f32_e32 v22, v70, v47
	v_fmac_f32_e32 v23, v71, v47
	v_fmac_f32_e32 v24, v68, v51
	v_fmac_f32_e32 v25, v69, v51
	v_fmac_f32_e32 v26, v70, v51
	v_fmac_f32_e32 v27, v71, v51
	v_fmac_f32_e32 v28, v68, v55
	v_fmac_f32_e32 v29, v69, v55
	v_fmac_f32_e32 v30, v70, v55
	v_fmac_f32_e32 v31, v71, v55
	s_add_u32 s8, s10, 0x14180000
	s_addc_u32 s9, s11, 0
	s_lshl_b32 s2, s44, 9
	s_add_u32 s8, s8, s2
	s_addc_u32 s9, s9, 0
	v_sub_u32_e32 v44, 128, v7
	v_and_b32_e32 v44, 0x7f, v44
	v_lshlrev_b32_e32 v44, 2, v44
	global_load_dword v32, v44, s[8:9]
	v_sub_u32_e32 v44, 129, v7
	v_and_b32_e32 v44, 0x7f, v44
	v_lshlrev_b32_e32 v44, 2, v44
	global_load_dword v33, v44, s[8:9]
	v_sub_u32_e32 v44, 130, v7
	v_and_b32_e32 v44, 0x7f, v44
	v_lshlrev_b32_e32 v44, 2, v44
	global_load_dword v34, v44, s[8:9]
	v_sub_u32_e32 v44, 131, v7
	v_and_b32_e32 v44, 0x7f, v44
	v_lshlrev_b32_e32 v44, 2, v44
	global_load_dword v35, v44, s[8:9]
	v_sub_u32_e32 v44, 64, v7
	v_and_b32_e32 v44, 0x7f, v44
	v_lshlrev_b32_e32 v44, 2, v44
	global_load_dword v36, v44, s[8:9]
	v_sub_u32_e32 v44, 65, v7
	v_and_b32_e32 v44, 0x7f, v44
	v_lshlrev_b32_e32 v44, 2, v44
	global_load_dword v37, v44, s[8:9]
	v_sub_u32_e32 v44, 66, v7
	v_and_b32_e32 v44, 0x7f, v44
	v_lshlrev_b32_e32 v44, 2, v44
	global_load_dword v38, v44, s[8:9]
	v_sub_u32_e32 v44, 67, v7
	v_and_b32_e32 v44, 0x7f, v44
	v_lshlrev_b32_e32 v44, 2, v44
	global_load_dword v39, v44, s[8:9]
	v_sub_u32_e32 v44, 0, v7
	v_and_b32_e32 v44, 0x7f, v44
	v_lshlrev_b32_e32 v44, 2, v44
	global_load_dword v40, v44, s[8:9]
	v_sub_u32_e32 v44, 1, v7
	v_and_b32_e32 v44, 0x7f, v44
	v_lshlrev_b32_e32 v44, 2, v44
	global_load_dword v41, v44, s[8:9]
	v_sub_u32_e32 v44, 2, v7
	v_and_b32_e32 v44, 0x7f, v44
	v_lshlrev_b32_e32 v44, 2, v44
	global_load_dword v42, v44, s[8:9]
	v_sub_u32_e32 v44, 3, v7
	v_and_b32_e32 v44, 0x7f, v44
	v_lshlrev_b32_e32 v44, 2, v44
	global_load_dword v43, v44, s[8:9]
	s_waitcnt vmcnt(0)
	v_add_f32_e32 v20, v20, v32
	v_add_f32_e32 v21, v21, v33
	v_add_f32_e32 v22, v22, v34
	v_add_f32_e32 v23, v23, v35
	v_add_f32_e32 v24, v24, v36
	v_add_f32_e32 v25, v25, v37
	v_add_f32_e32 v26, v26, v38
	v_add_f32_e32 v27, v27, v39
	v_add_f32_e32 v28, v28, v40
	v_add_f32_e32 v29, v29, v41
	v_add_f32_e32 v30, v30, v42
	v_add_f32_e32 v31, v31, v43
	v_mov_b32_e32 v45, 0xff800000
	v_cmp_lt_u32_e32 vcc, 0, v7
	s_nop 1
	v_cndmask_b32_e32 v20, v45, v20, vcc
	v_cmp_ge_u32_e32 vcc, 0, v7
	s_nop 1
	v_cndmask_b32_e32 v28, v45, v28, vcc
	v_cmp_lt_u32_e32 vcc, 1, v7
	s_nop 1
	v_cndmask_b32_e32 v21, v45, v21, vcc
	v_cmp_ge_u32_e32 vcc, 1, v7
	s_nop 1
	v_cndmask_b32_e32 v29, v45, v29, vcc
	v_cmp_lt_u32_e32 vcc, 2, v7
	s_nop 1
	v_cndmask_b32_e32 v22, v45, v22, vcc
	v_cmp_ge_u32_e32 vcc, 2, v7
	s_nop 1
	v_cndmask_b32_e32 v30, v45, v30, vcc
	v_cmp_lt_u32_e32 vcc, 3, v7
	s_nop 1
	v_cndmask_b32_e32 v23, v45, v23, vcc
	v_cmp_ge_u32_e32 vcc, 3, v7
	s_nop 1
	v_cndmask_b32_e32 v31, v45, v31, vcc
	v_max3_f32 v46, v20, v24, v28
	v_max3_f32 v47, v21, v25, v29
	v_max3_f32 v48, v22, v26, v30
	v_max3_f32 v49, v23, v27, v31
	v_xor_b32_e32 v54, 32, v7
	v_lshlrev_b32_e32 v54, 2, v54
	ds_swizzle_b32 v50, v46 offset:0x41f
	ds_swizzle_b32 v51, v47 offset:0x41f
	ds_swizzle_b32 v52, v48 offset:0x41f
	ds_swizzle_b32 v53, v49 offset:0x41f
	s_waitcnt lgkmcnt(0)
	v_max_f32_e32 v46, v46, v50
	v_max_f32_e32 v47, v47, v51
	v_max_f32_e32 v48, v48, v52
	v_max_f32_e32 v49, v49, v53
	ds_swizzle_b32 v50, v46 offset:0x81f
	ds_swizzle_b32 v51, v47 offset:0x81f
	ds_swizzle_b32 v52, v48 offset:0x81f
	ds_swizzle_b32 v53, v49 offset:0x81f
	s_waitcnt lgkmcnt(0)
	v_max_f32_e32 v46, v46, v50
	v_max_f32_e32 v47, v47, v51
	v_max_f32_e32 v48, v48, v52
	v_max_f32_e32 v49, v49, v53
	ds_swizzle_b32 v50, v46 offset:0x101f
	ds_swizzle_b32 v51, v47 offset:0x101f
	ds_swizzle_b32 v52, v48 offset:0x101f
	ds_swizzle_b32 v53, v49 offset:0x101f
	s_waitcnt lgkmcnt(0)
	v_max_f32_e32 v46, v46, v50
	v_max_f32_e32 v47, v47, v51
	v_max_f32_e32 v48, v48, v52
	v_max_f32_e32 v49, v49, v53
	ds_swizzle_b32 v50, v46 offset:0x201f
	ds_swizzle_b32 v51, v47 offset:0x201f
	ds_swizzle_b32 v52, v48 offset:0x201f
	ds_swizzle_b32 v53, v49 offset:0x201f
	s_waitcnt lgkmcnt(0)
	v_max_f32_e32 v46, v46, v50
	v_max_f32_e32 v47, v47, v51
	v_max_f32_e32 v48, v48, v52
	v_max_f32_e32 v49, v49, v53
	ds_swizzle_b32 v50, v46 offset:0x401f
	ds_swizzle_b32 v51, v47 offset:0x401f
	ds_swizzle_b32 v52, v48 offset:0x401f
	ds_swizzle_b32 v53, v49 offset:0x401f
	s_waitcnt lgkmcnt(0)
	v_max_f32_e32 v46, v46, v50
	v_max_f32_e32 v47, v47, v51
	v_max_f32_e32 v48, v48, v52
	v_max_f32_e32 v49, v49, v53
	ds_bpermute_b32 v50, v54, v46
	ds_bpermute_b32 v51, v54, v47
	ds_bpermute_b32 v52, v54, v48
	ds_bpermute_b32 v53, v54, v49
	s_waitcnt lgkmcnt(0)
	v_max_f32_e32 v46, v46, v50
	v_max_f32_e32 v47, v47, v51
	v_max_f32_e32 v48, v48, v52
	v_max_f32_e32 v49, v49, v53
	s_waitcnt lgkmcnt(0)
	v_max_f32_e32 v46, s58, v46
	v_max_f32_e32 v47, s58, v47
	v_max_f32_e32 v48, s58, v48
	v_max_f32_e32 v49, s58, v49
	v_mov_b32_e32 v55, 0x3fb8aa3b
	v_sub_f32_e32 v20, v20, v46
	v_sub_f32_e32 v21, v21, v47
	v_sub_f32_e32 v22, v22, v48
	v_sub_f32_e32 v23, v23, v49
	v_sub_f32_e32 v24, v24, v46
	v_sub_f32_e32 v25, v25, v47
	v_sub_f32_e32 v26, v26, v48
	v_sub_f32_e32 v27, v27, v49
	v_sub_f32_e32 v28, v28, v46
	v_sub_f32_e32 v29, v29, v47
	v_sub_f32_e32 v30, v30, v48
	v_sub_f32_e32 v31, v31, v49
	v_mul_f32_e32 v20, v55, v20
	v_mul_f32_e32 v21, v55, v21
	v_mul_f32_e32 v22, v55, v22
	v_mul_f32_e32 v23, v55, v23
	v_mul_f32_e32 v24, v55, v24
	v_mul_f32_e32 v25, v55, v25
	v_mul_f32_e32 v26, v55, v26
	v_mul_f32_e32 v27, v55, v27
	v_mul_f32_e32 v28, v55, v28
	v_mul_f32_e32 v29, v55, v29
	v_mul_f32_e32 v30, v55, v30
	v_mul_f32_e32 v31, v55, v31
	v_exp_f32_e32 v20, v20
	v_exp_f32_e32 v21, v21
	v_exp_f32_e32 v22, v22
	v_exp_f32_e32 v23, v23
	v_exp_f32_e32 v24, v24
	v_exp_f32_e32 v25, v25
	v_exp_f32_e32 v26, v26
	v_exp_f32_e32 v27, v27
	v_exp_f32_e32 v28, v28
	v_exp_f32_e32 v29, v29
	v_exp_f32_e32 v30, v30
	v_exp_f32_e32 v31, v31
	s_nop 1
	v_add_f32_e32 v56, v20, v24
	v_add_f32_e32 v57, v21, v25
	v_add_f32_e32 v58, v22, v26
	v_add_f32_e32 v59, v23, v27
	v_add_f32_e32 v56, v56, v28
	v_add_f32_e32 v57, v57, v29
	v_add_f32_e32 v58, v58, v30
	v_add_f32_e32 v59, v59, v31
	ds_swizzle_b32 v50, v56 offset:0x41f
	ds_swizzle_b32 v51, v57 offset:0x41f
	ds_swizzle_b32 v52, v58 offset:0x41f
	ds_swizzle_b32 v53, v59 offset:0x41f
	s_waitcnt lgkmcnt(0)
	v_add_f32_e32 v56, v56, v50
	v_add_f32_e32 v57, v57, v51
	v_add_f32_e32 v58, v58, v52
	v_add_f32_e32 v59, v59, v53
	ds_swizzle_b32 v50, v56 offset:0x81f
	ds_swizzle_b32 v51, v57 offset:0x81f
	ds_swizzle_b32 v52, v58 offset:0x81f
	ds_swizzle_b32 v53, v59 offset:0x81f
	s_waitcnt lgkmcnt(0)
	v_add_f32_e32 v56, v56, v50
	v_add_f32_e32 v57, v57, v51
	v_add_f32_e32 v58, v58, v52
	v_add_f32_e32 v59, v59, v53
	ds_swizzle_b32 v50, v56 offset:0x101f
	ds_swizzle_b32 v51, v57 offset:0x101f
	ds_swizzle_b32 v52, v58 offset:0x101f
	ds_swizzle_b32 v53, v59 offset:0x101f
	s_waitcnt lgkmcnt(0)
	v_add_f32_e32 v56, v56, v50
	v_add_f32_e32 v57, v57, v51
	v_add_f32_e32 v58, v58, v52
	v_add_f32_e32 v59, v59, v53
	ds_swizzle_b32 v50, v56 offset:0x201f
	ds_swizzle_b32 v51, v57 offset:0x201f
	ds_swizzle_b32 v52, v58 offset:0x201f
	ds_swizzle_b32 v53, v59 offset:0x201f
	s_waitcnt lgkmcnt(0)
	v_add_f32_e32 v56, v56, v50
	v_add_f32_e32 v57, v57, v51
	v_add_f32_e32 v58, v58, v52
	v_add_f32_e32 v59, v59, v53
	ds_swizzle_b32 v50, v56 offset:0x401f
	ds_swizzle_b32 v51, v57 offset:0x401f
	ds_swizzle_b32 v52, v58 offset:0x401f
	ds_swizzle_b32 v53, v59 offset:0x401f
	s_waitcnt lgkmcnt(0)
	v_add_f32_e32 v56, v56, v50
	v_add_f32_e32 v57, v57, v51
	v_add_f32_e32 v58, v58, v52
	v_add_f32_e32 v59, v59, v53
	ds_bpermute_b32 v50, v54, v56
	ds_bpermute_b32 v51, v54, v57
	ds_bpermute_b32 v52, v54, v58
	ds_bpermute_b32 v53, v54, v59
	s_waitcnt lgkmcnt(0)
	v_add_f32_e32 v56, v56, v50
	v_add_f32_e32 v57, v57, v51
	v_add_f32_e32 v58, v58, v52
	v_add_f32_e32 v59, v59, v53
	v_sub_f32_e32 v60, s58, v46
	v_sub_f32_e32 v61, s58, v47
	v_sub_f32_e32 v62, s58, v48
	v_sub_f32_e32 v63, s58, v49
	v_mul_f32_e32 v60, v55, v60
	v_mul_f32_e32 v61, v55, v61
	v_mul_f32_e32 v62, v55, v62
	v_mul_f32_e32 v63, v55, v63
	v_exp_f32_e32 v60, v60
	v_exp_f32_e32 v61, v61
	v_exp_f32_e32 v62, v62
	v_exp_f32_e32 v63, v63
	s_nop 1
	v_add_f32_e32 v56, v56, v60
	v_add_f32_e32 v57, v57, v61
	v_add_f32_e32 v58, v58, v62
	v_add_f32_e32 v59, v59, v63
	v_rcp_f32_e32 v60, v56
	v_rcp_f32_e32 v61, v57
	v_rcp_f32_e32 v62, v58
	v_rcp_f32_e32 v63, v59
	s_nop 1
	v_fma_f32 v50, -v56, v60, 1.0
	v_fma_f32 v51, -v57, v61, 1.0
	v_fma_f32 v52, -v58, v62, 1.0
	v_fma_f32 v53, -v59, v63, 1.0
	v_fma_f32 v60, v50, v60, v60
	v_fma_f32 v61, v51, v61, v61
	v_fma_f32 v62, v52, v62, v62
	v_fma_f32 v63, v53, v63, v63
	v_mul_f32_e32 v20, v20, v60
	v_mul_f32_e32 v21, v21, v61
	v_mul_f32_e32 v22, v22, v62
	v_mul_f32_e32 v23, v23, v63
	v_mul_f32_e32 v24, v24, v60
	v_mul_f32_e32 v25, v25, v61
	v_mul_f32_e32 v26, v26, v62
	v_mul_f32_e32 v27, v27, v63
	v_mul_f32_e32 v28, v28, v60
	v_mul_f32_e32 v29, v29, v61
	v_mul_f32_e32 v30, v30, v62
	v_mul_f32_e32 v31, v31, v63
	v_add_u32_e32 v17, 0x400, v17
	ds_write_b128 v17, v[20:23]
	ds_write_b128 v17, v[24:27] offset:1024
	ds_write_b128 v17, v[28:31] offset:2048
	s_waitcnt lgkmcnt(0)
	v_lshlrev_b32_e32 v19, 2, v7
	v_add_u32_e32 v19, 0x9000, v19
	s_add_i32 s2, s59, 0x400
	v_mov_b32_e32 v3, s2
	v_mov_b32_e32 v4, 0
	v_mov_b32_e32 v5, 0
	v_mov_b32_e32 v6, 0
	v_mov_b32_e32 v8, 0
	ds_read_b128 v[20:23], v3 offset:0
	ds_read_b32 v32, v19 offset:0
	ds_read_b128 v[24:27], v3 offset:16
	ds_read_b32 v33, v19 offset:256
	ds_read_b128 v[28:31], v3 offset:32
	ds_read_b32 v34, v19 offset:512
	ds_read_b128 v[36:39], v3 offset:48
	ds_read_b32 v48, v19 offset:768
	ds_read_b128 v[40:43], v3 offset:64
	ds_read_b32 v49, v19 offset:1024
	ds_read_b128 v[44:47], v3 offset:80
	ds_read_b32 v50, v19 offset:1280
	s_waitcnt lgkmcnt(10)
	v_fmac_f32_e32 v4, v20, v32
	v_fmac_f32_e32 v5, v21, v32
	v_fmac_f32_e32 v6, v22, v32
	v_fmac_f32_e32 v8, v23, v32
	s_waitcnt lgkmcnt(8)
	v_fmac_f32_e32 v4, v24, v33
	v_fmac_f32_e32 v5, v25, v33
	v_fmac_f32_e32 v6, v26, v33
	v_fmac_f32_e32 v8, v27, v33
	s_waitcnt lgkmcnt(6)
	v_fmac_f32_e32 v4, v28, v34
	v_fmac_f32_e32 v5, v29, v34
	v_fmac_f32_e32 v6, v30, v34
	v_fmac_f32_e32 v8, v31, v34
	ds_read_b128 v[20:23], v3 offset:96
	ds_read_b32 v32, v19 offset:1536
	ds_read_b128 v[24:27], v3 offset:112
	ds_read_b32 v33, v19 offset:1792
	ds_read_b128 v[28:31], v3 offset:128
	ds_read_b32 v34, v19 offset:2048
	s_waitcnt lgkmcnt(10)
	v_fmac_f32_e32 v4, v36, v48
	v_fmac_f32_e32 v5, v37, v48
	v_fmac_f32_e32 v6, v38, v48
	v_fmac_f32_e32 v8, v39, v48
	s_waitcnt lgkmcnt(8)
	v_fmac_f32_e32 v4, v40, v49
	v_fmac_f32_e32 v5, v41, v49
	v_fmac_f32_e32 v6, v42, v49
	v_fmac_f32_e32 v8, v43, v49
	s_waitcnt lgkmcnt(6)
	v_fmac_f32_e32 v4, v44, v50
	v_fmac_f32_e32 v5, v45, v50
	v_fmac_f32_e32 v6, v46, v50
	v_fmac_f32_e32 v8, v47, v50
	ds_read_b128 v[36:39], v3 offset:144
	ds_read_b32 v48, v19 offset:2304
	ds_read_b128 v[40:43], v3 offset:160
	ds_read_b32 v49, v19 offset:2560
	ds_read_b128 v[44:47], v3 offset:176
	ds_read_b32 v50, v19 offset:2816
	s_waitcnt lgkmcnt(10)
	v_fmac_f32_e32 v4, v20, v32
	v_fmac_f32_e32 v5, v21, v32
	v_fmac_f32_e32 v6, v22, v32
	v_fmac_f32_e32 v8, v23, v32
	s_waitcnt lgkmcnt(8)
	v_fmac_f32_e32 v4, v24, v33
	v_fmac_f32_e32 v5, v25, v33
	v_fmac_f32_e32 v6, v26, v33
	v_fmac_f32_e32 v8, v27, v33
	s_waitcnt lgkmcnt(6)
	v_fmac_f32_e32 v4, v28, v34
	v_fmac_f32_e32 v5, v29, v34
	v_fmac_f32_e32 v6, v30, v34
	v_fmac_f32_e32 v8, v31, v34
	ds_read_b128 v[20:23], v3 offset:192
	ds_read_b32 v32, v19 offset:3072
	ds_read_b128 v[24:27], v3 offset:208
	ds_read_b32 v33, v19 offset:3328
	ds_read_b128 v[28:31], v3 offset:224
	ds_read_b32 v34, v19 offset:3584
	s_waitcnt lgkmcnt(10)
	v_fmac_f32_e32 v4, v36, v48
	v_fmac_f32_e32 v5, v37, v48
	v_fmac_f32_e32 v6, v38, v48
	v_fmac_f32_e32 v8, v39, v48
	s_waitcnt lgkmcnt(8)
	v_fmac_f32_e32 v4, v40, v49
	v_fmac_f32_e32 v5, v41, v49
	v_fmac_f32_e32 v6, v42, v49
	v_fmac_f32_e32 v8, v43, v49
	s_waitcnt lgkmcnt(6)
	v_fmac_f32_e32 v4, v44, v50
	v_fmac_f32_e32 v5, v45, v50
	v_fmac_f32_e32 v6, v46, v50
	v_fmac_f32_e32 v8, v47, v50
	ds_read_b128 v[36:39], v3 offset:240
	ds_read_b32 v48, v19 offset:3840
	ds_read_b128 v[40:43], v3 offset:256
	ds_read_b32 v49, v19 offset:4096
	ds_read_b128 v[44:47], v3 offset:272
	ds_read_b32 v50, v19 offset:4352
	s_waitcnt lgkmcnt(10)
	v_fmac_f32_e32 v4, v20, v32
	v_fmac_f32_e32 v5, v21, v32
	v_fmac_f32_e32 v6, v22, v32
	v_fmac_f32_e32 v8, v23, v32
	s_waitcnt lgkmcnt(8)
	v_fmac_f32_e32 v4, v24, v33
	v_fmac_f32_e32 v5, v25, v33
	v_fmac_f32_e32 v6, v26, v33
	v_fmac_f32_e32 v8, v27, v33
	s_waitcnt lgkmcnt(6)
	v_fmac_f32_e32 v4, v28, v34
	v_fmac_f32_e32 v5, v29, v34
	v_fmac_f32_e32 v6, v30, v34
	v_fmac_f32_e32 v8, v31, v34
	ds_read_b128 v[20:23], v3 offset:288
	ds_read_b32 v32, v19 offset:4608
	ds_read_b128 v[24:27], v3 offset:304
	ds_read_b32 v33, v19 offset:4864
	ds_read_b128 v[28:31], v3 offset:320
	ds_read_b32 v34, v19 offset:5120
	s_waitcnt lgkmcnt(10)
	v_fmac_f32_e32 v4, v36, v48
	v_fmac_f32_e32 v5, v37, v48
	v_fmac_f32_e32 v6, v38, v48
	v_fmac_f32_e32 v8, v39, v48
	s_waitcnt lgkmcnt(8)
	v_fmac_f32_e32 v4, v40, v49
	v_fmac_f32_e32 v5, v41, v49
	v_fmac_f32_e32 v6, v42, v49
	v_fmac_f32_e32 v8, v43, v49
	s_waitcnt lgkmcnt(6)
	v_fmac_f32_e32 v4, v44, v50
	v_fmac_f32_e32 v5, v45, v50
	v_fmac_f32_e32 v6, v46, v50
	v_fmac_f32_e32 v8, v47, v50
	ds_read_b128 v[36:39], v3 offset:336
	ds_read_b32 v48, v19 offset:5376
	ds_read_b128 v[40:43], v3 offset:352
	ds_read_b32 v49, v19 offset:5632
	ds_read_b128 v[44:47], v3 offset:368
	ds_read_b32 v50, v19 offset:5888
	s_waitcnt lgkmcnt(10)
	v_fmac_f32_e32 v4, v20, v32
	v_fmac_f32_e32 v5, v21, v32
	v_fmac_f32_e32 v6, v22, v32
	v_fmac_f32_e32 v8, v23, v32
	s_waitcnt lgkmcnt(8)
	v_fmac_f32_e32 v4, v24, v33
	v_fmac_f32_e32 v5, v25, v33
	v_fmac_f32_e32 v6, v26, v33
	v_fmac_f32_e32 v8, v27, v33
	s_waitcnt lgkmcnt(6)
	v_fmac_f32_e32 v4, v28, v34
	v_fmac_f32_e32 v5, v29, v34
	v_fmac_f32_e32 v6, v30, v34
	v_fmac_f32_e32 v8, v31, v34
	ds_read_b128 v[20:23], v3 offset:384
	ds_read_b32 v32, v19 offset:6144
	ds_read_b128 v[24:27], v3 offset:400
	ds_read_b32 v33, v19 offset:6400
	ds_read_b128 v[28:31], v3 offset:416
	ds_read_b32 v34, v19 offset:6656
	s_waitcnt lgkmcnt(10)
	v_fmac_f32_e32 v4, v36, v48
	v_fmac_f32_e32 v5, v37, v48
	v_fmac_f32_e32 v6, v38, v48
	v_fmac_f32_e32 v8, v39, v48
	s_waitcnt lgkmcnt(8)
	v_fmac_f32_e32 v4, v40, v49
	v_fmac_f32_e32 v5, v41, v49
	v_fmac_f32_e32 v6, v42, v49
	v_fmac_f32_e32 v8, v43, v49
	s_waitcnt lgkmcnt(6)
	v_fmac_f32_e32 v4, v44, v50
	v_fmac_f32_e32 v5, v45, v50
	v_fmac_f32_e32 v6, v46, v50
	v_fmac_f32_e32 v8, v47, v50
	ds_read_b128 v[36:39], v3 offset:432
	ds_read_b32 v48, v19 offset:6912
	ds_read_b128 v[40:43], v3 offset:448
	ds_read_b32 v49, v19 offset:7168
	ds_read_b128 v[44:47], v3 offset:464
	ds_read_b32 v50, v19 offset:7424
	s_waitcnt lgkmcnt(10)
	v_fmac_f32_e32 v4, v20, v32
	v_fmac_f32_e32 v5, v21, v32
	v_fmac_f32_e32 v6, v22, v32
	v_fmac_f32_e32 v8, v23, v32
	s_waitcnt lgkmcnt(8)
	v_fmac_f32_e32 v4, v24, v33
	v_fmac_f32_e32 v5, v25, v33
	v_fmac_f32_e32 v6, v26, v33
	v_fmac_f32_e32 v8, v27, v33
	s_waitcnt lgkmcnt(6)
	v_fmac_f32_e32 v4, v28, v34
	v_fmac_f32_e32 v5, v29, v34
	v_fmac_f32_e32 v6, v30, v34
	v_fmac_f32_e32 v8, v31, v34
	ds_read_b128 v[20:23], v3 offset:480
	ds_read_b32 v32, v19 offset:7680
	ds_read_b128 v[24:27], v3 offset:496
	ds_read_b32 v33, v19 offset:7936
	ds_read_b128 v[28:31], v3 offset:512
	ds_read_b32 v34, v19 offset:8192
	s_waitcnt lgkmcnt(10)
	v_fmac_f32_e32 v4, v36, v48
	v_fmac_f32_e32 v5, v37, v48
	v_fmac_f32_e32 v6, v38, v48
	v_fmac_f32_e32 v8, v39, v48
	s_waitcnt lgkmcnt(8)
	v_fmac_f32_e32 v4, v40, v49
	v_fmac_f32_e32 v5, v41, v49
	v_fmac_f32_e32 v6, v42, v49
	v_fmac_f32_e32 v8, v43, v49
	s_waitcnt lgkmcnt(6)
	v_fmac_f32_e32 v4, v44, v50
	v_fmac_f32_e32 v5, v45, v50
	v_fmac_f32_e32 v6, v46, v50
	v_fmac_f32_e32 v8, v47, v50
	ds_read_b128 v[36:39], v3 offset:528
	ds_read_b32 v48, v19 offset:8448
	ds_read_b128 v[40:43], v3 offset:544
	ds_read_b32 v49, v19 offset:8704
	ds_read_b128 v[44:47], v3 offset:560
	ds_read_b32 v50, v19 offset:8960
	s_waitcnt lgkmcnt(10)
	v_fmac_f32_e32 v4, v20, v32
	v_fmac_f32_e32 v5, v21, v32
	v_fmac_f32_e32 v6, v22, v32
	v_fmac_f32_e32 v8, v23, v32
	s_waitcnt lgkmcnt(8)
	v_fmac_f32_e32 v4, v24, v33
	v_fmac_f32_e32 v5, v25, v33
	v_fmac_f32_e32 v6, v26, v33
	v_fmac_f32_e32 v8, v27, v33
	s_waitcnt lgkmcnt(6)
	v_fmac_f32_e32 v4, v28, v34
	v_fmac_f32_e32 v5, v29, v34
	v_fmac_f32_e32 v6, v30, v34
	v_fmac_f32_e32 v8, v31, v34
	ds_read_b128 v[20:23], v3 offset:576
	ds_read_b32 v32, v19 offset:9216
	ds_read_b128 v[24:27], v3 offset:592
	ds_read_b32 v33, v19 offset:9472
	ds_read_b128 v[28:31], v3 offset:608
	ds_read_b32 v34, v19 offset:9728
	s_waitcnt lgkmcnt(10)
	v_fmac_f32_e32 v4, v36, v48
	v_fmac_f32_e32 v5, v37, v48
	v_fmac_f32_e32 v6, v38, v48
	v_fmac_f32_e32 v8, v39, v48
	s_waitcnt lgkmcnt(8)
	v_fmac_f32_e32 v4, v40, v49
	v_fmac_f32_e32 v5, v41, v49
	v_fmac_f32_e32 v6, v42, v49
	v_fmac_f32_e32 v8, v43, v49
	s_waitcnt lgkmcnt(6)
	v_fmac_f32_e32 v4, v44, v50
	v_fmac_f32_e32 v5, v45, v50
	v_fmac_f32_e32 v6, v46, v50
	v_fmac_f32_e32 v8, v47, v50
	ds_read_b128 v[36:39], v3 offset:624
	ds_read_b32 v48, v19 offset:9984
	ds_read_b128 v[40:43], v3 offset:640
	ds_read_b32 v49, v19 offset:10240
	ds_read_b128 v[44:47], v3 offset:656
	ds_read_b32 v50, v19 offset:10496
	s_waitcnt lgkmcnt(10)
	v_fmac_f32_e32 v4, v20, v32
	v_fmac_f32_e32 v5, v21, v32
	v_fmac_f32_e32 v6, v22, v32
	v_fmac_f32_e32 v8, v23, v32
	s_waitcnt lgkmcnt(8)
	v_fmac_f32_e32 v4, v24, v33
	v_fmac_f32_e32 v5, v25, v33
	v_fmac_f32_e32 v6, v26, v33
	v_fmac_f32_e32 v8, v27, v33
	s_waitcnt lgkmcnt(6)
	v_fmac_f32_e32 v4, v28, v34
	v_fmac_f32_e32 v5, v29, v34
	v_fmac_f32_e32 v6, v30, v34
	v_fmac_f32_e32 v8, v31, v34
	ds_read_b128 v[20:23], v3 offset:672
	ds_read_b32 v32, v19 offset:10752
	ds_read_b128 v[24:27], v3 offset:688
	ds_read_b32 v33, v19 offset:11008
	ds_read_b128 v[28:31], v3 offset:704
	ds_read_b32 v34, v19 offset:11264
	s_waitcnt lgkmcnt(10)
	v_fmac_f32_e32 v4, v36, v48
	v_fmac_f32_e32 v5, v37, v48
	v_fmac_f32_e32 v6, v38, v48
	v_fmac_f32_e32 v8, v39, v48
	s_waitcnt lgkmcnt(8)
	v_fmac_f32_e32 v4, v40, v49
	v_fmac_f32_e32 v5, v41, v49
	v_fmac_f32_e32 v6, v42, v49
	v_fmac_f32_e32 v8, v43, v49
	s_waitcnt lgkmcnt(6)
	v_fmac_f32_e32 v4, v44, v50
	v_fmac_f32_e32 v5, v45, v50
	v_fmac_f32_e32 v6, v46, v50
	v_fmac_f32_e32 v8, v47, v50
	ds_read_b128 v[36:39], v3 offset:720
	ds_read_b32 v48, v19 offset:11520
	ds_read_b128 v[40:43], v3 offset:736
	ds_read_b32 v49, v19 offset:11776
	ds_read_b128 v[44:47], v3 offset:752
	ds_read_b32 v50, v19 offset:12032
	s_waitcnt lgkmcnt(10)
	v_fmac_f32_e32 v4, v20, v32
	v_fmac_f32_e32 v5, v21, v32
	v_fmac_f32_e32 v6, v22, v32
	v_fmac_f32_e32 v8, v23, v32
	s_waitcnt lgkmcnt(8)
	v_fmac_f32_e32 v4, v24, v33
	v_fmac_f32_e32 v5, v25, v33
	v_fmac_f32_e32 v6, v26, v33
	v_fmac_f32_e32 v8, v27, v33
	s_waitcnt lgkmcnt(6)
	v_fmac_f32_e32 v4, v28, v34
	v_fmac_f32_e32 v5, v29, v34
	v_fmac_f32_e32 v6, v30, v34
	v_fmac_f32_e32 v8, v31, v34
	ds_read_b128 v[20:23], v3 offset:768
	ds_read_b32 v32, v19 offset:12288
	ds_read_b128 v[24:27], v3 offset:784
	ds_read_b32 v33, v19 offset:12544
	ds_read_b128 v[28:31], v3 offset:800
	ds_read_b32 v34, v19 offset:12800
	s_waitcnt lgkmcnt(10)
	v_fmac_f32_e32 v4, v36, v48
	v_fmac_f32_e32 v5, v37, v48
	v_fmac_f32_e32 v6, v38, v48
	v_fmac_f32_e32 v8, v39, v48
	s_waitcnt lgkmcnt(8)
	v_fmac_f32_e32 v4, v40, v49
	v_fmac_f32_e32 v5, v41, v49
	v_fmac_f32_e32 v6, v42, v49
	v_fmac_f32_e32 v8, v43, v49
	s_waitcnt lgkmcnt(6)
	v_fmac_f32_e32 v4, v44, v50
	v_fmac_f32_e32 v5, v45, v50
	v_fmac_f32_e32 v6, v46, v50
	v_fmac_f32_e32 v8, v47, v50
	ds_read_b128 v[36:39], v3 offset:816
	ds_read_b32 v48, v19 offset:13056
	ds_read_b128 v[40:43], v3 offset:832
	ds_read_b32 v49, v19 offset:13312
	ds_read_b128 v[44:47], v3 offset:848
	ds_read_b32 v50, v19 offset:13568
	s_waitcnt lgkmcnt(10)
	v_fmac_f32_e32 v4, v20, v32
	v_fmac_f32_e32 v5, v21, v32
	v_fmac_f32_e32 v6, v22, v32
	v_fmac_f32_e32 v8, v23, v32
	s_waitcnt lgkmcnt(8)
	v_fmac_f32_e32 v4, v24, v33
	v_fmac_f32_e32 v5, v25, v33
	v_fmac_f32_e32 v6, v26, v33
	v_fmac_f32_e32 v8, v27, v33
	s_waitcnt lgkmcnt(6)
	v_fmac_f32_e32 v4, v28, v34
	v_fmac_f32_e32 v5, v29, v34
	v_fmac_f32_e32 v6, v30, v34
	v_fmac_f32_e32 v8, v31, v34
	ds_read_b128 v[20:23], v3 offset:864
	ds_read_b32 v32, v19 offset:13824
	ds_read_b128 v[24:27], v3 offset:880
	ds_read_b32 v33, v19 offset:14080
	ds_read_b128 v[28:31], v3 offset:896
	ds_read_b32 v34, v19 offset:14336
	s_waitcnt lgkmcnt(10)
	v_fmac_f32_e32 v4, v36, v48
	v_fmac_f32_e32 v5, v37, v48
	v_fmac_f32_e32 v6, v38, v48
	v_fmac_f32_e32 v8, v39, v48
	s_waitcnt lgkmcnt(8)
	v_fmac_f32_e32 v4, v40, v49
	v_fmac_f32_e32 v5, v41, v49
	v_fmac_f32_e32 v6, v42, v49
	v_fmac_f32_e32 v8, v43, v49
	s_waitcnt lgkmcnt(6)
	v_fmac_f32_e32 v4, v44, v50
	v_fmac_f32_e32 v5, v45, v50
	v_fmac_f32_e32 v6, v46, v50
	v_fmac_f32_e32 v8, v47, v50
	ds_read_b128 v[36:39], v3 offset:912
	ds_read_b32 v48, v19 offset:14592
	ds_read_b128 v[40:43], v3 offset:928
	ds_read_b32 v49, v19 offset:14848
	ds_read_b128 v[44:47], v3 offset:944
	ds_read_b32 v50, v19 offset:15104
	s_waitcnt lgkmcnt(10)
	v_fmac_f32_e32 v4, v20, v32
	v_fmac_f32_e32 v5, v21, v32
	v_fmac_f32_e32 v6, v22, v32
	v_fmac_f32_e32 v8, v23, v32
	s_waitcnt lgkmcnt(8)
	v_fmac_f32_e32 v4, v24, v33
	v_fmac_f32_e32 v5, v25, v33
	v_fmac_f32_e32 v6, v26, v33
	v_fmac_f32_e32 v8, v27, v33
	s_waitcnt lgkmcnt(6)
	v_fmac_f32_e32 v4, v28, v34
	v_fmac_f32_e32 v5, v29, v34
	v_fmac_f32_e32 v6, v30, v34
	v_fmac_f32_e32 v8, v31, v34
	ds_read_b128 v[20:23], v3 offset:960
	ds_read_b32 v32, v19 offset:15360
	ds_read_b128 v[24:27], v3 offset:976
	ds_read_b32 v33, v19 offset:15616
	ds_read_b128 v[28:31], v3 offset:992
	ds_read_b32 v34, v19 offset:15872
	s_waitcnt lgkmcnt(10)
	v_fmac_f32_e32 v4, v36, v48
	v_fmac_f32_e32 v5, v37, v48
	v_fmac_f32_e32 v6, v38, v48
	v_fmac_f32_e32 v8, v39, v48
	s_waitcnt lgkmcnt(8)
	v_fmac_f32_e32 v4, v40, v49
	v_fmac_f32_e32 v5, v41, v49
	v_fmac_f32_e32 v6, v42, v49
	v_fmac_f32_e32 v8, v43, v49
	s_waitcnt lgkmcnt(6)
	v_fmac_f32_e32 v4, v44, v50
	v_fmac_f32_e32 v5, v45, v50
	v_fmac_f32_e32 v6, v46, v50
	v_fmac_f32_e32 v8, v47, v50
	ds_read_b128 v[36:39], v3 offset:1008
	ds_read_b32 v48, v19 offset:16128
	ds_read_b128 v[40:43], v3 offset:1024
	ds_read_b32 v49, v19 offset:16384
	ds_read_b128 v[44:47], v3 offset:1040
	ds_read_b32 v50, v19 offset:16640
	s_waitcnt lgkmcnt(10)
	v_fmac_f32_e32 v4, v20, v32
	v_fmac_f32_e32 v5, v21, v32
	v_fmac_f32_e32 v6, v22, v32
	v_fmac_f32_e32 v8, v23, v32
	s_waitcnt lgkmcnt(8)
	v_fmac_f32_e32 v4, v24, v33
	v_fmac_f32_e32 v5, v25, v33
	v_fmac_f32_e32 v6, v26, v33
	v_fmac_f32_e32 v8, v27, v33
	s_waitcnt lgkmcnt(6)
	v_fmac_f32_e32 v4, v28, v34
	v_fmac_f32_e32 v5, v29, v34
	v_fmac_f32_e32 v6, v30, v34
	v_fmac_f32_e32 v8, v31, v34
	ds_read_b128 v[20:23], v3 offset:1056
	ds_read_b32 v32, v19 offset:16896
	ds_read_b128 v[24:27], v3 offset:1072
	ds_read_b32 v33, v19 offset:17152
	ds_read_b128 v[28:31], v3 offset:1088
	ds_read_b32 v34, v19 offset:17408
	s_waitcnt lgkmcnt(10)
	v_fmac_f32_e32 v4, v36, v48
	v_fmac_f32_e32 v5, v37, v48
	v_fmac_f32_e32 v6, v38, v48
	v_fmac_f32_e32 v8, v39, v48
	s_waitcnt lgkmcnt(8)
	v_fmac_f32_e32 v4, v40, v49
	v_fmac_f32_e32 v5, v41, v49
	v_fmac_f32_e32 v6, v42, v49
	v_fmac_f32_e32 v8, v43, v49
	s_waitcnt lgkmcnt(6)
	v_fmac_f32_e32 v4, v44, v50
	v_fmac_f32_e32 v5, v45, v50
	v_fmac_f32_e32 v6, v46, v50
	v_fmac_f32_e32 v8, v47, v50
	ds_read_b128 v[36:39], v3 offset:1104
	ds_read_b32 v48, v19 offset:17664
	ds_read_b128 v[40:43], v3 offset:1120
	ds_read_b32 v49, v19 offset:17920
	ds_read_b128 v[44:47], v3 offset:1136
	ds_read_b32 v50, v19 offset:18176
	s_waitcnt lgkmcnt(10)
	v_fmac_f32_e32 v4, v20, v32
	v_fmac_f32_e32 v5, v21, v32
	v_fmac_f32_e32 v6, v22, v32
	v_fmac_f32_e32 v8, v23, v32
	s_waitcnt lgkmcnt(8)
	v_fmac_f32_e32 v4, v24, v33
	v_fmac_f32_e32 v5, v25, v33
	v_fmac_f32_e32 v6, v26, v33
	v_fmac_f32_e32 v8, v27, v33
	s_waitcnt lgkmcnt(6)
	v_fmac_f32_e32 v4, v28, v34
	v_fmac_f32_e32 v5, v29, v34
	v_fmac_f32_e32 v6, v30, v34
	v_fmac_f32_e32 v8, v31, v34
	ds_read_b128 v[20:23], v3 offset:1152
	ds_read_b32 v32, v19 offset:18432
	ds_read_b128 v[24:27], v3 offset:1168
	ds_read_b32 v33, v19 offset:18688
	ds_read_b128 v[28:31], v3 offset:1184
	ds_read_b32 v34, v19 offset:18944
	s_waitcnt lgkmcnt(10)
	v_fmac_f32_e32 v4, v36, v48
	v_fmac_f32_e32 v5, v37, v48
	v_fmac_f32_e32 v6, v38, v48
	v_fmac_f32_e32 v8, v39, v48
	s_waitcnt lgkmcnt(8)
	v_fmac_f32_e32 v4, v40, v49
	v_fmac_f32_e32 v5, v41, v49
	v_fmac_f32_e32 v6, v42, v49
	v_fmac_f32_e32 v8, v43, v49
	s_waitcnt lgkmcnt(6)
	v_fmac_f32_e32 v4, v44, v50
	v_fmac_f32_e32 v5, v45, v50
	v_fmac_f32_e32 v6, v46, v50
	v_fmac_f32_e32 v8, v47, v50
	ds_read_b128 v[36:39], v3 offset:1200
	ds_read_b32 v48, v19 offset:19200
	ds_read_b128 v[40:43], v3 offset:1216
	ds_read_b32 v49, v19 offset:19456
	ds_read_b128 v[44:47], v3 offset:1232
	ds_read_b32 v50, v19 offset:19712
	s_waitcnt lgkmcnt(10)
	v_fmac_f32_e32 v4, v20, v32
	v_fmac_f32_e32 v5, v21, v32
	v_fmac_f32_e32 v6, v22, v32
	v_fmac_f32_e32 v8, v23, v32
	s_waitcnt lgkmcnt(8)
	v_fmac_f32_e32 v4, v24, v33
	v_fmac_f32_e32 v5, v25, v33
	v_fmac_f32_e32 v6, v26, v33
	v_fmac_f32_e32 v8, v27, v33
	s_waitcnt lgkmcnt(6)
	v_fmac_f32_e32 v4, v28, v34
	v_fmac_f32_e32 v5, v29, v34
	v_fmac_f32_e32 v6, v30, v34
	v_fmac_f32_e32 v8, v31, v34
	ds_read_b128 v[20:23], v3 offset:1248
	ds_read_b32 v32, v19 offset:19968
	ds_read_b128 v[24:27], v3 offset:1264
	ds_read_b32 v33, v19 offset:20224
	ds_read_b128 v[28:31], v3 offset:1280
	ds_read_b32 v34, v19 offset:20480
	s_waitcnt lgkmcnt(10)
	v_fmac_f32_e32 v4, v36, v48
	v_fmac_f32_e32 v5, v37, v48
	v_fmac_f32_e32 v6, v38, v48
	v_fmac_f32_e32 v8, v39, v48
	s_waitcnt lgkmcnt(8)
	v_fmac_f32_e32 v4, v40, v49
	v_fmac_f32_e32 v5, v41, v49
	v_fmac_f32_e32 v6, v42, v49
	v_fmac_f32_e32 v8, v43, v49
	s_waitcnt lgkmcnt(6)
	v_fmac_f32_e32 v4, v44, v50
	v_fmac_f32_e32 v5, v45, v50
	v_fmac_f32_e32 v6, v46, v50
	v_fmac_f32_e32 v8, v47, v50
	ds_read_b128 v[36:39], v3 offset:1296
	ds_read_b32 v48, v19 offset:20736
	ds_read_b128 v[40:43], v3 offset:1312
	ds_read_b32 v49, v19 offset:20992
	ds_read_b128 v[44:47], v3 offset:1328
	ds_read_b32 v50, v19 offset:21248
	s_waitcnt lgkmcnt(10)
	v_fmac_f32_e32 v4, v20, v32
	v_fmac_f32_e32 v5, v21, v32
	v_fmac_f32_e32 v6, v22, v32
	v_fmac_f32_e32 v8, v23, v32
	s_waitcnt lgkmcnt(8)
	v_fmac_f32_e32 v4, v24, v33
	v_fmac_f32_e32 v5, v25, v33
	v_fmac_f32_e32 v6, v26, v33
	v_fmac_f32_e32 v8, v27, v33
	s_waitcnt lgkmcnt(6)
	v_fmac_f32_e32 v4, v28, v34
	v_fmac_f32_e32 v5, v29, v34
	v_fmac_f32_e32 v6, v30, v34
	v_fmac_f32_e32 v8, v31, v34
	ds_read_b128 v[20:23], v3 offset:1344
	ds_read_b32 v32, v19 offset:21504
	ds_read_b128 v[24:27], v3 offset:1360
	ds_read_b32 v33, v19 offset:21760
	ds_read_b128 v[28:31], v3 offset:1376
	ds_read_b32 v34, v19 offset:22016
	s_waitcnt lgkmcnt(10)
	v_fmac_f32_e32 v4, v36, v48
	v_fmac_f32_e32 v5, v37, v48
	v_fmac_f32_e32 v6, v38, v48
	v_fmac_f32_e32 v8, v39, v48
	s_waitcnt lgkmcnt(8)
	v_fmac_f32_e32 v4, v40, v49
	v_fmac_f32_e32 v5, v41, v49
	v_fmac_f32_e32 v6, v42, v49
	v_fmac_f32_e32 v8, v43, v49
	s_waitcnt lgkmcnt(6)
	v_fmac_f32_e32 v4, v44, v50
	v_fmac_f32_e32 v5, v45, v50
	v_fmac_f32_e32 v6, v46, v50
	v_fmac_f32_e32 v8, v47, v50
	ds_read_b128 v[36:39], v3 offset:1392
	ds_read_b32 v48, v19 offset:22272
	ds_read_b128 v[40:43], v3 offset:1408
	ds_read_b32 v49, v19 offset:22528
	ds_read_b128 v[44:47], v3 offset:1424
	ds_read_b32 v50, v19 offset:22784
	s_waitcnt lgkmcnt(10)
	v_fmac_f32_e32 v4, v20, v32
	v_fmac_f32_e32 v5, v21, v32
	v_fmac_f32_e32 v6, v22, v32
	v_fmac_f32_e32 v8, v23, v32
	s_waitcnt lgkmcnt(8)
	v_fmac_f32_e32 v4, v24, v33
	v_fmac_f32_e32 v5, v25, v33
	v_fmac_f32_e32 v6, v26, v33
	v_fmac_f32_e32 v8, v27, v33
	s_waitcnt lgkmcnt(6)
	v_fmac_f32_e32 v4, v28, v34
	v_fmac_f32_e32 v5, v29, v34
	v_fmac_f32_e32 v6, v30, v34
	v_fmac_f32_e32 v8, v31, v34
	ds_read_b128 v[20:23], v3 offset:1440
	ds_read_b32 v32, v19 offset:23040
	ds_read_b128 v[24:27], v3 offset:1456
	ds_read_b32 v33, v19 offset:23296
	ds_read_b128 v[28:31], v3 offset:1472
	ds_read_b32 v34, v19 offset:23552
	s_waitcnt lgkmcnt(10)
	v_fmac_f32_e32 v4, v36, v48
	v_fmac_f32_e32 v5, v37, v48
	v_fmac_f32_e32 v6, v38, v48
	v_fmac_f32_e32 v8, v39, v48
	s_waitcnt lgkmcnt(8)
	v_fmac_f32_e32 v4, v40, v49
	v_fmac_f32_e32 v5, v41, v49
	v_fmac_f32_e32 v6, v42, v49
	v_fmac_f32_e32 v8, v43, v49
	s_waitcnt lgkmcnt(6)
	v_fmac_f32_e32 v4, v44, v50
	v_fmac_f32_e32 v5, v45, v50
	v_fmac_f32_e32 v6, v46, v50
	v_fmac_f32_e32 v8, v47, v50
	ds_read_b128 v[36:39], v3 offset:1488
	ds_read_b32 v48, v19 offset:23808
	ds_read_b128 v[40:43], v3 offset:1504
	ds_read_b32 v49, v19 offset:24064
	ds_read_b128 v[44:47], v3 offset:1520
	ds_read_b32 v50, v19 offset:24320
	s_waitcnt lgkmcnt(10)
	v_fmac_f32_e32 v4, v20, v32
	v_fmac_f32_e32 v5, v21, v32
	v_fmac_f32_e32 v6, v22, v32
	v_fmac_f32_e32 v8, v23, v32
	s_waitcnt lgkmcnt(8)
	v_fmac_f32_e32 v4, v24, v33
	v_fmac_f32_e32 v5, v25, v33
	v_fmac_f32_e32 v6, v26, v33
	v_fmac_f32_e32 v8, v27, v33
	s_waitcnt lgkmcnt(6)
	v_fmac_f32_e32 v4, v28, v34
	v_fmac_f32_e32 v5, v29, v34
	v_fmac_f32_e32 v6, v30, v34
	v_fmac_f32_e32 v8, v31, v34
	ds_read_b128 v[20:23], v3 offset:1536
	ds_read_b32 v32, v19 offset:24576
	ds_read_b128 v[24:27], v3 offset:1552
	ds_read_b32 v33, v19 offset:24832
	ds_read_b128 v[28:31], v3 offset:1568
	ds_read_b32 v34, v19 offset:25088
	s_waitcnt lgkmcnt(10)
	v_fmac_f32_e32 v4, v36, v48
	v_fmac_f32_e32 v5, v37, v48
	v_fmac_f32_e32 v6, v38, v48
	v_fmac_f32_e32 v8, v39, v48
	s_waitcnt lgkmcnt(8)
	v_fmac_f32_e32 v4, v40, v49
	v_fmac_f32_e32 v5, v41, v49
	v_fmac_f32_e32 v6, v42, v49
	v_fmac_f32_e32 v8, v43, v49
	s_waitcnt lgkmcnt(6)
	v_fmac_f32_e32 v4, v44, v50
	v_fmac_f32_e32 v5, v45, v50
	v_fmac_f32_e32 v6, v46, v50
	v_fmac_f32_e32 v8, v47, v50
	ds_read_b128 v[36:39], v3 offset:1584
	ds_read_b32 v48, v19 offset:25344
	ds_read_b128 v[40:43], v3 offset:1600
	ds_read_b32 v49, v19 offset:25600
	ds_read_b128 v[44:47], v3 offset:1616
	ds_read_b32 v50, v19 offset:25856
	s_waitcnt lgkmcnt(10)
	v_fmac_f32_e32 v4, v20, v32
	v_fmac_f32_e32 v5, v21, v32
	v_fmac_f32_e32 v6, v22, v32
	v_fmac_f32_e32 v8, v23, v32
	s_waitcnt lgkmcnt(8)
	v_fmac_f32_e32 v4, v24, v33
	v_fmac_f32_e32 v5, v25, v33
	v_fmac_f32_e32 v6, v26, v33
	v_fmac_f32_e32 v8, v27, v33
	s_waitcnt lgkmcnt(6)
	v_fmac_f32_e32 v4, v28, v34
	v_fmac_f32_e32 v5, v29, v34
	v_fmac_f32_e32 v6, v30, v34
	v_fmac_f32_e32 v8, v31, v34
	ds_read_b128 v[20:23], v3 offset:1632
	ds_read_b32 v32, v19 offset:26112
	ds_read_b128 v[24:27], v3 offset:1648
	ds_read_b32 v33, v19 offset:26368
	ds_read_b128 v[28:31], v3 offset:1664
	ds_read_b32 v34, v19 offset:26624
	s_waitcnt lgkmcnt(10)
	v_fmac_f32_e32 v4, v36, v48
	v_fmac_f32_e32 v5, v37, v48
	v_fmac_f32_e32 v6, v38, v48
	v_fmac_f32_e32 v8, v39, v48
	s_waitcnt lgkmcnt(8)
	v_fmac_f32_e32 v4, v40, v49
	v_fmac_f32_e32 v5, v41, v49
	v_fmac_f32_e32 v6, v42, v49
	v_fmac_f32_e32 v8, v43, v49
	s_waitcnt lgkmcnt(6)
	v_fmac_f32_e32 v4, v44, v50
	v_fmac_f32_e32 v5, v45, v50
	v_fmac_f32_e32 v6, v46, v50
	v_fmac_f32_e32 v8, v47, v50
	ds_read_b128 v[36:39], v3 offset:1680
	ds_read_b32 v48, v19 offset:26880
	ds_read_b128 v[40:43], v3 offset:1696
	ds_read_b32 v49, v19 offset:27136
	ds_read_b128 v[44:47], v3 offset:1712
	ds_read_b32 v50, v19 offset:27392
	s_waitcnt lgkmcnt(10)
	v_fmac_f32_e32 v4, v20, v32
	v_fmac_f32_e32 v5, v21, v32
	v_fmac_f32_e32 v6, v22, v32
	v_fmac_f32_e32 v8, v23, v32
	s_waitcnt lgkmcnt(8)
	v_fmac_f32_e32 v4, v24, v33
	v_fmac_f32_e32 v5, v25, v33
	v_fmac_f32_e32 v6, v26, v33
	v_fmac_f32_e32 v8, v27, v33
	s_waitcnt lgkmcnt(6)
	v_fmac_f32_e32 v4, v28, v34
	v_fmac_f32_e32 v5, v29, v34
	v_fmac_f32_e32 v6, v30, v34
	v_fmac_f32_e32 v8, v31, v34
	ds_read_b128 v[20:23], v3 offset:1728
	ds_read_b32 v32, v19 offset:27648
	ds_read_b128 v[24:27], v3 offset:1744
	ds_read_b32 v33, v19 offset:27904
	ds_read_b128 v[28:31], v3 offset:1760
	ds_read_b32 v34, v19 offset:28160
	s_waitcnt lgkmcnt(10)
	v_fmac_f32_e32 v4, v36, v48
	v_fmac_f32_e32 v5, v37, v48
	v_fmac_f32_e32 v6, v38, v48
	v_fmac_f32_e32 v8, v39, v48
	s_waitcnt lgkmcnt(8)
	v_fmac_f32_e32 v4, v40, v49
	v_fmac_f32_e32 v5, v41, v49
	v_fmac_f32_e32 v6, v42, v49
	v_fmac_f32_e32 v8, v43, v49
	s_waitcnt lgkmcnt(6)
	v_fmac_f32_e32 v4, v44, v50
	v_fmac_f32_e32 v5, v45, v50
	v_fmac_f32_e32 v6, v46, v50
	v_fmac_f32_e32 v8, v47, v50
	ds_read_b128 v[36:39], v3 offset:1776
	ds_read_b32 v48, v19 offset:28416
	ds_read_b128 v[40:43], v3 offset:1792
	ds_read_b32 v49, v19 offset:28672
	ds_read_b128 v[44:47], v3 offset:1808
	ds_read_b32 v50, v19 offset:28928
	s_waitcnt lgkmcnt(10)
	v_fmac_f32_e32 v4, v20, v32
	v_fmac_f32_e32 v5, v21, v32
	v_fmac_f32_e32 v6, v22, v32
	v_fmac_f32_e32 v8, v23, v32
	s_waitcnt lgkmcnt(8)
	v_fmac_f32_e32 v4, v24, v33
	v_fmac_f32_e32 v5, v25, v33
	v_fmac_f32_e32 v6, v26, v33
	v_fmac_f32_e32 v8, v27, v33
	s_waitcnt lgkmcnt(6)
	v_fmac_f32_e32 v4, v28, v34
	v_fmac_f32_e32 v5, v29, v34
	v_fmac_f32_e32 v6, v30, v34
	v_fmac_f32_e32 v8, v31, v34
	ds_read_b128 v[20:23], v3 offset:1824
	ds_read_b32 v32, v19 offset:29184
	ds_read_b128 v[24:27], v3 offset:1840
	ds_read_b32 v33, v19 offset:29440
	ds_read_b128 v[28:31], v3 offset:1856
	ds_read_b32 v34, v19 offset:29696
	s_waitcnt lgkmcnt(10)
	v_fmac_f32_e32 v4, v36, v48
	v_fmac_f32_e32 v5, v37, v48
	v_fmac_f32_e32 v6, v38, v48
	v_fmac_f32_e32 v8, v39, v48
	s_waitcnt lgkmcnt(8)
	v_fmac_f32_e32 v4, v40, v49
	v_fmac_f32_e32 v5, v41, v49
	v_fmac_f32_e32 v6, v42, v49
	v_fmac_f32_e32 v8, v43, v49
	s_waitcnt lgkmcnt(6)
	v_fmac_f32_e32 v4, v44, v50
	v_fmac_f32_e32 v5, v45, v50
	v_fmac_f32_e32 v6, v46, v50
	v_fmac_f32_e32 v8, v47, v50
	ds_read_b128 v[36:39], v3 offset:1872
	ds_read_b32 v48, v19 offset:29952
	ds_read_b128 v[40:43], v3 offset:1888
	ds_read_b32 v49, v19 offset:30208
	ds_read_b128 v[44:47], v3 offset:1904
	ds_read_b32 v50, v19 offset:30464
	s_waitcnt lgkmcnt(10)
	v_fmac_f32_e32 v4, v20, v32
	v_fmac_f32_e32 v5, v21, v32
	v_fmac_f32_e32 v6, v22, v32
	v_fmac_f32_e32 v8, v23, v32
	s_waitcnt lgkmcnt(8)
	v_fmac_f32_e32 v4, v24, v33
	v_fmac_f32_e32 v5, v25, v33
	v_fmac_f32_e32 v6, v26, v33
	v_fmac_f32_e32 v8, v27, v33
	s_waitcnt lgkmcnt(6)
	v_fmac_f32_e32 v4, v28, v34
	v_fmac_f32_e32 v5, v29, v34
	v_fmac_f32_e32 v6, v30, v34
	v_fmac_f32_e32 v8, v31, v34
	ds_read_b128 v[20:23], v3 offset:1920
	ds_read_b32 v32, v19 offset:30720
	ds_read_b128 v[24:27], v3 offset:1936
	ds_read_b32 v33, v19 offset:30976
	ds_read_b128 v[28:31], v3 offset:1952
	ds_read_b32 v34, v19 offset:31232
	s_waitcnt lgkmcnt(10)
	v_fmac_f32_e32 v4, v36, v48
	v_fmac_f32_e32 v5, v37, v48
	v_fmac_f32_e32 v6, v38, v48
	v_fmac_f32_e32 v8, v39, v48
	s_waitcnt lgkmcnt(8)
	v_fmac_f32_e32 v4, v40, v49
	v_fmac_f32_e32 v5, v41, v49
	v_fmac_f32_e32 v6, v42, v49
	v_fmac_f32_e32 v8, v43, v49
	s_waitcnt lgkmcnt(6)
	v_fmac_f32_e32 v4, v44, v50
	v_fmac_f32_e32 v5, v45, v50
	v_fmac_f32_e32 v6, v46, v50
	v_fmac_f32_e32 v8, v47, v50
	ds_read_b128 v[36:39], v3 offset:1968
	ds_read_b32 v48, v19 offset:31488
	ds_read_b128 v[40:43], v3 offset:1984
	ds_read_b32 v49, v19 offset:31744
	ds_read_b128 v[44:47], v3 offset:2000
	ds_read_b32 v50, v19 offset:32000
	s_waitcnt lgkmcnt(10)
	v_fmac_f32_e32 v4, v20, v32
	v_fmac_f32_e32 v5, v21, v32
	v_fmac_f32_e32 v6, v22, v32
	v_fmac_f32_e32 v8, v23, v32
	s_waitcnt lgkmcnt(8)
	v_fmac_f32_e32 v4, v24, v33
	v_fmac_f32_e32 v5, v25, v33
	v_fmac_f32_e32 v6, v26, v33
	v_fmac_f32_e32 v8, v27, v33
	s_waitcnt lgkmcnt(6)
	v_fmac_f32_e32 v4, v28, v34
	v_fmac_f32_e32 v5, v29, v34
	v_fmac_f32_e32 v6, v30, v34
	v_fmac_f32_e32 v8, v31, v34
	ds_read_b128 v[20:23], v3 offset:2016
	ds_read_b32 v32, v19 offset:32256
	ds_read_b128 v[24:27], v3 offset:2032
	ds_read_b32 v33, v19 offset:32512
	ds_read_b128 v[28:31], v3 offset:2048
	ds_read_b32 v34, v19 offset:32768
	s_waitcnt lgkmcnt(10)
	v_fmac_f32_e32 v4, v36, v48
	v_fmac_f32_e32 v5, v37, v48
	v_fmac_f32_e32 v6, v38, v48
	v_fmac_f32_e32 v8, v39, v48
	s_waitcnt lgkmcnt(8)
	v_fmac_f32_e32 v4, v40, v49
	v_fmac_f32_e32 v5, v41, v49
	v_fmac_f32_e32 v6, v42, v49
	v_fmac_f32_e32 v8, v43, v49
	s_waitcnt lgkmcnt(6)
	v_fmac_f32_e32 v4, v44, v50
	v_fmac_f32_e32 v5, v45, v50
	v_fmac_f32_e32 v6, v46, v50
	v_fmac_f32_e32 v8, v47, v50
	ds_read_b128 v[36:39], v3 offset:2064
	ds_read_b32 v48, v19 offset:33024
	ds_read_b128 v[40:43], v3 offset:2080
	ds_read_b32 v49, v19 offset:33280
	ds_read_b128 v[44:47], v3 offset:2096
	ds_read_b32 v50, v19 offset:33536
	s_waitcnt lgkmcnt(10)
	v_fmac_f32_e32 v4, v20, v32
	v_fmac_f32_e32 v5, v21, v32
	v_fmac_f32_e32 v6, v22, v32
	v_fmac_f32_e32 v8, v23, v32
	s_waitcnt lgkmcnt(8)
	v_fmac_f32_e32 v4, v24, v33
	v_fmac_f32_e32 v5, v25, v33
	v_fmac_f32_e32 v6, v26, v33
	v_fmac_f32_e32 v8, v27, v33
	s_waitcnt lgkmcnt(6)
	v_fmac_f32_e32 v4, v28, v34
	v_fmac_f32_e32 v5, v29, v34
	v_fmac_f32_e32 v6, v30, v34
	v_fmac_f32_e32 v8, v31, v34
	s_waitcnt lgkmcnt(4)
	v_fmac_f32_e32 v4, v36, v48
	v_fmac_f32_e32 v5, v37, v48
	v_fmac_f32_e32 v6, v38, v48
	v_fmac_f32_e32 v8, v39, v48
	s_waitcnt lgkmcnt(2)
	v_fmac_f32_e32 v4, v40, v49
	v_fmac_f32_e32 v5, v41, v49
	v_fmac_f32_e32 v6, v42, v49
	v_fmac_f32_e32 v8, v43, v49
	s_waitcnt lgkmcnt(0)
	v_fmac_f32_e32 v4, v44, v50
	v_fmac_f32_e32 v5, v45, v50
	v_fmac_f32_e32 v6, v46, v50
	v_fmac_f32_e32 v8, v47, v50
	s_add_u32 s42, s10, 0xd680000
	s_addc_u32 s43, s11, 0
	v_cvt_pk_bf16_f32 v4, v4, v4
	v_cvt_pk_bf16_f32 v5, v5, v5
	v_cvt_pk_bf16_f32 v6, v6, v6
	v_cvt_pk_bf16_f32 v8, v8, v8
	s_nop 0
	global_store_short v11, v4, s[42:43]
	global_store_short v11, v5, s[42:43] offset:2048
	global_store_short v12, v6, s[42:43]
	global_store_short v12, v8, s[42:43] offset:2048

.LBB0_238:
	s_waitcnt lgkmcnt(0)
	ds_read_b128 v[46:49], v120 offset:25856
	ds_read_b128 v[50:53], v120 offset:25920
	ds_read_b128 v[206:209], v120 offset:25984
	ds_read_b128 v[210:213], v120 offset:26048
	s_mov_b64 s[2:3], -1
	s_and_b64 vcc, exec, s[84:85]
	s_waitcnt lgkmcnt(3)
	v_mfma_f32_16x16x32_bf16 v[46:49], v[26:29], v[46:49], 0
	s_waitcnt lgkmcnt(2)
	v_mfma_f32_16x16x32_bf16 v[46:49], v[30:33], v[50:53], v[46:49]
	s_waitcnt lgkmcnt(1)
	v_mfma_f32_16x16x32_bf16 v[46:49], v[34:37], v[206:209], v[46:49]
	s_waitcnt lgkmcnt(0)
	v_mfma_f32_16x16x32_bf16 v[46:49], v[38:41], v[210:213], v[46:49]
	s_cbranch_vccz .LBB0_240
	v_lshl_add_u64 v[50:51], v[100:101], 0, v[104:105]
	v_add_co_u32_e32 v50, vcc, 0x9480000, v50
	s_mov_b64 s[2:3], 0
	s_nop 0
	v_addc_co_u32_e32 v51, vcc, 0, v51, vcc
	global_load_dwordx2 v[108:109], v[50:51], off
	s_nop 0
	global_load_dwordx4 v[50:53], v[90:91], off
	s_waitcnt vmcnt(1)
	v_lshlrev_b32_e32 v0, 16, v108
	s_waitcnt vmcnt(0)
	v_mul_f32_e32 v0, v50, v0
	v_and_b32_e32 v50, 0xffff0000, v108
	v_mul_f32_e32 v50, v51, v50
	v_cvt_pk_bf16_f32 v0, v0, v50
	v_lshlrev_b32_e32 v50, 16, v109
	v_and_b32_e32 v51, 0xffff0000, v109
	v_mul_f32_e32 v50, v52, v50
	v_mul_f32_e32 v51, v53, v51
	v_cvt_pk_bf16_f32 v53, v50, v51
	v_lshlrev_b32_e32 v50, 16, v0
	v_and_b32_e32 v51, 0xffff0000, v0
	v_lshlrev_b32_e32 v52, 16, v53
	v_and_b32_e32 v53, 0xffff0000, v53

.LBB0_269:
	s_waitcnt vmcnt(16)
	s_cmpk_gt_u32 s24, 0xff
	s_cbranch_scc1 .LBB0_271
	s_barrier

.LBB0_272:
	s_and_b64 vcc, exec, s[38:39]
	v_readfirstlane_b32 s0, v204
	s_cbranch_vccnz .LBB0_278
	s_ashr_i32 s22, s0, 6
	s_lshl_b32 s0, s22, 7
	s_ashr_i32 s1, s0, 31
	s_lshl_b64 s[0:1], s[0:1], 1
	s_add_u32 s2, s12, s0
	s_addc_u32 s3, s13, s1
	s_waitcnt vmcnt(16)
	v_bfe_u32 v2, v204, 4, 2
	s_add_u32 s0, s17, s0
	v_lshlrev_b32_e32 v0, 4, v2
	s_addc_u32 s1, s19, s1
	v_lshl_add_u64 v[38:39], s[2:3], 0, v[0:1]
	v_lshl_add_u64 v[40:41], s[0:1], 0, v[0:1]
	v_lshlrev_b32_e32 v0, 2, v2
	v_lshlrev_b32_e32 v4, 2, v204
	v_lshl_or_b32 v2, s22, 5, v0
	v_ashrrev_i32_e32 v0, 4, v204
	v_and_b32_e32 v44, 60, v4
	s_movk_i32 s2, 0x110
	v_lshl_add_u32 v3, v176, 2, 0
	v_lshl_add_u32 v4, v44, 2, 0
	s_cmp_lg_u64 s[28:29], 0
	v_mul_lo_u32 v2, v2, s2
	v_mul_lo_u32 v5, v0, s2
	s_cselect_b64 s[0:1], -1, 0
	s_lshl_b32 s2, s90, 6
	s_lshl_b32 s3, s92, 6
	v_add_u32_e32 v45, v3, v2
	v_add_u32_e32 v46, v4, v5
	s_mov_b32 s17, s90
	s_branch .LBB0_276

.LBB0_331:
	s_add_u32 s22, s24, 0x100
	s_addc_u32 s23, s25, 0
	s_add_i32 s52, 0, 0x10000
	v_add_u32_e32 v140, s52, v144
	ds_read_b128 v[164:167], v140
	ds_read_b128 v[168:171], v140 offset:1024
	ds_read_b128 v[172:175], v140 offset:2048
	ds_read_b128 v[176:179], v140 offset:3072
	s_cmp_eq_u32 s51, 40
	s_cselect_b32 s29, s3, s23
	s_cselect_b32 s28, s2, s22
	s_cselect_b32 s27, s1, s41
	s_cselect_b32 s26, s0, s40
	v_lshl_add_u64 v[140:141], s[24:25], 0, v[136:137]
	s_add_i32 m0, s35, 0xc000
	ds_read_b128 v[180:183], v162
	ds_read_b128 v[184:187], v162 offset:1024
	ds_read_b128 v[206:209], v162 offset:2048
	ds_read_b128 v[210:213], v162 offset:3072
	ds_read_b128 v[214:217], v162 offset:4096
	ds_read_b128 v[218:221], v162 offset:5120
	ds_read_b128 v[222:225], v162 offset:6144
	ds_read_b128 v[226:229], v162 offset:7168
	global_load_lds_dwordx4 v[140:141], off
	v_lshl_add_u64 v[140:141], s[24:25], 0, v[138:139]
	s_add_i32 m0, s35, 0xe000
	s_nop 0
	global_load_lds_dwordx4 v[140:141], off
	s_waitcnt lgkmcnt(8)
	s_barrier
	s_waitcnt lgkmcnt(0)
	s_setprio 1
	s_waitcnt lgkmcnt(0)
	v_mfma_f32_16x16x32_bf16 v[126:129], v[164:167], v[180:183], v[126:129]
	v_mfma_f32_16x16x32_bf16 v[122:125], v[172:175], v[180:183], v[122:125]
	v_mfma_f32_16x16x32_bf16 v[114:117], v[164:167], v[206:209], v[114:117]
	v_mfma_f32_16x16x32_bf16 v[106:109], v[172:175], v[206:209], v[106:109]
	v_mfma_f32_16x16x32_bf16 v[98:101], v[164:167], v[214:217], v[98:101]
	v_mfma_f32_16x16x32_bf16 v[90:93], v[172:175], v[214:217], v[90:93]
	v_mfma_f32_16x16x32_bf16 v[82:85], v[164:167], v[222:225], v[82:85]
	v_mfma_f32_16x16x32_bf16 v[74:77], v[172:175], v[222:225], v[74:77]
	v_mfma_f32_16x16x32_bf16 v[126:129], v[168:171], v[184:187], v[126:129]
	v_mfma_f32_16x16x32_bf16 v[122:125], v[176:179], v[184:187], v[122:125]
	v_mfma_f32_16x16x32_bf16 v[114:117], v[168:171], v[210:213], v[114:117]
	v_mfma_f32_16x16x32_bf16 v[106:109], v[176:179], v[210:213], v[106:109]
	v_mfma_f32_16x16x32_bf16 v[98:101], v[168:171], v[218:221], v[98:101]
	v_mfma_f32_16x16x32_bf16 v[90:93], v[176:179], v[218:221], v[90:93]
	v_mfma_f32_16x16x32_bf16 v[82:85], v[168:171], v[226:229], v[82:85]
	v_mfma_f32_16x16x32_bf16 v[74:77], v[176:179], v[226:229], v[74:77]
	s_setprio 0
	s_barrier
	s_add_i32 s53, 0, 0x14000
	v_add_u32_e32 v140, s53, v144
	s_add_i32 s24, s52, s31
	ds_read_b128 v[230:233], v140
	ds_read_b128 v[234:237], v140 offset:1024
	ds_read_b128 v[238:241], v140 offset:2048
	ds_read_b128 v[242:245], v140 offset:3072
	v_lshl_add_u64 v[140:141], s[26:27], 0, v[0:1]
	s_mov_b32 m0, s24
	v_lshl_add_u64 v[246:247], s[26:27], 0, v[130:131]
	global_load_lds_dwordx4 v[140:141], off
	s_add_i32 m0, s24, 0x2000
	s_nop 0
	global_load_lds_dwordx4 v[246:247], off
	s_barrier
	s_waitcnt lgkmcnt(0)
	s_setprio 1
	s_waitcnt lgkmcnt(0)
	v_mfma_f32_16x16x32_bf16 v[118:121], v[230:233], v[180:183], v[118:121]
	v_mfma_f32_16x16x32_bf16 v[110:113], v[238:241], v[180:183], v[110:113]
	v_mfma_f32_16x16x32_bf16 v[102:105], v[230:233], v[206:209], v[102:105]
	v_mfma_f32_16x16x32_bf16 v[94:97], v[238:241], v[206:209], v[94:97]
	v_mfma_f32_16x16x32_bf16 v[86:89], v[230:233], v[214:217], v[86:89]
	v_mfma_f32_16x16x32_bf16 v[78:81], v[238:241], v[214:217], v[78:81]
	v_mfma_f32_16x16x32_bf16 v[70:73], v[230:233], v[222:225], v[70:73]
	v_mfma_f32_16x16x32_bf16 v[66:69], v[238:241], v[222:225], v[66:69]
	v_mfma_f32_16x16x32_bf16 v[118:121], v[234:237], v[184:187], v[118:121]
	v_mfma_f32_16x16x32_bf16 v[110:113], v[242:245], v[184:187], v[110:113]
	v_mfma_f32_16x16x32_bf16 v[102:105], v[234:237], v[210:213], v[102:105]
	v_mfma_f32_16x16x32_bf16 v[94:97], v[242:245], v[210:213], v[94:97]
	v_mfma_f32_16x16x32_bf16 v[86:89], v[234:237], v[218:221], v[86:89]
	v_mfma_f32_16x16x32_bf16 v[78:81], v[242:245], v[218:221], v[78:81]
	v_mfma_f32_16x16x32_bf16 v[70:73], v[234:237], v[226:229], v[70:73]
	v_mfma_f32_16x16x32_bf16 v[66:69], v[242:245], v[226:229], v[66:69]
	s_setprio 0
	s_mov_b32 m0, s35
	v_lshl_add_u64 v[248:249], s[28:29], 0, v[134:135]
	s_barrier
	ds_read_b128 v[180:183], v162 offset:16384
	ds_read_b128 v[184:187], v162 offset:17408
	ds_read_b128 v[206:209], v162 offset:18432
	ds_read_b128 v[210:213], v162 offset:19456
	ds_read_b128 v[214:217], v162 offset:20480
	ds_read_b128 v[218:221], v162 offset:21504
	ds_read_b128 v[222:225], v162 offset:22528
	ds_read_b128 v[226:229], v162 offset:23552
	global_load_lds_dwordx4 v[248:249], off
	v_lshl_add_u64 v[250:251], s[28:29], 0, v[132:133]
	s_mov_b32 m0, s36
	s_nop 0
	global_load_lds_dwordx4 v[250:251], off
	s_barrier
	s_waitcnt lgkmcnt(0)
	s_setprio 1
	s_waitcnt lgkmcnt(0)
	v_mfma_f32_16x16x32_bf16 v[62:65], v[164:167], v[180:183], v[62:65]
	v_mfma_f32_16x16x32_bf16 v[58:61], v[172:175], v[180:183], v[58:61]
	v_mfma_f32_16x16x32_bf16 v[50:53], v[164:167], v[206:209], v[50:53]
	v_mfma_f32_16x16x32_bf16 v[42:45], v[172:175], v[206:209], v[42:45]
	v_mfma_f32_16x16x32_bf16 v[34:37], v[164:167], v[214:217], v[34:37]
	v_mfma_f32_16x16x32_bf16 v[26:29], v[172:175], v[214:217], v[26:29]
	v_mfma_f32_16x16x32_bf16 v[18:21], v[164:167], v[222:225], v[18:21]
	v_mfma_f32_16x16x32_bf16 v[10:13], v[172:175], v[222:225], v[10:13]
	v_mfma_f32_16x16x32_bf16 v[62:65], v[168:171], v[184:187], v[62:65]
	v_mfma_f32_16x16x32_bf16 v[58:61], v[176:179], v[184:187], v[58:61]
	v_mfma_f32_16x16x32_bf16 v[50:53], v[168:171], v[210:213], v[50:53]
	v_mfma_f32_16x16x32_bf16 v[42:45], v[176:179], v[210:213], v[42:45]
	v_mfma_f32_16x16x32_bf16 v[34:37], v[168:171], v[218:221], v[34:37]
	v_mfma_f32_16x16x32_bf16 v[26:29], v[176:179], v[218:221], v[26:29]
	v_mfma_f32_16x16x32_bf16 v[18:21], v[168:171], v[226:229], v[18:21]
	v_mfma_f32_16x16x32_bf16 v[10:13], v[176:179], v[226:229], v[10:13]
	s_setprio 0
	s_barrier
	s_add_u32 s24, s26, 0xb0000
	s_addc_u32 s25, s27, 0
	s_add_i32 s52, s53, s31
	v_lshl_add_u64 v[164:165], s[24:25], 0, v[0:1]
	s_mov_b32 m0, s52
	s_nop 0
	global_load_lds_dwordx4 v[164:165], off
	v_lshl_add_u64 v[164:165], s[24:25], 0, v[130:131]
	s_add_i32 m0, s52, 0x2000
	s_nop 0
	global_load_lds_dwordx4 v[164:165], off
	s_waitcnt vmcnt(6)
	s_barrier
	s_setprio 1
	v_mfma_f32_16x16x32_bf16 v[54:57], v[230:233], v[180:183], v[54:57]
	v_mfma_f32_16x16x32_bf16 v[46:49], v[238:241], v[180:183], v[46:49]
	v_mfma_f32_16x16x32_bf16 v[38:41], v[230:233], v[206:209], v[38:41]
	v_mfma_f32_16x16x32_bf16 v[30:33], v[238:241], v[206:209], v[30:33]
	v_mfma_f32_16x16x32_bf16 v[22:25], v[230:233], v[214:217], v[22:25]
	v_mfma_f32_16x16x32_bf16 v[14:17], v[238:241], v[214:217], v[14:17]
	v_mfma_f32_16x16x32_bf16 v[6:9], v[230:233], v[222:225], v[6:9]
	v_mfma_f32_16x16x32_bf16 v[2:5], v[238:241], v[222:225], v[2:5]
	v_mfma_f32_16x16x32_bf16 v[54:57], v[234:237], v[184:187], v[54:57]
	v_mfma_f32_16x16x32_bf16 v[46:49], v[242:245], v[184:187], v[46:49]
	v_mfma_f32_16x16x32_bf16 v[38:41], v[234:237], v[210:213], v[38:41]
	v_mfma_f32_16x16x32_bf16 v[30:33], v[242:245], v[210:213], v[30:33]
	v_mfma_f32_16x16x32_bf16 v[22:25], v[234:237], v[218:221], v[22:25]
	v_mfma_f32_16x16x32_bf16 v[14:17], v[242:245], v[218:221], v[14:17]
	v_mfma_f32_16x16x32_bf16 v[6:9], v[234:237], v[226:229], v[6:9]
	v_mfma_f32_16x16x32_bf16 v[2:5], v[242:245], v[226:229], v[2:5]
	s_setprio 0
	s_add_i32 s52, 0, 0x18000
	v_add_u32_e32 v163, s52, v144
	s_barrier
	ds_read_b128 v[164:167], v163
	ds_read_b128 v[168:171], v163 offset:1024
	ds_read_b128 v[172:175], v163 offset:2048
	ds_read_b128 v[176:179], v163 offset:3072
	s_add_u32 s24, s28, 0xb0000
	s_addc_u32 s25, s29, 0
	s_mov_b32 m0, s37
	v_lshl_add_u64 v[230:231], s[24:25], 0, v[134:135]
	ds_read_b128 v[180:183], v162 offset:32768
	ds_read_b128 v[184:187], v162 offset:33792
	ds_read_b128 v[206:209], v162 offset:34816
	ds_read_b128 v[210:213], v162 offset:35840
	ds_read_b128 v[214:217], v162 offset:36864
	ds_read_b128 v[218:221], v162 offset:37888
	ds_read_b128 v[222:225], v162 offset:38912
	ds_read_b128 v[226:229], v162 offset:39936
	global_load_lds_dwordx4 v[230:231], off
	v_lshl_add_u64 v[230:231], s[24:25], 0, v[132:133]
	s_mov_b32 m0, s42
	s_nop 0
	global_load_lds_dwordx4 v[230:231], off
	s_waitcnt lgkmcnt(8)
	s_barrier
	s_waitcnt lgkmcnt(0)
	s_setprio 1
	s_waitcnt lgkmcnt(0)
	v_mfma_f32_16x16x32_bf16 v[126:129], v[164:167], v[180:183], v[126:129]
	v_mfma_f32_16x16x32_bf16 v[122:125], v[172:175], v[180:183], v[122:125]
	v_mfma_f32_16x16x32_bf16 v[114:117], v[164:167], v[206:209], v[114:117]
	v_mfma_f32_16x16x32_bf16 v[106:109], v[172:175], v[206:209], v[106:109]
	v_mfma_f32_16x16x32_bf16 v[98:101], v[164:167], v[214:217], v[98:101]
	v_mfma_f32_16x16x32_bf16 v[90:93], v[172:175], v[214:217], v[90:93]
	v_mfma_f32_16x16x32_bf16 v[82:85], v[164:167], v[222:225], v[82:85]
	v_mfma_f32_16x16x32_bf16 v[74:77], v[172:175], v[222:225], v[74:77]
	v_mfma_f32_16x16x32_bf16 v[126:129], v[168:171], v[184:187], v[126:129]
	v_mfma_f32_16x16x32_bf16 v[122:125], v[176:179], v[184:187], v[122:125]
	v_mfma_f32_16x16x32_bf16 v[114:117], v[168:171], v[210:213], v[114:117]
	v_mfma_f32_16x16x32_bf16 v[106:109], v[176:179], v[210:213], v[106:109]
	v_mfma_f32_16x16x32_bf16 v[98:101], v[168:171], v[218:221], v[98:101]
	v_mfma_f32_16x16x32_bf16 v[90:93], v[176:179], v[218:221], v[90:93]
	v_mfma_f32_16x16x32_bf16 v[82:85], v[168:171], v[226:229], v[82:85]
	v_mfma_f32_16x16x32_bf16 v[74:77], v[176:179], v[226:229], v[74:77]
	s_setprio 0
	s_barrier
	s_add_i32 s28, 0, 0x1c000
	s_add_i32 s24, s52, s31
	v_add_u32_e32 v163, s28, v144
	v_lshl_add_u64 v[140:141], v[140:141], 0, s[94:95]
	s_mov_b32 m0, s24
	ds_read_b128 v[230:233], v163
	ds_read_b128 v[234:237], v163 offset:1024
	ds_read_b128 v[238:241], v163 offset:2048
	ds_read_b128 v[242:245], v163 offset:3072
	global_load_lds_dwordx4 v[140:141], off
	v_lshl_add_u64 v[140:141], v[246:247], 0, s[94:95]
	s_add_i32 m0, s24, 0x2000
	s_nop 0
	global_load_lds_dwordx4 v[140:141], off
	s_barrier
	s_waitcnt lgkmcnt(0)
	s_setprio 1
	s_waitcnt lgkmcnt(0)
	v_mfma_f32_16x16x32_bf16 v[118:121], v[230:233], v[180:183], v[118:121]
	v_mfma_f32_16x16x32_bf16 v[110:113], v[238:241], v[180:183], v[110:113]
	v_mfma_f32_16x16x32_bf16 v[102:105], v[230:233], v[206:209], v[102:105]
	v_mfma_f32_16x16x32_bf16 v[94:97], v[238:241], v[206:209], v[94:97]
	v_mfma_f32_16x16x32_bf16 v[86:89], v[230:233], v[214:217], v[86:89]
	v_mfma_f32_16x16x32_bf16 v[78:81], v[238:241], v[214:217], v[78:81]
	v_mfma_f32_16x16x32_bf16 v[70:73], v[230:233], v[222:225], v[70:73]
	v_mfma_f32_16x16x32_bf16 v[66:69], v[238:241], v[222:225], v[66:69]
	v_mfma_f32_16x16x32_bf16 v[118:121], v[234:237], v[184:187], v[118:121]
	v_mfma_f32_16x16x32_bf16 v[110:113], v[242:245], v[184:187], v[110:113]
	v_mfma_f32_16x16x32_bf16 v[102:105], v[234:237], v[210:213], v[102:105]
	v_mfma_f32_16x16x32_bf16 v[94:97], v[242:245], v[210:213], v[94:97]
	v_mfma_f32_16x16x32_bf16 v[86:89], v[234:237], v[218:221], v[86:89]
	v_mfma_f32_16x16x32_bf16 v[78:81], v[242:245], v[218:221], v[78:81]
	v_mfma_f32_16x16x32_bf16 v[70:73], v[234:237], v[226:229], v[70:73]
	v_mfma_f32_16x16x32_bf16 v[66:69], v[242:245], v[226:229], v[66:69]
	s_setprio 0
	s_mov_b32 m0, s44
	v_lshl_add_u64 v[140:141], v[248:249], 0, s[94:95]
	s_barrier
	ds_read_b128 v[180:183], v162 offset:49152
	ds_read_b128 v[184:187], v162 offset:50176
	ds_read_b128 v[206:209], v162 offset:51200
	ds_read_b128 v[210:213], v162 offset:52224
	ds_read_b128 v[214:217], v162 offset:53248
	ds_read_b128 v[218:221], v162 offset:54272
	ds_read_b128 v[222:225], v162 offset:55296
	ds_read_b128 v[226:229], v162 offset:56320
	global_load_lds_dwordx4 v[140:141], off
	v_lshl_add_u64 v[140:141], v[250:251], 0, s[94:95]
	s_mov_b32 m0, s45
	s_nop 0
	global_load_lds_dwordx4 v[140:141], off
	s_barrier
	s_waitcnt lgkmcnt(0)
	s_setprio 1
	s_waitcnt lgkmcnt(0)
	v_mfma_f32_16x16x32_bf16 v[62:65], v[164:167], v[180:183], v[62:65]
	v_mfma_f32_16x16x32_bf16 v[58:61], v[172:175], v[180:183], v[58:61]
	v_mfma_f32_16x16x32_bf16 v[50:53], v[164:167], v[206:209], v[50:53]
	v_mfma_f32_16x16x32_bf16 v[42:45], v[172:175], v[206:209], v[42:45]
	v_mfma_f32_16x16x32_bf16 v[34:37], v[164:167], v[214:217], v[34:37]
	v_mfma_f32_16x16x32_bf16 v[26:29], v[172:175], v[214:217], v[26:29]
	v_mfma_f32_16x16x32_bf16 v[18:21], v[164:167], v[222:225], v[18:21]
	v_mfma_f32_16x16x32_bf16 v[10:13], v[172:175], v[222:225], v[10:13]
	v_mfma_f32_16x16x32_bf16 v[62:65], v[168:171], v[184:187], v[62:65]
	v_mfma_f32_16x16x32_bf16 v[58:61], v[176:179], v[184:187], v[58:61]
	v_mfma_f32_16x16x32_bf16 v[50:53], v[168:171], v[210:213], v[50:53]
	v_mfma_f32_16x16x32_bf16 v[42:45], v[176:179], v[210:213], v[42:45]
	v_mfma_f32_16x16x32_bf16 v[34:37], v[168:171], v[218:221], v[34:37]
	v_mfma_f32_16x16x32_bf16 v[26:29], v[176:179], v[218:221], v[26:29]
	v_mfma_f32_16x16x32_bf16 v[18:21], v[168:171], v[226:229], v[18:21]
	v_mfma_f32_16x16x32_bf16 v[10:13], v[176:179], v[226:229], v[10:13]
	s_setprio 0
	s_barrier
	s_add_u32 s24, s26, 0xb0080
	s_addc_u32 s25, s27, 0
	s_add_i32 s26, s28, s31
	v_lshl_add_u64 v[140:141], s[24:25], 0, v[0:1]
	s_mov_b32 m0, s26
	s_nop 0
	global_load_lds_dwordx4 v[140:141], off
	v_lshl_add_u64 v[140:141], s[24:25], 0, v[130:131]
	s_add_i32 m0, s26, 0x2000
	s_nop 0
	global_load_lds_dwordx4 v[140:141], off
	s_waitcnt vmcnt(6)
	s_barrier
	s_setprio 1
	v_mfma_f32_16x16x32_bf16 v[54:57], v[230:233], v[180:183], v[54:57]
	v_mfma_f32_16x16x32_bf16 v[46:49], v[238:241], v[180:183], v[46:49]
	v_mfma_f32_16x16x32_bf16 v[38:41], v[230:233], v[206:209], v[38:41]
	v_mfma_f32_16x16x32_bf16 v[30:33], v[238:241], v[206:209], v[30:33]
	v_mfma_f32_16x16x32_bf16 v[22:25], v[230:233], v[214:217], v[22:25]
	v_mfma_f32_16x16x32_bf16 v[14:17], v[238:241], v[214:217], v[14:17]
	v_mfma_f32_16x16x32_bf16 v[6:9], v[230:233], v[222:225], v[6:9]
	v_mfma_f32_16x16x32_bf16 v[2:5], v[238:241], v[222:225], v[2:5]
	v_mfma_f32_16x16x32_bf16 v[54:57], v[234:237], v[184:187], v[54:57]
	v_mfma_f32_16x16x32_bf16 v[46:49], v[242:245], v[184:187], v[46:49]
	v_mfma_f32_16x16x32_bf16 v[38:41], v[234:237], v[210:213], v[38:41]
	v_mfma_f32_16x16x32_bf16 v[30:33], v[242:245], v[210:213], v[30:33]
	v_mfma_f32_16x16x32_bf16 v[22:25], v[234:237], v[218:221], v[22:25]
	v_mfma_f32_16x16x32_bf16 v[14:17], v[242:245], v[218:221], v[14:17]
	v_mfma_f32_16x16x32_bf16 v[6:9], v[234:237], v[226:229], v[6:9]
	v_mfma_f32_16x16x32_bf16 v[2:5], v[242:245], v[226:229], v[2:5]
	s_setprio 0
	s_add_i32 s51, s51, 2
	s_add_u32 s40, s40, 0x100
	s_addc_u32 s41, s41, 0
	s_cmp_gt_u32 s51, 41
	s_mov_b64 s[24:25], s[22:23]
	s_barrier
	s_cbranch_scc0 .LBB0_331
	v_lshl_or_b32 v140, s50, 8, v145
	v_lshl_add_u32 v164, s49, 8, v143
	v_ashrrev_i32_e32 v141, 31, v140
	v_ashrrev_i32_e32 v165, 31, v164
	v_lshl_add_u64 v[166:167], v[140:141], 1, s[20:21]
	v_lshlrev_b64 v[140:141], 11, v[164:165]
	v_lshl_add_u64 v[140:141], v[166:167], 0, v[140:141]
	v_pk_add_f32 v[128:129], v[128:129], 0 op_sel_hi:[1,0]
	v_pk_add_f32 v[126:127], v[126:127], 0 op_sel_hi:[1,0]
	v_pk_add_f32 v[168:169], v[124:125], 0 op_sel_hi:[1,0]
	v_pk_add_f32 v[124:125], v[122:123], 0 op_sel_hi:[1,0]
	v_cvt_pk_bf16_f32 v122, v126, v127
	v_cvt_pk_bf16_f32 v123, v128, v129
	v_pk_add_f32 v[118:119], v[118:119], 0 op_sel_hi:[1,0]
	v_cvt_pk_bf16_f32 v124, v124, v125
	v_cvt_pk_bf16_f32 v125, v168, v169
	global_store_dwordx4 v[140:141], v[122:125], off
	v_pk_add_f32 v[120:121], v[120:121], 0 op_sel_hi:[1,0]
	v_pk_add_f32 v[114:115], v[114:115], 0 op_sel_hi:[1,0]
	v_pk_add_f32 v[122:123], v[112:113], 0 op_sel_hi:[1,0]
	v_pk_add_f32 v[112:113], v[110:111], 0 op_sel_hi:[1,0]
	v_cvt_pk_bf16_f32 v110, v118, v119
	v_cvt_pk_bf16_f32 v111, v120, v121
	v_pk_add_f32 v[102:103], v[102:103], 0 op_sel_hi:[1,0]
	v_cvt_pk_bf16_f32 v112, v112, v113
	v_cvt_pk_bf16_f32 v113, v122, v123
	global_store_dwordx4 v[140:141], v[110:113], off offset:256
	v_pk_add_f32 v[104:105], v[104:105], 0 op_sel_hi:[1,0]
	v_pk_add_f32 v[98:99], v[98:99], 0 op_sel_hi:[1,0]
	v_or_b32_e32 v110, 16, v164
	v_ashrrev_i32_e32 v111, 31, v110
	v_lshlrev_b64 v[110:111], 11, v[110:111]
	v_lshl_add_u64 v[110:111], v[166:167], 0, v[110:111]
	v_pk_add_f32 v[112:113], v[116:117], 0 op_sel_hi:[1,0]
	v_pk_add_f32 v[116:117], v[108:109], 0 op_sel_hi:[1,0]
	v_pk_add_f32 v[108:109], v[106:107], 0 op_sel_hi:[1,0]
	v_cvt_pk_bf16_f32 v106, v114, v115
	v_cvt_pk_bf16_f32 v107, v112, v113
	v_pk_add_f32 v[86:87], v[86:87], 0 op_sel_hi:[1,0]
	v_cvt_pk_bf16_f32 v108, v108, v109
	v_cvt_pk_bf16_f32 v109, v116, v117
	global_store_dwordx4 v[110:111], v[106:109], off
	v_pk_add_f32 v[88:89], v[88:89], 0 op_sel_hi:[1,0]
	v_pk_add_f32 v[82:83], v[82:83], 0 op_sel_hi:[1,0]
	v_pk_add_f32 v[106:107], v[96:97], 0 op_sel_hi:[1,0]
	v_pk_add_f32 v[96:97], v[94:95], 0 op_sel_hi:[1,0]
	v_cvt_pk_bf16_f32 v94, v102, v103
	v_cvt_pk_bf16_f32 v95, v104, v105
	v_pk_add_f32 v[72:73], v[72:73], 0 op_sel_hi:[1,0]
	v_cvt_pk_bf16_f32 v96, v96, v97
	v_cvt_pk_bf16_f32 v97, v106, v107
	global_store_dwordx4 v[110:111], v[94:97], off offset:256
	v_pk_add_f32 v[70:71], v[70:71], 0 op_sel_hi:[1,0]
	v_pk_add_f32 v[62:63], v[62:63], 0 op_sel_hi:[1,0]
	v_or_b32_e32 v94, 32, v164
	v_ashrrev_i32_e32 v95, 31, v94
	v_lshlrev_b64 v[94:95], 11, v[94:95]
	v_lshl_add_u64 v[94:95], v[166:167], 0, v[94:95]
	v_pk_add_f32 v[96:97], v[100:101], 0 op_sel_hi:[1,0]
	v_pk_add_f32 v[100:101], v[92:93], 0 op_sel_hi:[1,0]
	v_pk_add_f32 v[92:93], v[90:91], 0 op_sel_hi:[1,0]
	v_cvt_pk_bf16_f32 v90, v98, v99
	v_cvt_pk_bf16_f32 v91, v96, v97
	v_pk_add_f32 v[64:65], v[64:65], 0 op_sel_hi:[1,0]
	v_cvt_pk_bf16_f32 v92, v92, v93
	v_cvt_pk_bf16_f32 v93, v100, v101
	global_store_dwordx4 v[94:95], v[90:93], off
	s_mov_b64 s[22:23], 0x40000
	v_pk_add_f32 v[56:57], v[56:57], 0 op_sel_hi:[1,0]
	v_pk_add_f32 v[90:91], v[80:81], 0 op_sel_hi:[1,0]
	v_pk_add_f32 v[80:81], v[78:79], 0 op_sel_hi:[1,0]
	v_cvt_pk_bf16_f32 v78, v86, v87
	v_cvt_pk_bf16_f32 v79, v88, v89
	v_pk_add_f32 v[54:55], v[54:55], 0 op_sel_hi:[1,0]
	v_cvt_pk_bf16_f32 v80, v80, v81
	v_cvt_pk_bf16_f32 v81, v90, v91
	global_store_dwordx4 v[94:95], v[78:81], off offset:256
	v_pk_add_f32 v[50:51], v[50:51], 0 op_sel_hi:[1,0]
	v_pk_add_f32 v[40:41], v[40:41], 0 op_sel_hi:[1,0]
	v_or_b32_e32 v78, 48, v164
	v_ashrrev_i32_e32 v79, 31, v78
	v_lshlrev_b64 v[78:79], 11, v[78:79]
	v_lshl_add_u64 v[78:79], v[166:167], 0, v[78:79]
	v_pk_add_f32 v[80:81], v[84:85], 0 op_sel_hi:[1,0]
	v_pk_add_f32 v[84:85], v[76:77], 0 op_sel_hi:[1,0]
	v_pk_add_f32 v[76:77], v[74:75], 0 op_sel_hi:[1,0]
	v_cvt_pk_bf16_f32 v74, v82, v83
	v_cvt_pk_bf16_f32 v75, v80, v81
	v_pk_add_f32 v[38:39], v[38:39], 0 op_sel_hi:[1,0]
	v_cvt_pk_bf16_f32 v76, v76, v77
	v_cvt_pk_bf16_f32 v77, v84, v85
	global_store_dwordx4 v[78:79], v[74:77], off
	v_pk_add_f32 v[34:35], v[34:35], 0 op_sel_hi:[1,0]
	v_pk_add_f32 v[24:25], v[24:25], 0 op_sel_hi:[1,0]
	v_pk_add_f32 v[74:75], v[68:69], 0 op_sel_hi:[1,0]
	v_pk_add_f32 v[68:69], v[66:67], 0 op_sel_hi:[1,0]
	v_cvt_pk_bf16_f32 v66, v70, v71
	v_cvt_pk_bf16_f32 v67, v72, v73
	v_pk_add_f32 v[22:23], v[22:23], 0 op_sel_hi:[1,0]
	v_cvt_pk_bf16_f32 v68, v68, v69
	v_cvt_pk_bf16_f32 v69, v74, v75
	global_store_dwordx4 v[78:79], v[66:69], off offset:256
	v_pk_add_f32 v[18:19], v[18:19], 0 op_sel_hi:[1,0]
	s_mov_b32 s50, s47
	v_pk_add_f32 v[68:69], v[60:61], 0 op_sel_hi:[1,0]
	v_pk_add_f32 v[60:61], v[58:59], 0 op_sel_hi:[1,0]
	v_cvt_pk_bf16_f32 v58, v62, v63
	v_add_co_u32_e32 v62, vcc, s67, v140
	v_cvt_pk_bf16_f32 v59, v64, v65
	v_cvt_pk_bf16_f32 v60, v60, v61
	v_cvt_pk_bf16_f32 v61, v68, v69
	v_lshl_add_u64 v[66:67], v[140:141], 0, s[22:23]
	s_nop 0
	v_addc_co_u32_e32 v63, vcc, 0, v141, vcc
	global_store_dwordx4 v[62:63], v[58:61], off
	s_mov_b64 s[22:23], 0x48000
	s_mov_b32 s49, s48
	v_pk_add_f32 v[58:59], v[48:49], 0 op_sel_hi:[1,0]
	v_pk_add_f32 v[48:49], v[46:47], 0 op_sel_hi:[1,0]
	v_cvt_pk_bf16_f32 v46, v54, v55
	v_cvt_pk_bf16_f32 v47, v56, v57
	s_mov_b64 s[24:25], s[2:3]
	v_cvt_pk_bf16_f32 v48, v48, v49
	v_cvt_pk_bf16_f32 v49, v58, v59
	global_store_dwordx4 v[66:67], v[46:49], off offset:256
	v_pk_add_f32 v[8:9], v[8:9], 0 op_sel_hi:[1,0]
	v_pk_add_f32 v[6:7], v[6:7], 0 op_sel_hi:[1,0]
	v_pk_add_f32 v[48:49], v[52:53], 0 op_sel_hi:[1,0]
	v_pk_add_f32 v[52:53], v[44:45], 0 op_sel_hi:[1,0]
	v_pk_add_f32 v[44:45], v[42:43], 0 op_sel_hi:[1,0]
	v_cvt_pk_bf16_f32 v42, v50, v51
	v_cvt_pk_bf16_f32 v43, v48, v49
	v_add_co_u32_e32 v48, vcc, s68, v140
	v_cvt_pk_bf16_f32 v44, v44, v45
	v_cvt_pk_bf16_f32 v45, v52, v53
	v_lshl_add_u64 v[46:47], v[140:141], 0, s[22:23]
	s_nop 0
	v_addc_co_u32_e32 v49, vcc, 0, v141, vcc
	global_store_dwordx4 v[48:49], v[42:45], off
	s_mov_b64 s[22:23], 0x50000
	s_nop 0
	v_pk_add_f32 v[42:43], v[32:33], 0 op_sel_hi:[1,0]
	v_pk_add_f32 v[32:33], v[30:31], 0 op_sel_hi:[1,0]
	v_cvt_pk_bf16_f32 v30, v38, v39
	v_cvt_pk_bf16_f32 v31, v40, v41
	s_nop 0
	v_cvt_pk_bf16_f32 v32, v32, v33
	v_cvt_pk_bf16_f32 v33, v42, v43
	global_store_dwordx4 v[46:47], v[30:33], off offset:256
	s_nop 1
	v_lshl_add_u64 v[30:31], v[140:141], 0, s[22:23]
	v_pk_add_f32 v[32:33], v[36:37], 0 op_sel_hi:[1,0]
	s_mov_b32 s22, 0x50000
	v_pk_add_f32 v[36:37], v[28:29], 0 op_sel_hi:[1,0]
	v_pk_add_f32 v[28:29], v[26:27], 0 op_sel_hi:[1,0]
	v_cvt_pk_bf16_f32 v26, v34, v35
	v_cvt_pk_bf16_f32 v27, v32, v33
	v_add_co_u32_e32 v32, vcc, s22, v140
	v_cvt_pk_bf16_f32 v28, v28, v29
	v_cvt_pk_bf16_f32 v29, v36, v37
	s_mov_b64 s[22:23], 0x58000
	s_nop 0
	v_addc_co_u32_e32 v33, vcc, 0, v141, vcc
	global_store_dwordx4 v[32:33], v[26:29], off
	s_nop 1
	v_pk_add_f32 v[26:27], v[16:17], 0 op_sel_hi:[1,0]
	v_pk_add_f32 v[16:17], v[14:15], 0 op_sel_hi:[1,0]
	v_cvt_pk_bf16_f32 v14, v22, v23
	v_cvt_pk_bf16_f32 v15, v24, v25
	s_nop 0
	v_cvt_pk_bf16_f32 v16, v16, v17
	v_cvt_pk_bf16_f32 v17, v26, v27
	global_store_dwordx4 v[30:31], v[14:17], off offset:256
	s_nop 1
	v_lshl_add_u64 v[14:15], v[140:141], 0, s[22:23]
	v_pk_add_f32 v[16:17], v[20:21], 0 op_sel_hi:[1,0]
	s_mov_b32 s22, 0x58000
	v_pk_add_f32 v[20:21], v[12:13], 0 op_sel_hi:[1,0]
	v_pk_add_f32 v[12:13], v[10:11], 0 op_sel_hi:[1,0]
	v_cvt_pk_bf16_f32 v10, v18, v19
	v_cvt_pk_bf16_f32 v11, v16, v17
	v_add_co_u32_e32 v16, vcc, s22, v140
	v_cvt_pk_bf16_f32 v12, v12, v13
	v_cvt_pk_bf16_f32 v13, v20, v21
	s_mov_b64 s[22:23], s[0:1]
	s_nop 0
	v_addc_co_u32_e32 v17, vcc, 0, v141, vcc
	global_store_dwordx4 v[16:17], v[10:13], off
	s_and_b64 vcc, exec, s[38:39]
	s_nop 0
	v_pk_add_f32 v[10:11], v[4:5], 0 op_sel_hi:[1,0]
	v_pk_add_f32 v[4:5], v[2:3], 0 op_sel_hi:[1,0]
	v_cvt_pk_bf16_f32 v2, v6, v7
	v_cvt_pk_bf16_f32 v3, v8, v9
	s_nop 0
	v_cvt_pk_bf16_f32 v4, v4, v5
	v_cvt_pk_bf16_f32 v5, v10, v11
	global_store_dwordx4 v[14:15], v[2:5], off offset:256
	s_cbranch_vccz .LBB0_320
	s_waitcnt vmcnt(16)
	s_cmpk_gt_u32 s30, 0xff
	s_cbranch_scc1 .LBB0_335
	s_barrier

.LBB0_336:
	s_andn2_b64 vcc, exec, s[8:9]
	v_readfirstlane_b32 s0, v204
	s_cbranch_vccnz .LBB0_339
	s_ashr_i32 s8, s0, 6
	s_mul_i32 s0, s8, 0x160
	s_ashr_i32 s1, s0, 31
	s_lshl_b64 s[0:1], s[0:1], 1
	s_add_u32 s2, s14, s0
	s_addc_u32 s3, s15, s1
	s_waitcnt vmcnt(16)
	v_bfe_u32 v2, v204, 4, 2
	s_add_u32 s0, s17, s0
	v_lshlrev_b32_e32 v0, 4, v2
	s_addc_u32 s1, s19, s1
	v_lshl_add_u64 v[58:59], s[2:3], 0, v[0:1]
	v_lshl_add_u64 v[60:61], s[0:1], 0, v[0:1]
	v_lshlrev_b32_e32 v0, 2, v2
	v_lshl_or_b32 v2, s8, 5, v0
	v_ashrrev_i32_e32 v0, 4, v204
	v_lshlrev_b32_e32 v4, 2, v204
	s_movk_i32 s0, 0x110
	v_and_b32_e32 v4, 60, v4
	v_mul_lo_u32 v2, v2, s0
	v_mul_lo_u32 v6, v0, s0
	s_mul_i32 s0, s90, 0x2c000
	v_lshl_add_u32 v3, v142, 2, 0
	v_lshl_add_u32 v5, v4, 2, 0
	v_lshl_or_b32 v66, s90, 6, v4
	v_mov_b32_e32 v4, s0
	s_movk_i32 s0, 0xb00
	s_lshl_b32 s2, s92, 6
	v_mad_u32_u24 v67, v142, s0, v4
	v_add_u32_e32 v68, v3, v2
	v_add_u32_e32 v69, v5, v6
	s_mov_b32 s3, s90

.LBB0_649:
	v_ashrrev_i32_e32 v3, 5, v2
	s_mov_b32 s14, 0x84210843
	v_mul_hi_i32 v4, v3, s14
	v_add_u32_e32 v4, v4, v3
	v_lshrrev_b32_e32 v5, 31, v4
	v_ashrrev_i32_e32 v4, 6, v4
	v_add_u32_e32 v4, v4, v5
	v_mul_lo_u32 v6, v4, s33
	v_sub_u32_e32 v6, v3, v6
	v_ashrrev_i32_e32 v5, 31, v4
	v_ashrrev_i32_e32 v7, 31, v6
	v_lshlrev_b64 v[4:5], 14, v[4:5]
	v_lshlrev_b64 v[6:7], 7, v[6:7]
	v_lshl_add_u64 v[4:5], v[4:5], 0, v[6:7]
	v_and_or_b32 v4, v0, s33, v4
	v_lshlrev_b64 v[8:9], 2, v[4:5]
	v_lshl_add_u64 v[4:5], s[40:41], 0, v[8:9]
	global_load_dwordx4 v[4:7], v[4:5], off offset:2048
	v_lshl_add_u64 v[10:11], s[8:9], 0, v[8:9]
	v_lshl_add_u64 v[12:13], s[42:43], 0, v[8:9]
	global_load_dwordx4 v[14:17], v[12:13], off offset:2048
	v_add_u32_e32 v2, s0, v2
	s_mov_b32 s14, 0x7bfff
	v_cmp_lt_i32_e32 vcc, s14, v2
	s_or_b64 s[12:13], vcc, s[12:13]
	v_add_u32_e32 v0, s1, v0
	v_lshl_add_u64 v[8:9], s[10:11], 0, v[8:9]
	s_waitcnt vmcnt(1)
	global_store_dwordx4 v[10:11], v[4:7], off
	s_waitcnt vmcnt(1)
	global_store_dwordx4 v[8:9], v[14:17], off
	s_andn2_b64 exec, exec, s[12:13]
	s_cbranch_execnz .LBB0_649
